# attention phases: LDS fragment reads of the QK/PV MFMA chains issued a block ahead into spare registers (memory attention both layers with later insertion points; sliding-window PV chains prompt+sampl
# speedup vs baseline: 1.0058x; 1.0035x over previous
; template <bool SAMPLE>
; __device__ __forceinline__ void mem_unit(const Params& p, int l, LAS unsigned char* lds, int unit, int tid, int wave, int lane) {
;     ...
;         for (int hb = 0; hb < 2; ++hb) {
;             float kk[4][8], vv[4][8];
; #pragma unroll
;             for (int it = 0; it < 4; ++it) { const int s = (tid >> 4) + 32 * (4 * hb + it);
;                 const float* kp; const float* vp;
;                 if (!SAMPLE) { kp = (const float*)(p.ws + W_MKV) + ((size_t)l * 1024 + b * 256 + s) * 1024 + h * 128 + sub * 8; vp = kp + 512; }
;                 else { const size_t o = ((((size_t)l * 128 + b) * 256 + s) * 4 + h) * 128 + sub * 8; kp = p.in[I_CMK] + o; vp = p.in[I_CMV] + o; }
;                 if (SAMPLE) { pg8::ld8f_nt(kp, kk[it]); pg8::ld8f_nt(vp, vv[it]); } else { pg8::ld8f(kp, kk[it]); pg8::ld8f(vp, vv[it]); } }
; #pragma unroll
;             for (int it = 0; it < 4; ++it) { const int s = (tid >> 4) + 32 * (4 * hb + it);
;                 float (&k)[8] = kk[it]; float (&v)[8] = vv[it];
;                 if (!SAMPLE) { float ss = 0.f;
; #pragma unroll
;                     for (int e = 0; e < 8; ++e) ss += k[e] * k[e];
;                     ss += __shfl_xor(ss, 1); ss += __shfl_xor(ss, 2); ss += __shfl_xor(ss, 4); ss += __shfl_xor(ss, 8);
;                     const float rs = rsqrtf(ss * (1.f / 128.f) + EPS);
; #pragma unroll
;                     for (int e = 0; e < 8; ++e) k[e] *= rs * kg[e];
;                     if (qt == 0) { const size_t o = ((((size_t)l * 4 + b) * 256 + s) * 4 + h) * 128 + sub * 8;
;                         *(f32x4*)(p.out + O_MKP + o) = (f32x4){k[0], k[1], k[2], k[3]}; *(f32x4*)(p.out + O_MKP + o + 4) = (f32x4){k[4], k[5], k[6], k[7]};
;                         *(f32x4*)(p.out + O_MVP + o) = (f32x4){v[0], v[1], v[2], v[3]}; *(f32x4*)(p.out + O_MVP + o + 4) = (f32x4){v[4], v[5], v[6], v[7]}; }
;                 }
;                 *(LAS bf16x8*)(Kl + s * MEM_KS + sub * 8) = pack8(k);
;                 *(LAS bf16x8*)(Vt + s * MEM_VS + sub * 8) = pack8(v);
;             }
;     ...
;         int q16 = lane & 15, kq = lane >> 4; asm volatile("" : "+v"(q16), "+v"(kq));
;         size_t row; bool st;
;         if (!SAMPLE) { row = (size_t)b * 8192 + (qt * 4 + qq) * 128 + 16 * wave + q16; st = true; } else { row = (size_t)MP + 8 * b + (q16 & 7); st = q16 < 8; }
;         bf16x8 qf[4];
;         {
.LBB0_599:
	s_waitcnt vmcnt(1)
	v_add_u32_e32 v66, s8, v81
	v_ashrrev_i32_e32 v67, 31, v66
	v_add_u32_e32 v6, 0x60, v66
	v_lshl_add_u64 v[8:9], v[66:67], 0, s[10:11]
	v_add_u32_e32 v2, 32, v66
	v_add_u32_e32 v4, 64, v66
	v_ashrrev_i32_e32 v7, 31, v6
	v_lshlrev_b64 v[8:9], 11, v[8:9]
	v_ashrrev_i32_e32 v3, 31, v2
	v_ashrrev_i32_e32 v5, 31, v4
	v_lshl_add_u64 v[6:7], v[6:7], 0, s[10:11]
	v_or_b32_e32 v8, v8, v0
	v_lshl_add_u64 v[2:3], v[2:3], 0, s[10:11]
	v_lshl_add_u64 v[4:5], v[4:5], 0, s[10:11]
	v_lshlrev_b64 v[22:23], 11, v[6:7]
	v_lshl_add_u64 v[6:7], s[78:79], 0, v[8:9]
	v_lshl_add_u64 v[14:15], s[80:81], 0, v[8:9]
	v_lshlrev_b64 v[18:19], 11, v[2:3]
	v_lshlrev_b64 v[20:21], 11, v[4:5]
	global_load_dwordx4 v[2:5], v[6:7], off nt
	s_nop 0
	global_load_dwordx4 v[6:9], v[6:7], off offset:16 nt
	s_nop 0
	global_load_dwordx4 v[10:13], v[14:15], off offset:16 nt
	s_nop 0
	global_load_dwordx4 v[14:17], v[14:15], off nt
	v_or_b32_e32 v18, v18, v0
	v_or_b32_e32 v20, v20, v0
	v_or_b32_e32 v22, v22, v0
	v_lshl_add_u64 v[24:25], s[78:79], 0, v[18:19]
	v_lshl_add_u64 v[30:31], s[80:81], 0, v[18:19]
	s_waitcnt vmcnt(4)
	v_lshl_add_u64 v[38:39], s[78:79], 0, v[20:21]
	v_lshl_add_u64 v[46:47], s[80:81], 0, v[20:21]
	v_lshl_add_u64 v[54:55], s[78:79], 0, v[22:23]
	v_lshl_add_u64 v[62:63], s[80:81], 0, v[22:23]
	global_load_dwordx4 v[18:21], v[24:25], off nt
	s_nop 0
	global_load_dwordx4 v[22:25], v[24:25], off offset:16 nt
	s_nop 0
	global_load_dwordx4 v[26:29], v[30:31], off nt
	s_nop 0
	global_load_dwordx4 v[30:33], v[30:31], off offset:16 nt
	s_nop 0
	global_load_dwordx4 v[34:37], v[38:39], off nt
	s_nop 0
	global_load_dwordx4 v[38:41], v[38:39], off offset:16 nt
	s_nop 0
	global_load_dwordx4 v[42:45], v[46:47], off nt
	s_nop 0
	global_load_dwordx4 v[46:49], v[46:47], off offset:16 nt
	s_nop 0
	global_load_dwordx4 v[50:53], v[54:55], off nt
	s_nop 0
	global_load_dwordx4 v[54:57], v[54:55], off offset:16 nt
	s_nop 0
	global_load_dwordx4 v[58:61], v[62:63], off nt
	s_nop 0
	global_load_dwordx4 v[62:65], v[62:63], off offset:16 nt
	v_cndmask_b32_e64 v1, 0, 1, s[0:1]
	v_cmp_ne_u32_e32 vcc, 1, v1
	v_mul_lo_u32 v1, v66, s30
	v_add_u32_e32 v66, v96, v1
	v_add_u32_e32 v1, v97, v1
	s_movk_i32 s8, 0x80
	s_mov_b64 s[0:1], 0
	s_and_b64 vcc, exec, vcc
	s_waitcnt vmcnt(15)
	v_cvt_pk_bf16_f32 v2, v2, v3
	v_cvt_pk_bf16_f32 v3, v4, v5
	s_waitcnt vmcnt(14)
	v_cvt_pk_bf16_f32 v4, v6, v7
	v_cvt_pk_bf16_f32 v5, v8, v9
	ds_write_b128 v66, v[2:5]
	s_waitcnt vmcnt(12)
	v_cvt_pk_bf16_f32 v2, v14, v15
	v_cvt_pk_bf16_f32 v3, v16, v17
	v_cvt_pk_bf16_f32 v4, v10, v11
	v_cvt_pk_bf16_f32 v5, v12, v13
	ds_write_b128 v1, v[2:5]
	s_waitcnt vmcnt(11)
	v_cvt_pk_bf16_f32 v2, v18, v19
	v_cvt_pk_bf16_f32 v3, v20, v21
	s_waitcnt vmcnt(10)
	v_cvt_pk_bf16_f32 v4, v22, v23
	v_cvt_pk_bf16_f32 v5, v24, v25
	ds_write_b128 v66, v[2:5] offset:8704
	s_waitcnt vmcnt(9)
	v_cvt_pk_bf16_f32 v2, v26, v27
	v_cvt_pk_bf16_f32 v3, v28, v29
	s_waitcnt vmcnt(8)
	v_cvt_pk_bf16_f32 v4, v30, v31
	v_cvt_pk_bf16_f32 v5, v32, v33
	ds_write_b128 v1, v[2:5] offset:8704
	s_waitcnt vmcnt(7)
	v_cvt_pk_bf16_f32 v2, v34, v35
	v_cvt_pk_bf16_f32 v3, v36, v37
	s_waitcnt vmcnt(6)
	v_cvt_pk_bf16_f32 v4, v38, v39
	v_cvt_pk_bf16_f32 v5, v40, v41
	ds_write_b128 v66, v[2:5] offset:17408
	s_waitcnt vmcnt(5)
	v_cvt_pk_bf16_f32 v2, v42, v43
	v_cvt_pk_bf16_f32 v3, v44, v45
	s_waitcnt vmcnt(4)
	v_cvt_pk_bf16_f32 v4, v46, v47
	v_cvt_pk_bf16_f32 v5, v48, v49
	ds_write_b128 v1, v[2:5] offset:17408
	s_waitcnt vmcnt(3)
	v_cvt_pk_bf16_f32 v2, v50, v51
	v_cvt_pk_bf16_f32 v3, v52, v53
	s_waitcnt vmcnt(2)
	v_cvt_pk_bf16_f32 v4, v54, v55
	v_cvt_pk_bf16_f32 v5, v56, v57
	ds_write_b128 v66, v[2:5] offset:26112
	s_waitcnt vmcnt(1)
	v_cvt_pk_bf16_f32 v2, v58, v59
	v_cvt_pk_bf16_f32 v3, v60, v61
	s_waitcnt vmcnt(0)
	v_cvt_pk_bf16_f32 v4, v62, v63
	v_cvt_pk_bf16_f32 v5, v64, v65
	ds_write_b128 v1, v[2:5] offset:26112
	s_cbranch_vccz .LBB0_599
	s_andn2_b64 vcc, exec, s[4:5]
	s_waitcnt lgkmcnt(0)
	s_barrier
	s_cbranch_vccnz .LBB0_618
	s_lshl_b32 s0, s2, 3
	s_add_i32 s1, s0, 0x8000
	s_lshl_b32 s0, s3, 1
	v_mov_b32_e32 v37, v95
	v_mov_b32_e32 v36, v94
	s_add_u32 s2, s64, s0
	s_addc_u32 s3, s65, 0
	v_and_or_b32 v0, v36, 7, s1
	v_lshlrev_b32_e32 v82, 10, v0
	v_lshlrev_b32_e32 v16, 3, v37
	v_lshl_add_u64 v[0:1], s[2:3], 0, v[82:83]
	v_ashrrev_i32_e32 v17, 31, v16
	v_lshl_add_u64 v[12:13], v[16:17], 1, v[0:1]
	global_load_dwordx4 v[0:3], v[12:13], off
	global_load_dwordx4 v[4:7], v[12:13], off offset:64
	global_load_dwordx4 v[8:11], v[12:13], off offset:128
	s_nop 0
	global_load_dwordx4 v[12:15], v[12:13], off offset:192
	v_and_b32_e32 v19, 64, v99
	v_xor_b32_e32 v18, 16, v99
	v_add_u32_e32 v34, 64, v19
	v_cmp_lt_i32_e32 vcc, v18, v34
	v_lshl_add_u64 v[24:25], v[16:17], 2, s[46:47]
	s_waitcnt vmcnt(3)
	v_and_b32_e32 v40, 0xffff0000, v0
	v_cndmask_b32_e32 v18, v99, v18, vcc
	v_lshlrev_b32_e32 v38, 2, v18
	global_load_dwordx4 v[16:19], v[24:25], off offset:16
	global_load_dwordx4 v[20:23], v[24:25], off
	v_lshlrev_b32_e32 v35, 16, v0
	s_waitcnt vmcnt(3)
; __device__ __forceinline__ void unpack8(const v4u w, float (&o)[8]) { o[0] = bflo(w.x); o[1] = bfhi(w.x); o[2] = bflo(w.y); o[3] = bfhi(w.y); o[4] = bflo(w.z); o[5] = bfhi(w.z); o[6] = bflo(w.w); o[7] = bfhi(w.w); }
; __device__ __forceinline__ bf16x8 pack8(const float (&o)[8]) { v4u w; w.x = pk2(o[0], o[1]); w.y = pk2(o[2], o[3]); w.z = pk2(o[4], o[5]); w.w = pk2(o[6], o[7]); return __builtin_bit_cast(bf16x8, w); }
; template <bool SAMPLE>
; __device__ __forceinline__ void mem_unit(const Params& p, int l, LAS unsigned char* lds, int unit, int tid, int wave, int lane) {
;     ...
;         bf16x8 qf[4];
;         {
;             float qv[4][8]; float ss = 0.f;
; #pragma unroll
;             for (int dc = 0; dc < 4; ++dc) { unpack8(*(const v4u*)(MQ + row * 512 + h * 128 + 32 * dc + 8 * kq), qv[dc]);
; #pragma unroll
;                 for (int e = 0; e < 8; ++e) ss += qv[dc][e] * qv[dc][e]; }
;             ss += __shfl_xor(ss, 16); ss += __shfl_xor(ss, 32);
;             const float rs = rsqrtf(ss * (1.f / 128.f) + EPS) * 0.08838834764831845f;
; #pragma unroll
;             for (int dc = 0; dc < 4; ++dc) { float qg[8]; pg8::ld8f(p.in[I_MQG] + l * 128 + 32 * dc + 8 * kq, qg);
; #pragma unroll
;                 for (int e = 0; e < 8; ++e) qv[dc][e] *= rs * qg[e];
;                 qf[dc] = pack8(qv[dc]); }
;         }
	v_lshlrev_b32_e32 v55, 16, v8
	v_and_b32_e32 v56, 0xffff0000, v8
	v_mul_f32_e32 v8, v40, v40
	v_lshlrev_b32_e32 v41, 16, v1
	v_fmac_f32_e32 v8, v35, v35
	v_and_b32_e32 v42, 0xffff0000, v1
	v_fmac_f32_e32 v8, v41, v41
	v_lshlrev_b32_e32 v43, 16, v2
	v_fmac_f32_e32 v8, v42, v42
	v_and_b32_e32 v44, 0xffff0000, v2
	v_fmac_f32_e32 v8, v43, v43
	v_lshlrev_b32_e32 v45, 16, v3
	v_fmac_f32_e32 v8, v44, v44
	v_and_b32_e32 v46, 0xffff0000, v3
	v_fmac_f32_e32 v8, v45, v45
	v_lshlrev_b32_e32 v47, 16, v4
	v_fmac_f32_e32 v8, v46, v46
	v_and_b32_e32 v48, 0xffff0000, v4
	v_fmac_f32_e32 v8, v47, v47
	v_lshlrev_b32_e32 v49, 16, v5
	v_fmac_f32_e32 v8, v48, v48
	v_and_b32_e32 v50, 0xffff0000, v5
	v_fmac_f32_e32 v8, v49, v49
	v_lshlrev_b32_e32 v51, 16, v6
	v_fmac_f32_e32 v8, v50, v50
	v_and_b32_e32 v52, 0xffff0000, v6
	v_fmac_f32_e32 v8, v51, v51
	v_lshlrev_b32_e32 v53, 16, v7
	v_fmac_f32_e32 v8, v52, v52
	v_and_b32_e32 v54, 0xffff0000, v7
	v_fmac_f32_e32 v8, v53, v53
	v_fmac_f32_e32 v8, v54, v54
	v_fmac_f32_e32 v8, v55, v55
	v_lshlrev_b32_e32 v57, 16, v9
	v_fmac_f32_e32 v8, v56, v56
	v_and_b32_e32 v58, 0xffff0000, v9
	v_fmac_f32_e32 v8, v57, v57
	v_lshlrev_b32_e32 v59, 16, v10
	v_fmac_f32_e32 v8, v58, v58
	v_and_b32_e32 v60, 0xffff0000, v10
	v_fmac_f32_e32 v8, v59, v59
	v_lshlrev_b32_e32 v61, 16, v11
	v_fmac_f32_e32 v8, v60, v60
	v_and_b32_e32 v62, 0xffff0000, v11
	s_waitcnt vmcnt(2)
	v_and_b32_e32 v26, 0xffff0000, v12
	v_lshlrev_b32_e32 v27, 16, v12
	v_fmac_f32_e32 v8, v61, v61
	v_pk_mul_f32 v[0:1], v[26:27], v[26:27]
	v_fmac_f32_e32 v8, v62, v62
	v_and_b32_e32 v28, 0xffff0000, v13
	v_lshlrev_b32_e32 v29, 16, v13
	v_add_f32_e32 v1, v1, v8
	v_pk_mul_f32 v[2:3], v[28:29], v[28:29]
	v_add_f32_e32 v0, v0, v1
	v_and_b32_e32 v30, 0xffff0000, v14
	v_lshlrev_b32_e32 v31, 16, v14
	v_add_f32_e32 v0, v3, v0
	v_pk_mul_f32 v[4:5], v[30:31], v[30:31]
	v_add_f32_e32 v0, v2, v0
	v_and_b32_e32 v32, 0xffff0000, v15
	v_lshlrev_b32_e32 v33, 16, v15
	v_add_f32_e32 v0, v5, v0
	v_pk_mul_f32 v[6:7], v[32:33], v[32:33]
	v_add_f32_e32 v0, v4, v0
	v_add_f32_e32 v0, v7, v0
	v_add_f32_e32 v0, v6, v0
	ds_bpermute_b32 v1, v38, v0
	v_xor_b32_e32 v2, 32, v99
	v_cmp_lt_i32_e32 vcc, v2, v34
	s_waitcnt lgkmcnt(0)
	v_add_f32_e32 v0, v0, v1
	v_cndmask_b32_e32 v2, v99, v2, vcc
	v_lshlrev_b32_e32 v39, 2, v2
	ds_bpermute_b32 v1, v39, v0
	s_waitcnt lgkmcnt(0)
	v_add_f32_e32 v0, v0, v1
	v_fmamk_f32 v0, v0, 0x3c000000, v98
	v_mul_f32_e32 v1, 0x4b800000, v0
	v_cmp_gt_f32_e32 vcc, s31, v0
	s_nop 1
	v_cndmask_b32_e32 v0, v0, v1, vcc
	v_rsq_f32_e32 v0, v0
	s_nop 0
	v_mul_f32_e32 v1, 0x45800000, v0
	v_cndmask_b32_e32 v0, v0, v1, vcc
	v_mul_f32_e32 v34, 0x3db504f3, v0
	s_waitcnt vmcnt(0)
	v_mul_f32_e32 v0, v20, v34
	v_mul_f32_e32 v1, v21, v34
	v_mul_f32_e32 v2, v22, v34
	v_mul_f32_e32 v3, v23, v34
	v_mul_f32_e32 v4, v16, v34
	v_mul_f32_e32 v5, v17, v34
	v_mul_f32_e32 v6, v18, v34
	v_mul_f32_e32 v7, v19, v34
	v_mul_f32_e32 v0, v0, v35
	v_mul_f32_e32 v1, v1, v40
	v_mul_f32_e32 v2, v2, v41
	v_mul_f32_e32 v3, v3, v42
	v_mul_f32_e32 v4, v4, v43
	v_mul_f32_e32 v5, v5, v44
	v_mul_f32_e32 v6, v6, v45
	v_mul_f32_e32 v7, v7, v46
	v_cvt_pk_bf16_f32 v0, v0, v1
	v_cvt_pk_bf16_f32 v1, v2, v3
	v_cvt_pk_bf16_f32 v2, v4, v5
	v_cvt_pk_bf16_f32 v3, v6, v7
	global_load_dwordx4 v[4:7], v[24:25], off offset:128
	global_load_dwordx4 v[8:11], v[24:25], off offset:144
	v_lshlrev_b32_e32 v20, 4, v37
	v_mul_lo_u32 v21, v36, s30
	v_add3_u32 v92, 0, v20, v21
	s_waitcnt vmcnt(1)
	v_mul_f32_e32 v4, v4, v34
	v_mul_f32_e32 v5, v5, v34
	v_mul_f32_e32 v6, v6, v34
	v_mul_f32_e32 v7, v7, v34
	s_waitcnt vmcnt(0)
	v_mul_f32_e32 v8, v8, v34
	v_mul_f32_e32 v9, v9, v34
	v_mul_f32_e32 v10, v10, v34
	v_mul_f32_e32 v11, v11, v34
	v_mul_f32_e32 v4, v4, v47
	v_mul_f32_e32 v5, v5, v48
	v_mul_f32_e32 v6, v6, v49
	v_mul_f32_e32 v7, v7, v50
	v_mul_f32_e32 v12, v8, v51
	v_mul_f32_e32 v13, v9, v52
	v_mul_f32_e32 v14, v10, v53
	v_mul_f32_e32 v11, v11, v54
	v_cvt_pk_bf16_f32 v8, v4, v5
	v_cvt_pk_bf16_f32 v9, v6, v7
	v_cvt_pk_bf16_f32 v10, v12, v13
	v_cvt_pk_bf16_f32 v11, v14, v11
	global_load_dwordx4 v[4:7], v[24:25], off offset:256
	global_load_dwordx4 v[12:15], v[24:25], off offset:272
	s_waitcnt vmcnt(1)
	v_mul_f32_e32 v4, v4, v34
	v_mul_f32_e32 v5, v5, v34
	v_mul_f32_e32 v6, v6, v34
	v_mul_f32_e32 v7, v7, v34
	s_waitcnt vmcnt(0)
	v_mul_f32_e32 v12, v12, v34
	v_mul_f32_e32 v13, v13, v34
	v_mul_f32_e32 v14, v14, v34
	v_mul_f32_e32 v15, v15, v34
	v_mul_f32_e32 v4, v4, v55
	v_mul_f32_e32 v5, v5, v56
	v_mul_f32_e32 v6, v6, v57
	v_mul_f32_e32 v7, v7, v58
	v_mul_f32_e32 v12, v12, v59
	v_mul_f32_e32 v13, v13, v60
	v_mul_f32_e32 v14, v14, v61
	v_mul_f32_e32 v15, v15, v62
	v_cvt_pk_bf16_f32 v4, v4, v5
	v_cvt_pk_bf16_f32 v5, v6, v7
	v_cvt_pk_bf16_f32 v6, v12, v13
	v_cvt_pk_bf16_f32 v7, v14, v15
	global_load_dwordx4 v[12:15], v[24:25], off offset:384
	global_load_dwordx4 v[16:19], v[24:25], off offset:400
	s_waitcnt vmcnt(1)
	v_mul_f32_e32 v12, v12, v34
	v_mul_f32_e32 v13, v13, v34
	v_mul_f32_e32 v14, v14, v34
	v_mul_f32_e32 v15, v15, v34
	s_waitcnt vmcnt(0)
; #define LAS __attribute__((address_space(3)))
; __device__ __forceinline__ bf16x8 pack8(const float (&o)[8]) { v4u w; w.x = pk2(o[0], o[1]); w.y = pk2(o[2], o[3]); w.z = pk2(o[4], o[5]); w.w = pk2(o[6], o[7]); return __builtin_bit_cast(bf16x8, w); }
; template <bool SAMPLE>
; __device__ __forceinline__ void mem_unit(const Params& p, int l, LAS unsigned char* lds, int unit, int tid, int wave, int lane) {
;     ...
;                 qf[dc] = pack8(qv[dc]); }
;         }
;         f32x4 S[8][2]; float mx = -INFINITY;
; #pragma unroll
;         for (int cc = 0; cc < 8; ++cc)
; #pragma unroll
;             for (int tt = 0; tt < 2; ++tt) { const int kb = 32 * cc + 16 * tt; f32x4 a = (f32x4){0.f, 0.f, 0.f, 0.f};
; #pragma unroll
;                 for (int dc = 0; dc < 4; ++dc) { const bf16x8 kf = *(const LAS bf16x8*)(Kl + (kb + q16) * MEM_KS + 32 * dc + 8 * kq);
;                     a = __builtin_amdgcn_mfma_f32_16x16x32_bf16(kf, qf[dc], a, 0, 0, 0); }
; #pragma unroll
;                 for (int e = 0; e < 4; ++e) mx = fmaxf(mx, a[e]);
;                 S[cc][tt] = a; }
	v_mul_f32_e32 v16, v16, v34
	v_mul_f32_e32 v17, v17, v34
	v_mul_f32_e32 v18, v18, v34
	v_mul_f32_e32 v19, v19, v34
	v_mul_f32_e32 v12, v12, v27
	v_mul_f32_e32 v13, v13, v26
	v_mul_f32_e32 v14, v14, v29
	v_mul_f32_e32 v15, v15, v28
	v_mul_f32_e32 v16, v16, v31
	v_mul_f32_e32 v17, v17, v30
	v_mul_f32_e32 v18, v18, v33
	v_mul_f32_e32 v19, v19, v32
	v_cvt_pk_bf16_f32 v32, v12, v13
	v_cvt_pk_bf16_f32 v33, v14, v15
	v_cvt_pk_bf16_f32 v34, v16, v17
	v_cvt_pk_bf16_f32 v35, v18, v19
	ds_read_b128 v[186:189], v92
	ds_read_b128 v[190:193], v92 offset:4352
	ds_read_b128 v[194:197], v92 offset:8704
	ds_read_b128 v[198:201], v92 offset:13056
	ds_read_b128 v[202:205], v92 offset:17408
	ds_read_b128 v[206:209], v92 offset:21760
	ds_read_b128 v[210:213], v92 offset:26112
	s_nop 0
	ds_read_b128 v[16:19], v92 offset:64
	s_nop 0
	ds_read_b128 v[24:27], v92 offset:4416
	s_nop 0
	ds_read_b128 v[40:43], v92 offset:8768
	s_nop 0
	ds_read_b128 v[48:51], v92 offset:13120
	s_nop 0
	ds_read_b128 v[56:59], v92 offset:17472
	s_nop 0
	ds_read_b128 v[64:67], v92 offset:21824
	s_nop 0
	ds_read_b128 v[72:75], v92 offset:26176
	ds_read_b128 v[76:79], v92 offset:30464
	ds_read_b128 v[88:91], v92 offset:30528
	ds_read_b128 v[100:103], v92 offset:34816
	ds_read_b128 v[104:107], v92 offset:34880
	ds_read_b128 v[108:111], v92 offset:39168
	ds_read_b128 v[112:115], v92 offset:39232
	ds_read_b128 v[116:119], v92 offset:43520
	ds_read_b128 v[120:123], v92 offset:43584
	ds_read_b128 v[124:127], v92 offset:47872
	ds_read_b128 v[128:131], v92 offset:47936
	ds_read_b128 v[132:135], v92 offset:52224
	ds_read_b128 v[136:139], v92 offset:52288
	ds_read_b128 v[140:143], v92 offset:56576
	ds_read_b128 v[144:147], v92 offset:56640
	ds_read_b128 v[148:151], v92 offset:60928
	ds_read_b128 v[152:155], v92 offset:60992
	ds_read_b128 v[156:159], v92 offset:65280
	ds_read_b128 v[160:163], v92 offset:65344
	s_waitcnt lgkmcnt(14)
	v_mfma_f32_16x16x32_bf16 v[12:15], v[186:189], v[0:3], 0
	v_mfma_f32_16x16x32_bf16 v[20:23], v[190:193], v[0:3], 0
	v_mfma_f32_16x16x32_bf16 v[28:31], v[194:197], v[0:3], 0
	v_mfma_f32_16x16x32_bf16 v[44:47], v[198:201], v[0:3], 0
	v_mfma_f32_16x16x32_bf16 v[52:55], v[202:205], v[0:3], 0
	v_mfma_f32_16x16x32_bf16 v[60:63], v[206:209], v[0:3], 0
	v_mfma_f32_16x16x32_bf16 v[68:71], v[210:213], v[0:3], 0
	v_mfma_f32_16x16x32_bf16 v[76:79], v[76:79], v[0:3], 0
	v_mfma_f32_16x16x32_bf16 v[100:103], v[100:103], v[0:3], 0
	s_waitcnt lgkmcnt(13)
	v_mfma_f32_16x16x32_bf16 v[108:111], v[108:111], v[0:3], 0
	s_waitcnt lgkmcnt(11)
	v_mfma_f32_16x16x32_bf16 v[116:119], v[116:119], v[0:3], 0
	s_waitcnt lgkmcnt(9)
	v_mfma_f32_16x16x32_bf16 v[124:127], v[124:127], v[0:3], 0
	s_waitcnt lgkmcnt(7)
	v_mfma_f32_16x16x32_bf16 v[132:135], v[132:135], v[0:3], 0
	s_waitcnt lgkmcnt(5)
	v_mfma_f32_16x16x32_bf16 v[140:143], v[140:143], v[0:3], 0
	s_waitcnt lgkmcnt(3)
	v_mfma_f32_16x16x32_bf16 v[148:151], v[148:151], v[0:3], 0
	s_waitcnt lgkmcnt(1)
	v_mfma_f32_16x16x32_bf16 v[0:3], v[156:159], v[0:3], 0
	v_mfma_f32_16x16x32_bf16 v[12:15], v[16:19], v[8:11], v[12:15]
	v_mfma_f32_16x16x32_bf16 v[16:19], v[24:27], v[8:11], v[20:23]
	v_mfma_f32_16x16x32_bf16 v[20:23], v[40:43], v[8:11], v[28:31]
	v_mfma_f32_16x16x32_bf16 v[24:27], v[48:51], v[8:11], v[44:47]
	v_mfma_f32_16x16x32_bf16 v[28:31], v[56:59], v[8:11], v[52:55]
	ds_read_b128 v[198:201], v92 offset:128
	ds_read_b128 v[202:205], v92 offset:4480
	ds_read_b128 v[206:209], v92 offset:8832
	ds_read_b128 v[210:213], v92 offset:13184
	v_mfma_f32_16x16x32_bf16 v[40:43], v[64:67], v[8:11], v[60:63]
	v_mfma_f32_16x16x32_bf16 v[44:47], v[72:75], v[8:11], v[68:71]
	v_mfma_f32_16x16x32_bf16 v[48:51], v[88:91], v[8:11], v[76:79]
	v_mfma_f32_16x16x32_bf16 v[52:55], v[104:107], v[8:11], v[100:103]
	v_mfma_f32_16x16x32_bf16 v[56:59], v[112:115], v[8:11], v[108:111]
	v_mfma_f32_16x16x32_bf16 v[60:63], v[120:123], v[8:11], v[116:119]
	v_mfma_f32_16x16x32_bf16 v[64:67], v[128:131], v[8:11], v[124:127]
	ds_read_b128 v[218:221], v92 offset:17536
	ds_read_b128 v[222:225], v92 offset:21888
	ds_read_b128 v[226:229], v92 offset:26240
	ds_read_b128 v[230:233], v92 offset:30592
	ds_read_b128 v[234:237], v92 offset:34944
	ds_read_b128 v[242:245], v92 offset:39296
	ds_read_b128 v[246:249], v92 offset:43648
	v_mfma_f32_16x16x32_bf16 v[68:71], v[136:139], v[8:11], v[132:135]
	v_mfma_f32_16x16x32_bf16 v[72:75], v[144:147], v[8:11], v[140:143]
	v_mfma_f32_16x16x32_bf16 v[76:79], v[152:155], v[8:11], v[148:151]
	s_waitcnt lgkmcnt(11)
	v_mfma_f32_16x16x32_bf16 v[0:3], v[160:163], v[8:11], v[0:3]
	s_nop 0
	ds_read_b128 v[88:91], v92 offset:192
	s_waitcnt lgkmcnt(11)
	v_mfma_f32_16x16x32_bf16 v[8:11], v[198:201], v[4:7], v[12:15]
	s_nop 2
	s_nop 0
	ds_read_b128 v[100:103], v92 offset:4544
	s_waitcnt lgkmcnt(11)
	v_mfma_f32_16x16x32_bf16 v[12:15], v[202:205], v[4:7], v[16:19]
	s_nop 2
	s_nop 0
	ds_read_b128 v[104:107], v92 offset:8896
	s_waitcnt lgkmcnt(11)
	v_mfma_f32_16x16x32_bf16 v[16:19], v[206:209], v[4:7], v[20:23]
	s_nop 2
	s_nop 0
	ds_read_b128 v[108:111], v92 offset:13248
	s_waitcnt lgkmcnt(11)
	v_mfma_f32_16x16x32_bf16 v[20:23], v[210:213], v[4:7], v[24:27]
	s_nop 2
	s_nop 0
	ds_read_b128 v[112:115], v92 offset:17600
	s_waitcnt lgkmcnt(11)
	ds_read_b128 v[186:189], v92 offset:48000
	ds_read_b128 v[190:193], v92 offset:52352
	ds_read_b128 v[194:197], v92 offset:56704
	ds_read_b128 v[198:201], v92 offset:61056
	ds_read_b128 v[202:205], v92 offset:65408
	v_mfma_f32_16x16x32_bf16 v[24:27], v[218:221], v[4:7], v[28:31]
	s_nop 2
	s_nop 0
	ds_read_b128 v[116:119], v92 offset:21952
	s_waitcnt lgkmcnt(15)
; #define LAS __attribute__((address_space(3)))
; template <bool SAMPLE>
; __device__ __forceinline__ void mem_unit(const Params& p, int l, LAS unsigned char* lds, int unit, int tid, int wave, int lane) {
;     ...
;             for (int tt = 0; tt < 2; ++tt) { const int kb = 32 * cc + 16 * tt; f32x4 a = (f32x4){0.f, 0.f, 0.f, 0.f};
; #pragma unroll
;                 for (int dc = 0; dc < 4; ++dc) { const bf16x8 kf = *(const LAS bf16x8*)(Kl + (kb + q16) * MEM_KS + 32 * dc + 8 * kq);
;                     a = __builtin_amdgcn_mfma_f32_16x16x32_bf16(kf, qf[dc], a, 0, 0, 0); }
; #pragma unroll
;                 for (int e = 0; e < 4; ++e) mx = fmaxf(mx, a[e]);
;                 S[cc][tt] = a; }
;         mx = fmaxf(mx, __shfl_xor(mx, 16)); mx = fmaxf(mx, __shfl_xor(mx, 32));
;         float den = 0.f;
; #pragma unroll
;         for (int cc = 0; cc < 8; ++cc)
; #pragma unroll
;             for (int tt = 0; tt < 2; ++tt)
; #pragma unroll
;                 for (int e = 0; e < 4; ++e) { const float pe = __expf(S[cc][tt][e] - mx); S[cc][tt][e] = pe; den += pe; }
	v_mfma_f32_16x16x32_bf16 v[28:31], v[222:225], v[4:7], v[40:43]
	s_nop 2
	s_nop 0
	ds_read_b128 v[120:123], v92 offset:26304
	s_waitcnt lgkmcnt(15)
	v_mfma_f32_16x16x32_bf16 v[40:43], v[226:229], v[4:7], v[44:47]
	s_nop 2
	s_nop 0
	ds_read_b128 v[124:127], v92 offset:30656
	s_waitcnt lgkmcnt(15)
	v_mfma_f32_16x16x32_bf16 v[44:47], v[230:233], v[4:7], v[48:51]
	s_nop 2
	s_nop 0
	ds_read_b128 v[128:131], v92 offset:35008
	s_waitcnt lgkmcnt(15)
	v_mfma_f32_16x16x32_bf16 v[48:51], v[234:237], v[4:7], v[52:55]
	s_nop 2
	s_nop 0
	ds_read_b128 v[132:135], v92 offset:39360
	s_waitcnt lgkmcnt(15)
	v_mfma_f32_16x16x32_bf16 v[52:55], v[242:245], v[4:7], v[56:59]
	s_nop 2
	s_nop 0
	ds_read_b128 v[136:139], v92 offset:43712
	s_waitcnt lgkmcnt(15)
	v_mfma_f32_16x16x32_bf16 v[56:59], v[246:249], v[4:7], v[60:63]
	s_nop 2
	s_nop 0
	ds_read_b128 v[140:143], v92 offset:48064
	s_waitcnt lgkmcnt(11)
	v_mfma_f32_16x16x32_bf16 v[60:63], v[186:189], v[4:7], v[64:67]
	s_nop 2
	s_nop 0
	ds_read_b128 v[144:147], v92 offset:52416
	s_waitcnt lgkmcnt(11)
	v_mfma_f32_16x16x32_bf16 v[64:67], v[190:193], v[4:7], v[68:71]
	s_nop 2
	s_nop 0
	ds_read_b128 v[148:151], v92 offset:56768
	s_waitcnt lgkmcnt(11)
	v_mfma_f32_16x16x32_bf16 v[68:71], v[194:197], v[4:7], v[72:75]
	s_nop 2
	s_nop 0
	ds_read_b128 v[152:155], v92 offset:61120
	s_waitcnt lgkmcnt(11)
	v_mfma_f32_16x16x32_bf16 v[72:75], v[198:201], v[4:7], v[76:79]
	s_nop 2
	s_nop 0
	ds_read_b128 v[156:159], v92 offset:65472
	s_waitcnt lgkmcnt(11)
	v_mfma_f32_16x16x32_bf16 v[0:3], v[202:205], v[4:7], v[0:3]
	v_mfma_f32_16x16x32_bf16 v[76:79], v[88:91], v[32:35], v[8:11]
	v_mfma_f32_16x16x32_bf16 v[88:91], v[100:103], v[32:35], v[12:15]
	v_mfma_f32_16x16x32_bf16 v[100:103], v[104:107], v[32:35], v[16:19]
	v_mfma_f32_16x16x32_bf16 v[104:107], v[108:111], v[32:35], v[20:23]
	v_mfma_f32_16x16x32_bf16 v[108:111], v[112:115], v[32:35], v[24:27]
	v_mfma_f32_16x16x32_bf16 v[112:115], v[116:119], v[32:35], v[28:31]
	v_mfma_f32_16x16x32_bf16 v[40:43], v[120:123], v[32:35], v[40:43]
	v_mfma_f32_16x16x32_bf16 v[44:47], v[124:127], v[32:35], v[44:47]
	v_mfma_f32_16x16x32_bf16 v[28:31], v[128:131], v[32:35], v[48:51]
	v_mfma_f32_16x16x32_bf16 v[24:27], v[132:135], v[32:35], v[52:55]
	v_mfma_f32_16x16x32_bf16 v[20:23], v[136:139], v[32:35], v[56:59]
	v_mfma_f32_16x16x32_bf16 v[16:19], v[140:143], v[32:35], v[60:63]
	v_mfma_f32_16x16x32_bf16 v[12:15], v[144:147], v[32:35], v[64:67]
	v_mfma_f32_16x16x32_bf16 v[8:11], v[148:151], v[32:35], v[68:71]
	v_mfma_f32_16x16x32_bf16 v[4:7], v[152:155], v[32:35], v[72:75]
	s_waitcnt lgkmcnt(0)
	v_mfma_f32_16x16x32_bf16 v[0:3], v[156:159], v[32:35], v[0:3]
	v_max3_f32 v32, v76, s33, v77
	v_max3_f32 v32, v32, v78, v79
	v_max3_f32 v32, v32, v88, v89
	v_max3_f32 v32, v32, v90, v91
	v_max3_f32 v32, v32, v100, v101
	v_max3_f32 v32, v32, v102, v103
	v_max3_f32 v32, v32, v104, v105
	v_max3_f32 v32, v32, v106, v107
	v_max3_f32 v32, v32, v108, v109
	v_max3_f32 v32, v32, v110, v111
	v_max3_f32 v32, v32, v112, v113
	v_max3_f32 v32, v32, v114, v115
	v_max3_f32 v32, v32, v40, v41
	v_max3_f32 v32, v32, v42, v43
	v_max3_f32 v32, v32, v44, v45
	v_max3_f32 v32, v32, v46, v47
	v_max3_f32 v32, v32, v28, v29
	v_max3_f32 v32, v32, v30, v31
	v_max3_f32 v32, v32, v24, v25
	v_max3_f32 v32, v32, v26, v27
	v_max3_f32 v32, v32, v20, v21
	v_max3_f32 v32, v32, v22, v23
	v_max3_f32 v32, v32, v16, v17
	v_max3_f32 v32, v32, v18, v19
	v_max3_f32 v32, v32, v12, v13
	v_max3_f32 v32, v32, v14, v15
	v_max3_f32 v32, v32, v8, v9
	v_max3_f32 v32, v32, v10, v11
	v_max3_f32 v32, v32, v4, v5
	v_max3_f32 v32, v32, v6, v7
	v_max3_f32 v32, v32, v0, v1
	v_max3_f32 v32, v32, v2, v3
	ds_bpermute_b32 v33, v38, v32
	s_waitcnt lgkmcnt(0)
	v_max_f32_e32 v33, v33, v33
	v_max_f32_e32 v32, v32, v33
	ds_bpermute_b32 v33, v39, v32
	s_waitcnt lgkmcnt(0)
	v_max_f32_e32 v33, v33, v33
	v_max_f32_e32 v32, v32, v33
	v_sub_f32_e32 v33, v76, v32
	v_sub_f32_e32 v34, v77, v32
	v_mul_f32_e32 v33, 0x3fb8aa3b, v33
	v_sub_f32_e32 v35, v78, v32
	v_mul_f32_e32 v34, 0x3fb8aa3b, v34
	v_exp_f32_e32 v33, v33
	v_sub_f32_e32 v48, v79, v32
	v_mul_f32_e32 v35, 0x3fb8aa3b, v35
	v_exp_f32_e32 v34, v34
	v_sub_f32_e32 v49, v88, v32
	v_mul_f32_e32 v48, 0x3fb8aa3b, v48
	v_exp_f32_e32 v35, v35
	v_sub_f32_e32 v50, v89, v32
	v_mul_f32_e32 v49, 0x3fb8aa3b, v49
	v_exp_f32_e32 v48, v48
	v_sub_f32_e32 v51, v90, v32
	v_mul_f32_e32 v50, 0x3fb8aa3b, v50
	v_exp_f32_e32 v49, v49
	v_add_f32_e32 v69, 0, v33
	v_sub_f32_e32 v52, v91, v32
	v_mul_f32_e32 v51, 0x3fb8aa3b, v51
	v_exp_f32_e32 v50, v50
	v_add_f32_e32 v69, v34, v69
	v_sub_f32_e32 v53, v100, v32
	v_mul_f32_e32 v52, 0x3fb8aa3b, v52
	v_exp_f32_e32 v51, v51
	v_add_f32_e32 v69, v35, v69
	v_sub_f32_e32 v54, v101, v32
	v_mul_f32_e32 v53, 0x3fb8aa3b, v53
	v_exp_f32_e32 v52, v52
	v_add_f32_e32 v69, v48, v69
	v_sub_f32_e32 v55, v102, v32
	v_mul_f32_e32 v54, 0x3fb8aa3b, v54
	v_exp_f32_e32 v53, v53
	v_add_f32_e32 v69, v49, v69
	v_sub_f32_e32 v56, v103, v32
	v_mul_f32_e32 v55, 0x3fb8aa3b, v55
	v_exp_f32_e32 v54, v54
	v_add_f32_e32 v69, v50, v69
	v_sub_f32_e32 v57, v104, v32
	v_mul_f32_e32 v56, 0x3fb8aa3b, v56
	v_exp_f32_e32 v55, v55
	v_add_f32_e32 v69, v51, v69
	v_sub_f32_e32 v58, v105, v32
	v_mul_f32_e32 v57, 0x3fb8aa3b, v57
	v_exp_f32_e32 v56, v56
	v_add_f32_e32 v69, v52, v69
	v_sub_f32_e32 v59, v106, v32
	v_mul_f32_e32 v58, 0x3fb8aa3b, v58
	v_exp_f32_e32 v57, v57
	v_add_f32_e32 v69, v53, v69
	v_sub_f32_e32 v60, v107, v32
	v_mul_f32_e32 v59, 0x3fb8aa3b, v59
	v_exp_f32_e32 v58, v58
	v_add_f32_e32 v69, v54, v69
	v_sub_f32_e32 v61, v108, v32
	v_mul_f32_e32 v60, 0x3fb8aa3b, v60
	v_exp_f32_e32 v59, v59
	v_add_f32_e32 v69, v55, v69
	v_sub_f32_e32 v62, v109, v32
; __device__ __forceinline__ bf16x8 pack8(const float (&o)[8]) { v4u w; w.x = pk2(o[0], o[1]); w.y = pk2(o[2], o[3]); w.z = pk2(o[4], o[5]); w.w = pk2(o[6], o[7]); return __builtin_bit_cast(bf16x8, w); }
; template <bool SAMPLE>
; __device__ __forceinline__ void mem_unit(const Params& p, int l, LAS unsigned char* lds, int unit, int tid, int wave, int lane) {
;     ...
;         float den = 0.f;
; #pragma unroll
;         for (int cc = 0; cc < 8; ++cc)
; #pragma unroll
;             for (int tt = 0; tt < 2; ++tt)
; #pragma unroll
;                 for (int e = 0; e < 4; ++e) { const float pe = __expf(S[cc][tt][e] - mx); S[cc][tt][e] = pe; den += pe; }
;         den += __shfl_xor(den, 16); den += __shfl_xor(den, 32);
;         const float rden = 1.f / den;
;         bf16x8 pf[8];
; #pragma unroll
;         for (int cc = 0; cc < 8; ++cc) { float t8[8];
; #pragma unroll
;             for (int e = 0; e < 4; ++e) { t8[e] = S[cc][0][e]; t8[4 + e] = S[cc][1][e]; }
;             pf[cc] = pack8(t8); }
	v_mul_f32_e32 v61, 0x3fb8aa3b, v61
	v_exp_f32_e32 v60, v60
	v_add_f32_e32 v69, v56, v69
	v_sub_f32_e32 v63, v110, v32
	v_mul_f32_e32 v62, 0x3fb8aa3b, v62
	v_exp_f32_e32 v61, v61
	v_add_f32_e32 v69, v57, v69
	v_sub_f32_e32 v64, v111, v32
	v_mul_f32_e32 v63, 0x3fb8aa3b, v63
	v_exp_f32_e32 v62, v62
	v_add_f32_e32 v69, v58, v69
	v_sub_f32_e32 v65, v112, v32
	v_mul_f32_e32 v64, 0x3fb8aa3b, v64
	v_exp_f32_e32 v63, v63
	v_add_f32_e32 v69, v59, v69
	v_sub_f32_e32 v66, v113, v32
	v_mul_f32_e32 v65, 0x3fb8aa3b, v65
	v_exp_f32_e32 v64, v64
	v_add_f32_e32 v69, v60, v69
	v_sub_f32_e32 v67, v114, v32
	v_mul_f32_e32 v66, 0x3fb8aa3b, v66
	v_exp_f32_e32 v65, v65
	v_add_f32_e32 v69, v61, v69
	v_sub_f32_e32 v68, v115, v32
	v_mul_f32_e32 v67, 0x3fb8aa3b, v67
	v_exp_f32_e32 v66, v66
	v_add_f32_e32 v69, v62, v69
	v_sub_f32_e32 v40, v40, v32
	v_mul_f32_e32 v68, 0x3fb8aa3b, v68
	v_exp_f32_e32 v67, v67
	v_add_f32_e32 v69, v63, v69
	v_sub_f32_e32 v41, v41, v32
	v_mul_f32_e32 v40, 0x3fb8aa3b, v40
	v_exp_f32_e32 v68, v68
	v_add_f32_e32 v69, v64, v69
	v_sub_f32_e32 v42, v42, v32
	v_mul_f32_e32 v41, 0x3fb8aa3b, v41
	v_exp_f32_e32 v40, v40
	v_add_f32_e32 v69, v65, v69
	v_sub_f32_e32 v43, v43, v32
	v_mul_f32_e32 v42, 0x3fb8aa3b, v42
	v_exp_f32_e32 v41, v41
	v_add_f32_e32 v69, v66, v69
	v_sub_f32_e32 v44, v44, v32
	v_mul_f32_e32 v43, 0x3fb8aa3b, v43
	v_exp_f32_e32 v42, v42
	v_add_f32_e32 v69, v67, v69
	v_sub_f32_e32 v45, v45, v32
	v_mul_f32_e32 v44, 0x3fb8aa3b, v44
	v_exp_f32_e32 v43, v43
	v_add_f32_e32 v69, v68, v69
	v_sub_f32_e32 v46, v46, v32
	v_mul_f32_e32 v45, 0x3fb8aa3b, v45
	v_exp_f32_e32 v44, v44
	v_add_f32_e32 v69, v40, v69
	v_sub_f32_e32 v47, v47, v32
	v_mul_f32_e32 v46, 0x3fb8aa3b, v46
	v_exp_f32_e32 v45, v45
	v_add_f32_e32 v69, v41, v69
	v_sub_f32_e32 v28, v28, v32
	v_mul_f32_e32 v47, 0x3fb8aa3b, v47
	v_exp_f32_e32 v46, v46
	v_add_f32_e32 v69, v42, v69
	v_sub_f32_e32 v29, v29, v32
	v_mul_f32_e32 v28, 0x3fb8aa3b, v28
	v_exp_f32_e32 v47, v47
	v_add_f32_e32 v69, v43, v69
	v_exp_f32_e32 v28, v28
	v_add_f32_e32 v69, v44, v69
	v_mul_f32_e32 v29, 0x3fb8aa3b, v29
	v_sub_f32_e32 v30, v30, v32
	v_sub_f32_e32 v24, v24, v32
	v_add_f32_e32 v69, v45, v69
	v_exp_f32_e32 v29, v29
	v_mul_f32_e32 v30, 0x3fb8aa3b, v30
	v_sub_f32_e32 v31, v31, v32
	v_mul_f32_e32 v24, 0x3fb8aa3b, v24
	v_add_f32_e32 v69, v46, v69
	v_exp_f32_e32 v30, v30
	v_mul_f32_e32 v31, 0x3fb8aa3b, v31
	v_exp_f32_e32 v70, v24
	v_sub_f32_e32 v24, v25, v32
	v_add_f32_e32 v69, v47, v69
	v_exp_f32_e32 v31, v31
	v_mul_f32_e32 v24, 0x3fb8aa3b, v24
	v_add_f32_e32 v69, v28, v69
	v_exp_f32_e32 v71, v24
	v_sub_f32_e32 v24, v26, v32
	v_add_f32_e32 v69, v29, v69
	v_mul_f32_e32 v24, 0x3fb8aa3b, v24
	v_add_f32_e32 v69, v30, v69
	v_exp_f32_e32 v72, v24
	v_sub_f32_e32 v24, v27, v32
	v_sub_f32_e32 v20, v20, v32
	v_add_f32_e32 v69, v31, v69
	v_mul_f32_e32 v24, 0x3fb8aa3b, v24
	v_mul_f32_e32 v20, 0x3fb8aa3b, v20
	v_exp_f32_e32 v73, v24
	v_add_f32_e32 v24, v70, v69
	v_exp_f32_e32 v69, v20
	v_sub_f32_e32 v20, v21, v32
	v_mul_f32_e32 v20, 0x3fb8aa3b, v20
	v_exp_f32_e32 v74, v20
	v_sub_f32_e32 v20, v22, v32
	v_sub_f32_e32 v16, v16, v32
	v_mul_f32_e32 v20, 0x3fb8aa3b, v20
	v_mul_f32_e32 v16, 0x3fb8aa3b, v16
	v_add_f32_e32 v24, v71, v24
	v_exp_f32_e32 v75, v20
	v_sub_f32_e32 v20, v23, v32
	v_exp_f32_e32 v77, v16
	v_sub_f32_e32 v16, v17, v32
	v_add_f32_e32 v24, v72, v24
	v_mul_f32_e32 v20, 0x3fb8aa3b, v20
	v_mul_f32_e32 v16, 0x3fb8aa3b, v16
	v_add_f32_e32 v24, v73, v24
	v_exp_f32_e32 v76, v20
	v_exp_f32_e32 v78, v16
	v_sub_f32_e32 v16, v18, v32
	v_sub_f32_e32 v12, v12, v32
	v_add_f32_e32 v20, v69, v24
	v_mul_f32_e32 v16, 0x3fb8aa3b, v16
	v_mul_f32_e32 v12, 0x3fb8aa3b, v12
	v_add_f32_e32 v20, v74, v20
	v_exp_f32_e32 v79, v16
	v_sub_f32_e32 v16, v19, v32
	v_exp_f32_e32 v89, v12
	v_sub_f32_e32 v12, v13, v32
	v_add_f32_e32 v20, v75, v20
	v_mul_f32_e32 v16, 0x3fb8aa3b, v16
	v_mul_f32_e32 v12, 0x3fb8aa3b, v12
	v_add_f32_e32 v20, v76, v20
	v_exp_f32_e32 v88, v16
	v_exp_f32_e32 v90, v12
	v_sub_f32_e32 v12, v14, v32
	v_sub_f32_e32 v8, v8, v32
	v_add_f32_e32 v16, v77, v20
	v_mul_f32_e32 v12, 0x3fb8aa3b, v12
	v_mul_f32_e32 v8, 0x3fb8aa3b, v8
	v_add_f32_e32 v16, v78, v16
	v_exp_f32_e32 v91, v12
	v_sub_f32_e32 v12, v15, v32
	v_exp_f32_e32 v93, v8
	v_sub_f32_e32 v8, v9, v32
	v_add_f32_e32 v16, v79, v16
	v_mul_f32_e32 v12, 0x3fb8aa3b, v12
	v_mul_f32_e32 v8, 0x3fb8aa3b, v8
	v_add_f32_e32 v16, v88, v16
	v_exp_f32_e32 v92, v12
	v_exp_f32_e32 v100, v8
	v_sub_f32_e32 v8, v10, v32
	v_sub_f32_e32 v4, v4, v32
	v_add_f32_e32 v12, v89, v16
	v_mul_f32_e32 v8, 0x3fb8aa3b, v8
	v_mul_f32_e32 v4, 0x3fb8aa3b, v4
	v_add_f32_e32 v12, v90, v12
	v_exp_f32_e32 v101, v8
	v_sub_f32_e32 v8, v11, v32
	v_exp_f32_e32 v103, v4
	v_sub_f32_e32 v4, v5, v32
	v_add_f32_e32 v12, v91, v12
	v_mul_f32_e32 v8, 0x3fb8aa3b, v8
	v_mul_f32_e32 v4, 0x3fb8aa3b, v4
	v_add_f32_e32 v12, v92, v12
	v_exp_f32_e32 v102, v8
	v_exp_f32_e32 v104, v4
	v_sub_f32_e32 v4, v6, v32
	v_sub_f32_e32 v0, v0, v32
	v_add_f32_e32 v8, v93, v12
	v_mul_f32_e32 v4, 0x3fb8aa3b, v4
	v_mul_f32_e32 v0, 0x3fb8aa3b, v0
	v_add_f32_e32 v8, v100, v8
	v_exp_f32_e32 v105, v4
	v_sub_f32_e32 v4, v7, v32
	v_exp_f32_e32 v107, v0
	v_sub_f32_e32 v0, v1, v32
	v_add_f32_e32 v8, v101, v8
	v_mul_f32_e32 v4, 0x3fb8aa3b, v4
	v_mul_f32_e32 v0, 0x3fb8aa3b, v0
	v_add_f32_e32 v8, v102, v8
	v_exp_f32_e32 v106, v4
	v_exp_f32_e32 v108, v0
	v_sub_f32_e32 v0, v2, v32
	v_add_f32_e32 v4, v103, v8
	v_mul_f32_e32 v0, 0x3fb8aa3b, v0
	v_add_f32_e32 v4, v104, v4
	v_exp_f32_e32 v109, v0
	v_sub_f32_e32 v0, v3, v32
	v_add_f32_e32 v4, v105, v4
	v_mul_f32_e32 v0, 0x3fb8aa3b, v0
	v_add_f32_e32 v4, v106, v4
	v_exp_f32_e32 v32, v0
	v_add_f32_e32 v0, v107, v4
	v_add_f32_e32 v0, v108, v0
	v_add_f32_e32 v0, v109, v0
	v_add_f32_e32 v0, v32, v0
	ds_bpermute_b32 v1, v38, v0
	v_cvt_pk_bf16_f32 v24, v33, v34
	v_cvt_pk_bf16_f32 v25, v35, v48
	v_cvt_pk_bf16_f32 v26, v49, v50
	v_cvt_pk_bf16_f32 v27, v51, v52
	s_waitcnt lgkmcnt(0)
; #define LAS __attribute__((address_space(3)))
; __device__ __forceinline__ unsigned pk2(float lo, float hi) { return pg8::cvt_pk_bf16(lo, hi); }
; __device__ __forceinline__ bf16x8 pack8(const float (&o)[8]) { v4u w; w.x = pk2(o[0], o[1]); w.y = pk2(o[2], o[3]); w.z = pk2(o[4], o[5]); w.w = pk2(o[6], o[7]); return __builtin_bit_cast(bf16x8, w); }
; __device__ __forceinline__ v2u vtr(const LAS bf16* p) { return __builtin_bit_cast(v2u, __builtin_amdgcn_ds_read_tr16_b64_v4i16((LAS v4i16_t*)p)); }
; template <bool SAMPLE>
; __device__ __forceinline__ void mem_unit(const Params& p, int l, LAS unsigned char* lds, int unit, int tid, int wave, int lane) {
;     ...
;         den += __shfl_xor(den, 16); den += __shfl_xor(den, 32);
;         const float rden = 1.f / den;
;         bf16x8 pf[8];
; #pragma unroll
;         for (int cc = 0; cc < 8; ++cc) { float t8[8];
; #pragma unroll
;             for (int e = 0; e < 4; ++e) { t8[e] = S[cc][0][e]; t8[4 + e] = S[cc][1][e]; }
;             pf[cc] = pack8(t8); }
; #pragma unroll
;         for (int dt = 0; dt < 8; ++dt) { f32x4 o = (f32x4){0.f, 0.f, 0.f, 0.f};
; #pragma unroll
;             for (int cc = 0; cc < 8; ++cc) { const LAS bf16* vp = Vt + (32 * cc + 4 * kq + (q16 >> 2)) * MEM_VS + 16 * dt + 4 * (q16 & 3);
;                 const v2u lo = vtr(vp), hi = vtr(vp + 16 * MEM_VS);
;                 v4u av; av.x = lo.x; av.y = lo.y; av.z = hi.x; av.w = hi.y;
;                 o = __builtin_amdgcn_mfma_f32_16x16x32_bf16(__builtin_bit_cast(bf16x8, av), pf[cc], o, 0, 0, 0); }
;             if (st) { v2u w; w.x = pk2(o[0] * rden, o[1] * rden); w.y = pk2(o[2] * rden, o[3] * rden);
;                 *(v2u*)(MO + row * 512 + h * 128 + 16 * dt + 4 * kq) = w; } }
	v_add_f32_e32 v0, v0, v1
	ds_bpermute_b32 v1, v39, v0
	v_cvt_pk_bf16_f32 v20, v53, v54
	v_cvt_pk_bf16_f32 v21, v55, v56
	v_cvt_pk_bf16_f32 v22, v57, v58
	v_cvt_pk_bf16_f32 v23, v59, v60
	s_waitcnt lgkmcnt(0)
	v_add_f32_e32 v39, v0, v1
	v_cvt_pk_bf16_f32 v16, v61, v62
	v_cvt_pk_bf16_f32 v17, v63, v64
	v_cvt_pk_bf16_f32 v18, v65, v66
	v_cvt_pk_bf16_f32 v19, v67, v68
	v_cvt_pk_bf16_f32 v12, v40, v41
	v_cvt_pk_bf16_f32 v13, v42, v43
	v_cvt_pk_bf16_f32 v14, v44, v45
	v_cvt_pk_bf16_f32 v15, v46, v47
	v_cvt_pk_bf16_f32 v8, v28, v29
	v_cvt_pk_bf16_f32 v9, v30, v31
	v_cvt_pk_bf16_f32 v10, v70, v71
	v_cvt_pk_bf16_f32 v11, v72, v73
	v_cvt_pk_bf16_f32 v4, v69, v74
	v_cvt_pk_bf16_f32 v5, v75, v76
	v_cvt_pk_bf16_f32 v6, v77, v78
	v_cvt_pk_bf16_f32 v7, v79, v88
	v_cvt_pk_bf16_f32 v0, v89, v90
	v_cvt_pk_bf16_f32 v1, v91, v92
	v_cvt_pk_bf16_f32 v2, v93, v100
	v_cvt_pk_bf16_f32 v3, v101, v102
	v_cvt_pk_bf16_f32 v28, v103, v104
	v_cvt_pk_bf16_f32 v29, v105, v106
	v_cvt_pk_bf16_f32 v30, v107, v108
	v_cvt_pk_bf16_f32 v31, v109, v32
	v_lshlrev_b32_e32 v52, 2, v37
	v_lshrrev_b32_e32 v32, 2, v36
	v_add_u32_e32 v32, v32, v52
	v_lshlrev_b32_e32 v33, 3, v36
	v_and_b32_e32 v33, 24, v33
	v_mul_lo_u32 v32, v32, s30
	v_add3_u32 v38, s90, v33, v32
	ds_read_b64_tr_b16 v[230:231], v38
	ds_read_b64_tr_b16 v[232:233], v38 offset:4352
	ds_read_b64_tr_b16 v[234:235], v38 offset:8704
	ds_read_b64_tr_b16 v[236:237], v38 offset:13056
	ds_read_b64_tr_b16 v[242:243], v38 offset:17408
	ds_read_b64_tr_b16 v[244:245], v38 offset:21760
	ds_read_b64_tr_b16 v[246:247], v38 offset:26112
	ds_read_b64_tr_b16 v[248:249], v38 offset:30464
	ds_read_b64_tr_b16 v[186:187], v38 offset:34816
	ds_read_b64_tr_b16 v[188:189], v38 offset:39168
	s_nop 3
	s_waitcnt lgkmcnt(8)
	v_mfma_f32_16x16x32_bf16 v[32:35], v[230:233], v[24:27], 0
	s_nop 3
	v_div_scale_f32 v53, s[2:3], v39, v39, 1.0
	s_waitcnt lgkmcnt(6)
	v_mfma_f32_16x16x32_bf16 v[32:35], v[234:237], v[20:23], v[32:35]
	s_nop 1
	v_rcp_f32_e32 v37, v53
	s_add_u32 s2, s28, s0
	s_waitcnt lgkmcnt(4)
	v_mfma_f32_16x16x32_bf16 v[32:35], v[242:245], v[16:19], v[32:35]
	ds_read_b64_tr_b16 v[44:45], v38 offset:43520
	ds_read_b64_tr_b16 v[46:47], v38 offset:47872
	v_cmp_gt_i32_e64 s[0:1], 8, v36
	v_fma_f32 v36, -v53, v37, 1.0
	s_waitcnt lgkmcnt(4)
	v_mfma_f32_16x16x32_bf16 v[32:35], v[246:249], v[12:15], v[32:35]
	ds_read_b64_tr_b16 v[48:49], v38 offset:52224
	ds_read_b64_tr_b16 v[50:51], v38 offset:56576
	v_fmac_f32_e32 v37, v36, v37
	v_div_scale_f32 v36, vcc, 1.0, v39, 1.0
	s_waitcnt lgkmcnt(4)
	v_mfma_f32_16x16x32_bf16 v[32:35], v[186:189], v[8:11], v[32:35]
	ds_read_b64_tr_b16 v[40:41], v38 offset:60928
	ds_read_b64_tr_b16 v[42:43], v38 offset:65280
	v_mul_f32_e32 v54, v36, v37
	v_fma_f32 v55, -v53, v54, v36
	s_waitcnt lgkmcnt(4)
	v_mfma_f32_16x16x32_bf16 v[32:35], v[44:47], v[4:7], v[32:35]
	v_fmac_f32_e32 v54, v55, v37
	v_fma_f32 v36, -v53, v54, v36
	s_addc_u32 s3, s29, 0
	s_waitcnt lgkmcnt(2)
	v_mfma_f32_16x16x32_bf16 v[32:35], v[48:51], v[0:3], v[32:35]
	v_div_fmas_f32 v36, v36, v37, v54
	v_div_fixup_f32 v39, v36, v39, 1.0
	v_lshl_add_u64 v[36:37], s[2:3], 0, v[82:83]
	s_waitcnt lgkmcnt(0)
	v_mfma_f32_16x16x32_bf16 v[32:35], v[40:43], v[28:31], v[32:35]
	v_ashrrev_i32_e32 v53, 31, v52
	v_lshl_add_u64 v[36:37], v[52:53], 1, v[36:37]
	s_and_saveexec_b64 s[2:3], s[0:1]
	s_cbranch_execz .LBB0_603
	s_nop 3
	v_mul_f32_e32 v32, v32, v39
	v_mul_f32_e32 v33, v33, v39
	v_cvt_pk_bf16_f32 v32, v32, v33
	v_mul_f32_e32 v33, v34, v39
	v_mul_f32_e32 v34, v35, v39
	v_cvt_pk_bf16_f32 v33, v33, v34
	global_store_dwordx2 v[36:37], v[32:33], off

; template <bool SAMPLE>
; __device__ __forceinline__ void mem_unit(const Params& p, int l, LAS unsigned char* lds, int unit, int tid, int wave, int lane) {
;     ...
;     }
;     __syncthreads();
.LBB0_618:
	s_nop 0
	s_nop 0
	s_nop 0
	s_nop 0
	s_nop 0
	s_nop 0
	s_nop 0
	s_mov_b64 s[0:1], 0
	s_barrier

; __device__ __forceinline__ void unpack8(const v4u w, float (&o)[8]) { o[0] = bflo(w.x); o[1] = bfhi(w.x); o[2] = bflo(w.y); o[3] = bfhi(w.y); o[4] = bflo(w.z); o[5] = bfhi(w.z); o[6] = bflo(w.w); o[7] = bfhi(w.w); }
; __device__ __forceinline__ bf16x8 pack8(const float (&o)[8]) { v4u w; w.x = pk2(o[0], o[1]); w.y = pk2(o[2], o[3]); w.z = pk2(o[4], o[5]); w.w = pk2(o[6], o[7]); return __builtin_bit_cast(bf16x8, w); }
; template <bool SAMPLE>
; __device__ __forceinline__ void mem_unit(const Params& p, int l, LAS unsigned char* lds, int unit, int tid, int wave, int lane) {
;     ...
;       for (int qq = 0; qq < (SAMPLE ? 1 : 4); ++qq) {
;         int q16 = lane & 15, kq = lane >> 4; asm volatile("" : "+v"(q16), "+v"(kq));
;         size_t row; bool st;
;         if (!SAMPLE) { row = (size_t)b * 8192 + (qt * 4 + qq) * 128 + 16 * wave + q16; st = true; } else { row = (size_t)MP + 8 * b + (q16 & 7); st = q16 < 8; }
;         bf16x8 qf[4];
;         {
;             float qv[4][8]; float ss = 0.f;
; #pragma unroll
;             for (int dc = 0; dc < 4; ++dc) { unpack8(*(const v4u*)(MQ + row * 512 + h * 128 + 32 * dc + 8 * kq), qv[dc]);
; #pragma unroll
;                 for (int e = 0; e < 8; ++e) ss += qv[dc][e] * qv[dc][e]; }
;             ss += __shfl_xor(ss, 16); ss += __shfl_xor(ss, 32);
;             const float rs = rsqrtf(ss * (1.f / 128.f) + EPS) * 0.08838834764831845f;
; #pragma unroll
;             for (int dc = 0; dc < 4; ++dc) { float qg[8]; pg8::ld8f(p.in[I_MQG] + l * 128 + 32 * dc + 8 * kq, qg);
; #pragma unroll
;                 for (int e = 0; e < 8; ++e) qv[dc][e] *= rs * qg[e];
;                 qf[dc] = pack8(qv[dc]); }
;         }
.LBB0_631:
	v_mov_b32_e32 v90, v94
	v_mov_b32_e32 v92, v95
	s_add_u32 s16, s10, s8
	s_addc_u32 s17, s18, s9
	v_ashrrev_i32_e32 v91, 31, v90
	v_lshl_add_u64 v[0:1], s[16:17], 0, v[90:91]
	v_lshlrev_b32_e32 v8, 3, v92
	v_lshlrev_b64 v[88:89], 10, v[0:1]
	v_ashrrev_i32_e32 v9, 31, v8
	v_lshl_add_u64 v[10:11], s[0:1], 0, v[88:89]
	v_lshlrev_b32_e32 v2, 4, v92
	v_mul_lo_u32 v3, v90, s30
	v_lshl_add_u64 v[24:25], v[8:9], 2, s[46:47]
	v_lshl_add_u64 v[20:21], v[8:9], 1, v[10:11]
	v_add3_u32 v91, 0, v2, v3
	global_load_dwordx4 v[0:3], v[24:25], off offset:16
	global_load_dwordx4 v[4:7], v[24:25], off
	global_load_dwordx4 v[8:11], v[20:21], off
	global_load_dwordx4 v[12:15], v[20:21], off offset:64
	global_load_dwordx4 v[16:19], v[20:21], off offset:128
	s_nop 0
	global_load_dwordx4 v[20:23], v[20:21], off offset:192
	v_lshlrev_b32_e32 v92, 2, v92
	v_ashrrev_i32_e32 v93, 31, v92
	s_add_u32 s8, s8, 0x80
	s_addc_u32 s9, s9, 0
	s_cmpk_lg_i32 s8, 0x200
	s_waitcnt vmcnt(3)
	v_and_b32_e32 v31, 0xffff0000, v8
	v_lshlrev_b32_e32 v30, 16, v8
	v_mul_f32_e32 v50, v31, v31
	v_lshlrev_b32_e32 v32, 16, v9
	v_fmac_f32_e32 v50, v30, v30
	v_and_b32_e32 v33, 0xffff0000, v9
	v_fmac_f32_e32 v50, v32, v32
	v_lshlrev_b32_e32 v34, 16, v10
	v_fmac_f32_e32 v50, v33, v33
	v_and_b32_e32 v35, 0xffff0000, v10
	v_fmac_f32_e32 v50, v34, v34
	v_lshlrev_b32_e32 v36, 16, v11
	v_fmac_f32_e32 v50, v35, v35
	v_and_b32_e32 v37, 0xffff0000, v11
	v_fmac_f32_e32 v50, v36, v36
	s_waitcnt vmcnt(2)
	v_lshlrev_b32_e32 v38, 16, v12
	v_fmac_f32_e32 v50, v37, v37
	v_and_b32_e32 v39, 0xffff0000, v12
	v_fmac_f32_e32 v50, v38, v38
	v_lshlrev_b32_e32 v40, 16, v13
	v_fmac_f32_e32 v50, v39, v39
	v_and_b32_e32 v41, 0xffff0000, v13
	v_fmac_f32_e32 v50, v40, v40
	v_lshlrev_b32_e32 v42, 16, v14
	v_fmac_f32_e32 v50, v41, v41
	v_and_b32_e32 v43, 0xffff0000, v14
	v_fmac_f32_e32 v50, v42, v42
	v_lshlrev_b32_e32 v44, 16, v15
	v_fmac_f32_e32 v50, v43, v43
	v_and_b32_e32 v45, 0xffff0000, v15
	v_fmac_f32_e32 v50, v44, v44
	s_waitcnt vmcnt(1)
	v_lshlrev_b32_e32 v46, 16, v16
	v_fmac_f32_e32 v50, v45, v45
	v_and_b32_e32 v16, 0xffff0000, v16
	v_fmac_f32_e32 v50, v46, v46
	v_lshlrev_b32_e32 v47, 16, v17
	v_fmac_f32_e32 v50, v16, v16
	v_and_b32_e32 v17, 0xffff0000, v17
	v_fmac_f32_e32 v50, v47, v47
	v_lshlrev_b32_e32 v48, 16, v18
	v_fmac_f32_e32 v50, v17, v17
	v_and_b32_e32 v18, 0xffff0000, v18
	v_fmac_f32_e32 v50, v48, v48
	v_lshlrev_b32_e32 v49, 16, v19
	v_fmac_f32_e32 v50, v18, v18
	v_and_b32_e32 v19, 0xffff0000, v19
	s_waitcnt vmcnt(0)
	v_and_b32_e32 v26, 0xffff0000, v20
	v_lshlrev_b32_e32 v27, 16, v20
	v_fmac_f32_e32 v50, v49, v49
	v_pk_mul_f32 v[8:9], v[26:27], v[26:27]
	v_fmac_f32_e32 v50, v19, v19
	v_and_b32_e32 v20, 0xffff0000, v21
	v_lshlrev_b32_e32 v21, 16, v21
	v_add_f32_e32 v9, v9, v50
	v_pk_mul_f32 v[10:11], v[20:21], v[20:21]
	v_add_f32_e32 v8, v8, v9
	v_and_b32_e32 v28, 0xffff0000, v22
	v_lshlrev_b32_e32 v29, 16, v22
	v_add_f32_e32 v8, v11, v8
	v_pk_mul_f32 v[12:13], v[28:29], v[28:29]
	v_add_f32_e32 v8, v10, v8
	v_and_b32_e32 v22, 0xffff0000, v23
	v_lshlrev_b32_e32 v23, 16, v23
	v_add_f32_e32 v8, v13, v8
	v_pk_mul_f32 v[14:15], v[22:23], v[22:23]
	v_add_f32_e32 v8, v12, v8
	v_add_f32_e32 v8, v15, v8
	v_add_f32_e32 v8, v14, v8
	ds_bpermute_b32 v9, v82, v8
	s_waitcnt lgkmcnt(0)
	v_add_f32_e32 v8, v8, v9
	ds_bpermute_b32 v9, v100, v8
	s_waitcnt lgkmcnt(0)
	v_add_f32_e32 v8, v8, v9
	v_fmamk_f32 v8, v8, 0x3c000000, v98
	v_mul_f32_e32 v9, 0x4b800000, v8
	v_cmp_gt_f32_e32 vcc, s31, v8
	s_nop 1
	v_cndmask_b32_e32 v8, v8, v9, vcc
	v_rsq_f32_e32 v8, v8
	s_nop 0
	v_mul_f32_e32 v9, 0x45800000, v8
	v_cndmask_b32_e32 v8, v8, v9, vcc
	v_mul_f32_e32 v50, 0x3db504f3, v8
	v_mul_f32_e32 v4, v4, v50
	v_mul_f32_e32 v5, v5, v50
	v_mul_f32_e32 v6, v6, v50
	v_mul_f32_e32 v7, v7, v50
	v_mul_f32_e32 v0, v0, v50
	v_mul_f32_e32 v1, v1, v50
	v_mul_f32_e32 v2, v2, v50
	v_mul_f32_e32 v3, v3, v50
	v_mul_f32_e32 v4, v4, v30
	v_mul_f32_e32 v5, v5, v31
	v_mul_f32_e32 v6, v6, v32
	v_mul_f32_e32 v7, v7, v33
	v_mul_f32_e32 v0, v0, v34
	v_mul_f32_e32 v1, v1, v35
	v_mul_f32_e32 v2, v2, v36
	v_mul_f32_e32 v3, v3, v37
	v_cvt_pk_bf16_f32 v8, v4, v5
	v_cvt_pk_bf16_f32 v9, v6, v7
	v_cvt_pk_bf16_f32 v10, v0, v1
	v_cvt_pk_bf16_f32 v11, v2, v3
	global_load_dwordx4 v[0:3], v[24:25], off offset:128
	global_load_dwordx4 v[4:7], v[24:25], off offset:144
	s_waitcnt vmcnt(1)
	v_mul_f32_e32 v0, v0, v50
	v_mul_f32_e32 v1, v1, v50
	v_mul_f32_e32 v2, v2, v50
	v_mul_f32_e32 v3, v3, v50
	s_waitcnt vmcnt(0)
	v_mul_f32_e32 v4, v4, v50
	v_mul_f32_e32 v5, v5, v50
	v_mul_f32_e32 v6, v6, v50
	v_mul_f32_e32 v7, v7, v50
	v_mul_f32_e32 v0, v0, v38
	v_mul_f32_e32 v1, v1, v39
	v_mul_f32_e32 v2, v2, v40
	v_mul_f32_e32 v3, v3, v41
	v_mul_f32_e32 v4, v4, v42
	v_mul_f32_e32 v5, v5, v43
	v_mul_f32_e32 v6, v6, v44
	v_mul_f32_e32 v7, v7, v45
	v_cvt_pk_bf16_f32 v12, v0, v1
	v_cvt_pk_bf16_f32 v13, v2, v3
	v_cvt_pk_bf16_f32 v14, v4, v5
	v_cvt_pk_bf16_f32 v15, v6, v7
	global_load_dwordx4 v[0:3], v[24:25], off offset:256
	global_load_dwordx4 v[4:7], v[24:25], off offset:272
	s_waitcnt vmcnt(1)
	v_mul_f32_e32 v0, v0, v50
	v_mul_f32_e32 v1, v1, v50
	v_mul_f32_e32 v2, v2, v50
	v_mul_f32_e32 v3, v3, v50
	s_waitcnt vmcnt(0)
	v_mul_f32_e32 v4, v4, v50
	v_mul_f32_e32 v5, v5, v50
	v_mul_f32_e32 v6, v6, v50
	v_mul_f32_e32 v7, v7, v50
	v_mul_f32_e32 v0, v0, v46
	v_mul_f32_e32 v1, v1, v16
	v_mul_f32_e32 v2, v2, v47
	v_mul_f32_e32 v3, v3, v17
	v_mul_f32_e32 v16, v4, v48
	v_mul_f32_e32 v17, v5, v18
	v_mul_f32_e32 v18, v6, v49
	v_mul_f32_e32 v7, v7, v19
	v_cvt_pk_bf16_f32 v4, v0, v1
	v_cvt_pk_bf16_f32 v5, v2, v3
	v_cvt_pk_bf16_f32 v6, v16, v17
	v_cvt_pk_bf16_f32 v7, v18, v7
	global_load_dwordx4 v[0:3], v[24:25], off offset:384
	global_load_dwordx4 v[16:19], v[24:25], off offset:400
	s_waitcnt vmcnt(1)
; #define LAS __attribute__((address_space(3)))
; __device__ __forceinline__ bf16x8 pack8(const float (&o)[8]) { v4u w; w.x = pk2(o[0], o[1]); w.y = pk2(o[2], o[3]); w.z = pk2(o[4], o[5]); w.w = pk2(o[6], o[7]); return __builtin_bit_cast(bf16x8, w); }
; template <bool SAMPLE>
; __device__ __forceinline__ void mem_unit(const Params& p, int l, LAS unsigned char* lds, int unit, int tid, int wave, int lane) {
;     ...
;             for (int dc = 0; dc < 4; ++dc) { float qg[8]; pg8::ld8f(p.in[I_MQG] + l * 128 + 32 * dc + 8 * kq, qg);
; #pragma unroll
;                 for (int e = 0; e < 8; ++e) qv[dc][e] *= rs * qg[e];
;                 qf[dc] = pack8(qv[dc]); }
;         }
;         f32x4 S[8][2]; float mx = -INFINITY;
; #pragma unroll
;         for (int cc = 0; cc < 8; ++cc)
; #pragma unroll
;             for (int tt = 0; tt < 2; ++tt) { const int kb = 32 * cc + 16 * tt; f32x4 a = (f32x4){0.f, 0.f, 0.f, 0.f};
; #pragma unroll
;                 for (int dc = 0; dc < 4; ++dc) { const bf16x8 kf = *(const LAS bf16x8*)(Kl + (kb + q16) * MEM_KS + 32 * dc + 8 * kq);
;                     a = __builtin_amdgcn_mfma_f32_16x16x32_bf16(kf, qf[dc], a, 0, 0, 0); }
; #pragma unroll
;                 for (int e = 0; e < 4; ++e) mx = fmaxf(mx, a[e]);
;                 S[cc][tt] = a; }
	v_mul_f32_e32 v0, v0, v50
	v_mul_f32_e32 v1, v1, v50
	v_mul_f32_e32 v2, v2, v50
	v_mul_f32_e32 v3, v3, v50
	s_waitcnt vmcnt(0)
	v_mul_f32_e32 v16, v16, v50
	v_mul_f32_e32 v17, v17, v50
	v_mul_f32_e32 v18, v18, v50
	v_mul_f32_e32 v19, v19, v50
	v_mul_f32_e32 v0, v0, v27
	v_mul_f32_e32 v1, v1, v26
	v_mul_f32_e32 v2, v2, v21
	v_mul_f32_e32 v3, v3, v20
	v_mul_f32_e32 v16, v16, v29
	v_mul_f32_e32 v17, v17, v28
	v_mul_f32_e32 v18, v18, v23
	v_mul_f32_e32 v19, v19, v22
	v_cvt_pk_bf16_f32 v0, v0, v1
	v_cvt_pk_bf16_f32 v1, v2, v3
	v_cvt_pk_bf16_f32 v2, v16, v17
	v_cvt_pk_bf16_f32 v3, v18, v19
	ds_read_b128 v[186:189], v91
	ds_read_b128 v[190:193], v91 offset:4352
	ds_read_b128 v[194:197], v91 offset:8704
	ds_read_b128 v[198:201], v91 offset:13056
	ds_read_b128 v[202:205], v91 offset:17408
	ds_read_b128 v[206:209], v91 offset:21760
	ds_read_b128 v[210:213], v91 offset:26112
	s_nop 0
	ds_read_b128 v[20:23], v91 offset:64
	s_nop 0
	ds_read_b128 v[28:31], v91 offset:4416
	s_nop 0
	ds_read_b128 v[36:39], v91 offset:8768
	s_nop 0
	ds_read_b128 v[44:47], v91 offset:13120
	s_nop 0
	ds_read_b128 v[52:55], v91 offset:17472
	s_nop 0
	ds_read_b128 v[60:63], v91 offset:21824
	s_nop 0
	ds_read_b128 v[68:71], v91 offset:26176
	ds_read_b128 v[72:75], v91 offset:30464
	ds_read_b128 v[76:79], v91 offset:30528
	ds_read_b128 v[102:105], v91 offset:34816
	ds_read_b128 v[106:109], v91 offset:34880
	ds_read_b128 v[110:113], v91 offset:39168
	ds_read_b128 v[114:117], v91 offset:39232
	ds_read_b128 v[118:121], v91 offset:43520
	ds_read_b128 v[122:125], v91 offset:43584
	ds_read_b128 v[126:129], v91 offset:47872
	ds_read_b128 v[130:133], v91 offset:47936
	ds_read_b128 v[134:137], v91 offset:52224
	ds_read_b128 v[138:141], v91 offset:52288
	ds_read_b128 v[142:145], v91 offset:56576
	ds_read_b128 v[146:149], v91 offset:56640
	ds_read_b128 v[150:153], v91 offset:60928
	ds_read_b128 v[154:157], v91 offset:60992
	ds_read_b128 v[158:161], v91 offset:65280
	ds_read_b128 v[162:165], v91 offset:65344
	s_waitcnt lgkmcnt(14)
	v_mfma_f32_16x16x32_bf16 v[16:19], v[186:189], v[8:11], 0
	v_mfma_f32_16x16x32_bf16 v[24:27], v[190:193], v[8:11], 0
	v_mfma_f32_16x16x32_bf16 v[32:35], v[194:197], v[8:11], 0
	v_mfma_f32_16x16x32_bf16 v[40:43], v[198:201], v[8:11], 0
	v_mfma_f32_16x16x32_bf16 v[48:51], v[202:205], v[8:11], 0
	v_mfma_f32_16x16x32_bf16 v[56:59], v[206:209], v[8:11], 0
	v_mfma_f32_16x16x32_bf16 v[64:67], v[210:213], v[8:11], 0
	v_mfma_f32_16x16x32_bf16 v[72:75], v[72:75], v[8:11], 0
	v_mfma_f32_16x16x32_bf16 v[102:105], v[102:105], v[8:11], 0
	s_waitcnt lgkmcnt(13)
	v_mfma_f32_16x16x32_bf16 v[110:113], v[110:113], v[8:11], 0
	s_waitcnt lgkmcnt(11)
	v_mfma_f32_16x16x32_bf16 v[118:121], v[118:121], v[8:11], 0
	s_waitcnt lgkmcnt(9)
	v_mfma_f32_16x16x32_bf16 v[126:129], v[126:129], v[8:11], 0
	s_waitcnt lgkmcnt(7)
	v_mfma_f32_16x16x32_bf16 v[134:137], v[134:137], v[8:11], 0
	s_waitcnt lgkmcnt(5)
	v_mfma_f32_16x16x32_bf16 v[142:145], v[142:145], v[8:11], 0
	s_waitcnt lgkmcnt(3)
	v_mfma_f32_16x16x32_bf16 v[150:153], v[150:153], v[8:11], 0
	s_waitcnt lgkmcnt(1)
	v_mfma_f32_16x16x32_bf16 v[8:11], v[158:161], v[8:11], 0
	v_mfma_f32_16x16x32_bf16 v[16:19], v[20:23], v[12:15], v[16:19]
	v_mfma_f32_16x16x32_bf16 v[20:23], v[28:31], v[12:15], v[24:27]
	v_mfma_f32_16x16x32_bf16 v[24:27], v[36:39], v[12:15], v[32:35]
	v_mfma_f32_16x16x32_bf16 v[28:31], v[44:47], v[12:15], v[40:43]
	v_mfma_f32_16x16x32_bf16 v[32:35], v[52:55], v[12:15], v[48:51]
	ds_read_b128 v[202:205], v91 offset:128
	ds_read_b128 v[206:209], v91 offset:4480
	ds_read_b128 v[210:213], v91 offset:8832
	v_mfma_f32_16x16x32_bf16 v[36:39], v[60:63], v[12:15], v[56:59]
	v_mfma_f32_16x16x32_bf16 v[40:43], v[68:71], v[12:15], v[64:67]
	v_mfma_f32_16x16x32_bf16 v[44:47], v[76:79], v[12:15], v[72:75]
	v_mfma_f32_16x16x32_bf16 v[48:51], v[106:109], v[12:15], v[102:105]
	v_mfma_f32_16x16x32_bf16 v[52:55], v[114:117], v[12:15], v[110:113]
	v_mfma_f32_16x16x32_bf16 v[56:59], v[122:125], v[12:15], v[118:121]
	v_mfma_f32_16x16x32_bf16 v[60:63], v[130:133], v[12:15], v[126:129]
	ds_read_b128 v[218:221], v91 offset:13184
	ds_read_b128 v[222:225], v91 offset:17536
	ds_read_b128 v[226:229], v91 offset:21888
	ds_read_b128 v[230:233], v91 offset:26240
	ds_read_b128 v[234:237], v91 offset:30592
	ds_read_b128 v[242:245], v91 offset:34944
	ds_read_b128 v[246:249], v91 offset:39296
	v_mfma_f32_16x16x32_bf16 v[64:67], v[138:141], v[12:15], v[134:137]
	v_mfma_f32_16x16x32_bf16 v[68:71], v[146:149], v[12:15], v[142:145]
	v_mfma_f32_16x16x32_bf16 v[102:105], v[154:157], v[12:15], v[150:153]
	s_waitcnt lgkmcnt(10)
	v_mfma_f32_16x16x32_bf16 v[8:11], v[162:165], v[12:15], v[8:11]
	s_nop 0
	ds_read_b128 v[106:109], v91 offset:192
	s_waitcnt lgkmcnt(10)
	v_mfma_f32_16x16x32_bf16 v[12:15], v[202:205], v[4:7], v[16:19]
	s_nop 2
	s_nop 0
	ds_read_b128 v[110:113], v91 offset:4544
	s_waitcnt lgkmcnt(10)
	v_mfma_f32_16x16x32_bf16 v[16:19], v[206:209], v[4:7], v[20:23]
	s_nop 2
	s_nop 0
	ds_read_b128 v[114:117], v91 offset:8896
	s_waitcnt lgkmcnt(10)
	v_mfma_f32_16x16x32_bf16 v[20:23], v[210:213], v[4:7], v[24:27]
	s_nop 2
	s_nop 0
	ds_read_b128 v[118:121], v91 offset:13248
	s_waitcnt lgkmcnt(10)
	ds_read_b128 v[186:189], v91 offset:43648
	ds_read_b128 v[190:193], v91 offset:48000
	ds_read_b128 v[194:197], v91 offset:52352
	ds_read_b128 v[198:201], v91 offset:56704
	ds_read_b128 v[202:205], v91 offset:61056
	ds_read_b128 v[206:209], v91 offset:65408
	v_mfma_f32_16x16x32_bf16 v[24:27], v[218:221], v[4:7], v[28:31]
	s_nop 2
	s_nop 0
	ds_read_b128 v[122:125], v91 offset:17600
	s_waitcnt lgkmcnt(15)
; #define LAS __attribute__((address_space(3)))
; __device__ __forceinline__ v2u vtr(const LAS bf16* p) { return __builtin_bit_cast(v2u, __builtin_amdgcn_ds_read_tr16_b64_v4i16((LAS v4i16_t*)p)); }
; template <bool SAMPLE>
; __device__ __forceinline__ void mem_unit(const Params& p, int l, LAS unsigned char* lds, int unit, int tid, int wave, int lane) {
;     ...
;         f32x4 S[8][2]; float mx = -INFINITY;
; #pragma unroll
;         for (int cc = 0; cc < 8; ++cc)
; #pragma unroll
;             for (int tt = 0; tt < 2; ++tt) { const int kb = 32 * cc + 16 * tt; f32x4 a = (f32x4){0.f, 0.f, 0.f, 0.f};
; #pragma unroll
;                 for (int dc = 0; dc < 4; ++dc) { const bf16x8 kf = *(const LAS bf16x8*)(Kl + (kb + q16) * MEM_KS + 32 * dc + 8 * kq);
;                     a = __builtin_amdgcn_mfma_f32_16x16x32_bf16(kf, qf[dc], a, 0, 0, 0); }
; #pragma unroll
;                 for (int e = 0; e < 4; ++e) mx = fmaxf(mx, a[e]);
;                 S[cc][tt] = a; }
;         mx = fmaxf(mx, __shfl_xor(mx, 16)); mx = fmaxf(mx, __shfl_xor(mx, 32));
;     ...
; #pragma unroll
;         for (int dt = 0; dt < 8; ++dt) { f32x4 o = (f32x4){0.f, 0.f, 0.f, 0.f};
; #pragma unroll
;             for (int cc = 0; cc < 8; ++cc) { const LAS bf16* vp = Vt + (32 * cc + 4 * kq + (q16 >> 2)) * MEM_VS + 16 * dt + 4 * (q16 & 3);
;                 const v2u lo = vtr(vp), hi = vtr(vp + 16 * MEM_VS);
;                 v4u av; av.x = lo.x; av.y = lo.y; av.z = hi.x; av.w = hi.y;
;                 o = __builtin_amdgcn_mfma_f32_16x16x32_bf16(__builtin_bit_cast(bf16x8, av), pf[cc], o, 0, 0, 0); }
	v_mfma_f32_16x16x32_bf16 v[28:31], v[222:225], v[4:7], v[32:35]
	s_nop 2
	s_nop 0
	ds_read_b128 v[126:129], v91 offset:21952
	s_waitcnt lgkmcnt(15)
	v_mfma_f32_16x16x32_bf16 v[32:35], v[226:229], v[4:7], v[36:39]
	s_nop 2
	s_nop 0
	ds_read_b128 v[130:133], v91 offset:26304
	s_waitcnt lgkmcnt(15)
	v_mfma_f32_16x16x32_bf16 v[134:137], v[230:233], v[4:7], v[40:43]
	s_nop 0
	ds_read_b128 v[138:141], v91 offset:30656
	s_waitcnt lgkmcnt(15)
	v_mfma_f32_16x16x32_bf16 v[142:145], v[234:237], v[4:7], v[44:47]
	s_nop 0
	ds_read_b128 v[146:149], v91 offset:35008
	s_waitcnt lgkmcnt(15)
	v_mfma_f32_16x16x32_bf16 v[150:153], v[242:245], v[4:7], v[48:51]
	s_nop 0
	ds_read_b128 v[154:157], v91 offset:39360
	s_waitcnt lgkmcnt(15)
	v_mfma_f32_16x16x32_bf16 v[158:161], v[246:249], v[4:7], v[52:55]
	s_nop 0
	ds_read_b128 v[162:165], v91 offset:43712
	s_waitcnt lgkmcnt(12)
	v_mfma_f32_16x16x32_bf16 v[166:169], v[186:189], v[4:7], v[56:59]
	s_nop 0
	ds_read_b128 v[170:173], v91 offset:48064
	s_waitcnt lgkmcnt(12)
	v_mfma_f32_16x16x32_bf16 v[174:177], v[190:193], v[4:7], v[60:63]
	s_nop 0
	ds_read_b128 v[178:181], v91 offset:52416
	s_waitcnt lgkmcnt(12)
	v_mfma_f32_16x16x32_bf16 v[182:185], v[194:197], v[4:7], v[64:67]
	s_nop 0
	ds_read_b128 v[72:75], v91 offset:56768
	s_waitcnt lgkmcnt(12)
	v_mfma_f32_16x16x32_bf16 v[76:79], v[198:201], v[4:7], v[68:71]
	s_nop 0
	ds_read_b128 v[64:67], v91 offset:61120
	s_waitcnt lgkmcnt(12)
	v_mfma_f32_16x16x32_bf16 v[68:71], v[202:205], v[4:7], v[102:105]
	s_nop 0
	ds_read_b128 v[56:59], v91 offset:65472
	v_lshrrev_b32_e32 v91, 2, v90
	s_waitcnt lgkmcnt(12)
	v_mfma_f32_16x16x32_bf16 v[60:63], v[206:209], v[4:7], v[8:11]
	v_mfma_f32_16x16x32_bf16 v[52:55], v[106:109], v[0:3], v[12:15]
	v_mfma_f32_16x16x32_bf16 v[48:51], v[110:113], v[0:3], v[16:19]
	v_mfma_f32_16x16x32_bf16 v[44:47], v[114:117], v[0:3], v[20:23]
	v_mfma_f32_16x16x32_bf16 v[40:43], v[118:121], v[0:3], v[24:27]
	v_mfma_f32_16x16x32_bf16 v[36:39], v[122:125], v[0:3], v[28:31]
	v_mfma_f32_16x16x32_bf16 v[32:35], v[126:129], v[0:3], v[32:35]
	v_mfma_f32_16x16x32_bf16 v[28:31], v[130:133], v[0:3], v[134:137]
	v_mfma_f32_16x16x32_bf16 v[24:27], v[138:141], v[0:3], v[142:145]
	v_mfma_f32_16x16x32_bf16 v[20:23], v[146:149], v[0:3], v[150:153]
	v_mfma_f32_16x16x32_bf16 v[16:19], v[154:157], v[0:3], v[158:161]
	v_mfma_f32_16x16x32_bf16 v[12:15], v[162:165], v[0:3], v[166:169]
	v_mfma_f32_16x16x32_bf16 v[8:11], v[170:173], v[0:3], v[174:177]
	v_mfma_f32_16x16x32_bf16 v[4:7], v[178:181], v[0:3], v[182:185]
	v_mfma_f32_16x16x32_bf16 v[72:75], v[72:75], v[0:3], v[76:79]
	v_mfma_f32_16x16x32_bf16 v[66:69], v[64:67], v[0:3], v[68:71]
	s_nop 1
	v_lshlrev_b32_e32 v76, 3, v90
	v_add_u32_e32 v77, v91, v92
	v_and_b32_e32 v76, 24, v76
	s_waitcnt lgkmcnt(0)
	v_mfma_f32_16x16x32_bf16 v[0:3], v[56:59], v[0:3], v[60:63]
	v_max3_f32 v56, v52, s33, v53
	v_max3_f32 v56, v56, v54, v55
	v_max3_f32 v56, v56, v48, v49
	v_max3_f32 v56, v56, v50, v51
	v_max3_f32 v56, v56, v44, v45
	v_max3_f32 v56, v56, v46, v47
	v_max3_f32 v56, v56, v40, v41
	v_max3_f32 v56, v56, v42, v43
	v_max3_f32 v56, v56, v36, v37
	v_max3_f32 v56, v56, v38, v39
	v_max3_f32 v56, v56, v32, v33
	v_max3_f32 v56, v56, v34, v35
	v_max3_f32 v56, v56, v28, v29
	v_max3_f32 v56, v56, v30, v31
	v_max3_f32 v56, v56, v24, v25
	v_max3_f32 v56, v56, v26, v27
	v_max3_f32 v56, v56, v20, v21
	v_max3_f32 v56, v56, v22, v23
	v_max3_f32 v56, v56, v16, v17
	v_max3_f32 v56, v56, v18, v19
	v_max3_f32 v56, v56, v12, v13
	v_max3_f32 v56, v56, v14, v15
	v_max3_f32 v56, v56, v8, v9
	v_max3_f32 v56, v56, v10, v11
	v_max3_f32 v56, v56, v4, v5
	v_max3_f32 v56, v56, v6, v7
	v_max3_f32 v56, v56, v72, v73
	v_max3_f32 v56, v56, v74, v75
	v_max3_f32 v56, v56, v66, v67
	v_max3_f32 v56, v56, v68, v69
	v_max3_f32 v56, v56, v0, v1
	v_max3_f32 v56, v56, v2, v3
	ds_bpermute_b32 v57, v82, v56
	v_mul_lo_u32 v64, v77, s30
	v_add3_u32 v64, s90, v76, v64
	ds_read_b64_tr_b16 v[198:199], v64
	ds_read_b64_tr_b16 v[200:201], v64 offset:4352
	ds_read_b64_tr_b16 v[202:203], v64 offset:8704
	ds_read_b64_tr_b16 v[204:205], v64 offset:13056
	ds_read_b64_tr_b16 v[206:207], v64 offset:17408
	ds_read_b64_tr_b16 v[208:209], v64 offset:21760
	ds_read_b64_tr_b16 v[210:211], v64 offset:26112
	ds_read_b64_tr_b16 v[212:213], v64 offset:30464
	ds_read_b64_tr_b16 v[218:219], v64 offset:34816
	ds_read_b64_tr_b16 v[220:221], v64 offset:39168
	ds_read_b64_tr_b16 v[222:223], v64 offset:32
	ds_read_b64_tr_b16 v[224:225], v64 offset:4384
	ds_read_b64_tr_b16 v[226:227], v64 offset:8736
	ds_read_b64_tr_b16 v[228:229], v64 offset:13088
	ds_read_b64_tr_b16 v[230:231], v64 offset:17440
	ds_read_b64_tr_b16 v[232:233], v64 offset:21792
	ds_read_b64_tr_b16 v[234:235], v64 offset:26144
	ds_read_b64_tr_b16 v[236:237], v64 offset:30496
	ds_read_b64_tr_b16 v[242:243], v64 offset:34848
	ds_read_b64_tr_b16 v[244:245], v64 offset:39200
	ds_read_b64_tr_b16 v[246:247], v64 offset:43552
	ds_read_b64_tr_b16 v[248:249], v64 offset:47904
	s_waitcnt lgkmcnt(15)
	v_max_f32_e32 v57, v57, v57
	v_max_f32_e32 v56, v56, v57
	ds_bpermute_b32 v57, v100, v56
	s_waitcnt lgkmcnt(0)
; template <bool SAMPLE>
; __device__ __forceinline__ void mem_unit(const Params& p, int l, LAS unsigned char* lds, int unit, int tid, int wave, int lane) {
;     ...
;         mx = fmaxf(mx, __shfl_xor(mx, 16)); mx = fmaxf(mx, __shfl_xor(mx, 32));
;         float den = 0.f;
; #pragma unroll
;         for (int cc = 0; cc < 8; ++cc)
; #pragma unroll
;             for (int tt = 0; tt < 2; ++tt)
; #pragma unroll
;                 for (int e = 0; e < 4; ++e) { const float pe = __expf(S[cc][tt][e] - mx); S[cc][tt][e] = pe; den += pe; }
	v_max_f32_e32 v57, v57, v57
	v_max_f32_e32 v56, v56, v57
	v_sub_f32_e32 v52, v52, v56
	v_sub_f32_e32 v53, v53, v56
	v_mul_f32_e32 v52, 0x3fb8aa3b, v52
	v_sub_f32_e32 v54, v54, v56
	v_sub_f32_e32 v57, v72, v56
	v_sub_f32_e32 v58, v73, v56
	v_sub_f32_e32 v59, v74, v56
	v_sub_f32_e32 v60, v75, v56
	v_sub_f32_e32 v61, v66, v56
	v_sub_f32_e32 v62, v67, v56
	v_sub_f32_e32 v63, v68, v56
	v_sub_f32_e32 v65, v69, v56
	v_mul_f32_e32 v53, 0x3fb8aa3b, v53
	v_exp_f32_e32 v52, v52
	v_sub_f32_e32 v55, v55, v56
	v_sub_f32_e32 v48, v48, v56
	v_sub_f32_e32 v49, v49, v56
	v_sub_f32_e32 v50, v50, v56
	v_sub_f32_e32 v51, v51, v56
	v_sub_f32_e32 v44, v44, v56
	v_sub_f32_e32 v45, v45, v56
	v_sub_f32_e32 v46, v46, v56
	v_sub_f32_e32 v47, v47, v56
	v_sub_f32_e32 v40, v40, v56
	v_sub_f32_e32 v41, v41, v56
	v_sub_f32_e32 v42, v42, v56
	v_sub_f32_e32 v43, v43, v56
	v_sub_f32_e32 v36, v36, v56
	v_sub_f32_e32 v37, v37, v56
	v_sub_f32_e32 v38, v38, v56
	v_sub_f32_e32 v39, v39, v56
	v_sub_f32_e32 v32, v32, v56
	v_sub_f32_e32 v33, v33, v56
	v_sub_f32_e32 v34, v34, v56
	v_sub_f32_e32 v35, v35, v56
	v_sub_f32_e32 v28, v28, v56
	v_sub_f32_e32 v29, v29, v56
	v_sub_f32_e32 v30, v30, v56
	v_sub_f32_e32 v31, v31, v56
	v_sub_f32_e32 v24, v24, v56
	v_sub_f32_e32 v25, v25, v56
	v_sub_f32_e32 v26, v26, v56
	v_sub_f32_e32 v27, v27, v56
	v_sub_f32_e32 v20, v20, v56
	v_sub_f32_e32 v21, v21, v56
	v_sub_f32_e32 v22, v22, v56
	v_sub_f32_e32 v23, v23, v56
	v_sub_f32_e32 v16, v16, v56
	v_sub_f32_e32 v17, v17, v56
	v_sub_f32_e32 v18, v18, v56
	v_sub_f32_e32 v19, v19, v56
	v_sub_f32_e32 v12, v12, v56
	v_sub_f32_e32 v13, v13, v56
	v_sub_f32_e32 v14, v14, v56
	v_sub_f32_e32 v15, v15, v56
	v_sub_f32_e32 v8, v8, v56
	v_sub_f32_e32 v9, v9, v56
	v_sub_f32_e32 v10, v10, v56
	v_sub_f32_e32 v11, v11, v56
	v_sub_f32_e32 v4, v4, v56
	v_sub_f32_e32 v5, v5, v56
	v_sub_f32_e32 v6, v6, v56
	v_sub_f32_e32 v7, v7, v56
	v_sub_f32_e32 v0, v0, v56
	v_sub_f32_e32 v1, v1, v56
	v_sub_f32_e32 v2, v2, v56
	v_sub_f32_e32 v3, v3, v56
	v_mul_f32_e32 v54, 0x3fb8aa3b, v54
	v_mul_f32_e32 v56, 0x3fb8aa3b, v57
	v_mul_f32_e32 v57, 0x3fb8aa3b, v58
	v_mul_f32_e32 v58, 0x3fb8aa3b, v59
	v_mul_f32_e32 v59, 0x3fb8aa3b, v60
	v_mul_f32_e32 v60, 0x3fb8aa3b, v61
	v_mul_f32_e32 v61, 0x3fb8aa3b, v62
	v_mul_f32_e32 v62, 0x3fb8aa3b, v63
	v_mul_f32_e32 v63, 0x3fb8aa3b, v65
	v_exp_f32_e32 v65, v53
	v_mul_f32_e32 v55, 0x3fb8aa3b, v55
	v_exp_f32_e32 v66, v54
	v_mul_f32_e32 v48, 0x3fb8aa3b, v48
	v_exp_f32_e32 v67, v55
	v_mul_f32_e32 v49, 0x3fb8aa3b, v49
	v_mul_f32_e32 v0, 0x3fb8aa3b, v0
	v_exp_f32_e32 v68, v48
	v_add_f32_e32 v147, 0, v52
	v_mul_f32_e32 v50, 0x3fb8aa3b, v50
	v_exp_f32_e32 v69, v49
	v_exp_f32_e32 v143, v0
	v_cvt_pk_bf16_f32 v0, v52, v65
	v_add_f32_e32 v65, v65, v147
	v_mul_f32_e32 v51, 0x3fb8aa3b, v51
	v_exp_f32_e32 v70, v50
	v_add_f32_e32 v65, v66, v65
	v_mul_f32_e32 v44, 0x3fb8aa3b, v44
	v_exp_f32_e32 v71, v51
	v_add_f32_e32 v65, v67, v65
	v_mul_f32_e32 v45, 0x3fb8aa3b, v45
	v_exp_f32_e32 v72, v44
	v_add_f32_e32 v65, v68, v65
	v_mul_f32_e32 v46, 0x3fb8aa3b, v46
	v_exp_f32_e32 v73, v45
	v_add_f32_e32 v65, v69, v65
	v_mul_f32_e32 v47, 0x3fb8aa3b, v47
	v_exp_f32_e32 v74, v46
	v_add_f32_e32 v65, v70, v65
	v_mul_f32_e32 v40, 0x3fb8aa3b, v40
	v_exp_f32_e32 v75, v47
	v_add_f32_e32 v65, v71, v65
	v_mul_f32_e32 v41, 0x3fb8aa3b, v41
	v_mul_f32_e32 v42, 0x3fb8aa3b, v42
	v_mul_f32_e32 v43, 0x3fb8aa3b, v43
	v_mul_f32_e32 v36, 0x3fb8aa3b, v36
	v_mul_f32_e32 v37, 0x3fb8aa3b, v37
	v_mul_f32_e32 v38, 0x3fb8aa3b, v38
	v_mul_f32_e32 v39, 0x3fb8aa3b, v39
	v_mul_f32_e32 v32, 0x3fb8aa3b, v32
	v_mul_f32_e32 v33, 0x3fb8aa3b, v33
	v_mul_f32_e32 v34, 0x3fb8aa3b, v34
	v_mul_f32_e32 v35, 0x3fb8aa3b, v35
	v_mul_f32_e32 v28, 0x3fb8aa3b, v28
	v_mul_f32_e32 v29, 0x3fb8aa3b, v29
	v_mul_f32_e32 v30, 0x3fb8aa3b, v30
	v_mul_f32_e32 v31, 0x3fb8aa3b, v31
	v_mul_f32_e32 v24, 0x3fb8aa3b, v24
	v_mul_f32_e32 v25, 0x3fb8aa3b, v25
	v_mul_f32_e32 v26, 0x3fb8aa3b, v26
	v_mul_f32_e32 v27, 0x3fb8aa3b, v27
	v_mul_f32_e32 v20, 0x3fb8aa3b, v20
	v_mul_f32_e32 v21, 0x3fb8aa3b, v21
	v_mul_f32_e32 v22, 0x3fb8aa3b, v22
	v_mul_f32_e32 v23, 0x3fb8aa3b, v23
	v_mul_f32_e32 v16, 0x3fb8aa3b, v16
	v_mul_f32_e32 v17, 0x3fb8aa3b, v17
	v_mul_f32_e32 v18, 0x3fb8aa3b, v18
	v_mul_f32_e32 v19, 0x3fb8aa3b, v19
	v_mul_f32_e32 v12, 0x3fb8aa3b, v12
	v_mul_f32_e32 v13, 0x3fb8aa3b, v13
	v_mul_f32_e32 v14, 0x3fb8aa3b, v14
	v_mul_f32_e32 v15, 0x3fb8aa3b, v15
	v_mul_f32_e32 v8, 0x3fb8aa3b, v8
	v_mul_f32_e32 v9, 0x3fb8aa3b, v9
	v_mul_f32_e32 v10, 0x3fb8aa3b, v10
	v_mul_f32_e32 v11, 0x3fb8aa3b, v11
	v_mul_f32_e32 v4, 0x3fb8aa3b, v4
	v_mul_f32_e32 v5, 0x3fb8aa3b, v5
	v_mul_f32_e32 v6, 0x3fb8aa3b, v6
	v_mul_f32_e32 v7, 0x3fb8aa3b, v7
	v_mul_f32_e32 v1, 0x3fb8aa3b, v1
	v_mul_f32_e32 v2, 0x3fb8aa3b, v2
	v_mul_f32_e32 v3, 0x3fb8aa3b, v3
	v_exp_f32_e32 v76, v40
	v_add_f32_e32 v65, v72, v65
	v_exp_f32_e32 v77, v41
	v_exp_f32_e32 v78, v42
	v_exp_f32_e32 v79, v43
	v_exp_f32_e32 v90, v36
	v_exp_f32_e32 v91, v37
	v_exp_f32_e32 v101, v38
	v_exp_f32_e32 v102, v39
	v_exp_f32_e32 v103, v32
	v_exp_f32_e32 v104, v33
	v_exp_f32_e32 v105, v34
	v_exp_f32_e32 v106, v35
	v_exp_f32_e32 v107, v28
	v_exp_f32_e32 v108, v29
	v_exp_f32_e32 v109, v30
	v_exp_f32_e32 v110, v31
	v_exp_f32_e32 v111, v24
	v_exp_f32_e32 v112, v25
	v_exp_f32_e32 v113, v26
	v_exp_f32_e32 v114, v27
	v_exp_f32_e32 v115, v20
	v_exp_f32_e32 v116, v21
	v_exp_f32_e32 v117, v22
	v_exp_f32_e32 v118, v23
	v_exp_f32_e32 v119, v16
	v_exp_f32_e32 v120, v17
	v_exp_f32_e32 v121, v18
	v_exp_f32_e32 v122, v19
	v_exp_f32_e32 v123, v12
	v_exp_f32_e32 v124, v13
	v_exp_f32_e32 v125, v14
	v_exp_f32_e32 v126, v15
	v_exp_f32_e32 v127, v8
	v_exp_f32_e32 v128, v9
	v_exp_f32_e32 v129, v10
; #define LAS __attribute__((address_space(3)))
; __device__ __forceinline__ bf16x8 pack8(const float (&o)[8]) { v4u w; w.x = pk2(o[0], o[1]); w.y = pk2(o[2], o[3]); w.z = pk2(o[4], o[5]); w.w = pk2(o[6], o[7]); return __builtin_bit_cast(bf16x8, w); }
; __device__ __forceinline__ v2u vtr(const LAS bf16* p) { return __builtin_bit_cast(v2u, __builtin_amdgcn_ds_read_tr16_b64_v4i16((LAS v4i16_t*)p)); }
; template <bool SAMPLE>
; __device__ __forceinline__ void mem_unit(const Params& p, int l, LAS unsigned char* lds, int unit, int tid, int wave, int lane) {
;     ...
;                 for (int e = 0; e < 4; ++e) { const float pe = __expf(S[cc][tt][e] - mx); S[cc][tt][e] = pe; den += pe; }
;         den += __shfl_xor(den, 16); den += __shfl_xor(den, 32);
;         const float rden = 1.f / den;
;         bf16x8 pf[8];
; #pragma unroll
;         for (int cc = 0; cc < 8; ++cc) { float t8[8];
; #pragma unroll
;             for (int e = 0; e < 4; ++e) { t8[e] = S[cc][0][e]; t8[4 + e] = S[cc][1][e]; }
;             pf[cc] = pack8(t8); }
; #pragma unroll
;         for (int dt = 0; dt < 8; ++dt) { f32x4 o = (f32x4){0.f, 0.f, 0.f, 0.f};
; #pragma unroll
;             for (int cc = 0; cc < 8; ++cc) { const LAS bf16* vp = Vt + (32 * cc + 4 * kq + (q16 >> 2)) * MEM_VS + 16 * dt + 4 * (q16 & 3);
;                 const v2u lo = vtr(vp), hi = vtr(vp + 16 * MEM_VS);
;                 v4u av; av.x = lo.x; av.y = lo.y; av.z = hi.x; av.w = hi.y;
;                 o = __builtin_amdgcn_mfma_f32_16x16x32_bf16(__builtin_bit_cast(bf16x8, av), pf[cc], o, 0, 0, 0); }
	v_exp_f32_e32 v130, v11
	v_exp_f32_e32 v131, v4
	v_exp_f32_e32 v132, v5
	v_exp_f32_e32 v133, v6
	v_exp_f32_e32 v134, v7
	v_exp_f32_e32 v135, v56
	v_exp_f32_e32 v136, v57
	v_exp_f32_e32 v137, v58
	v_exp_f32_e32 v138, v59
	v_exp_f32_e32 v139, v60
	v_exp_f32_e32 v140, v61
	v_exp_f32_e32 v141, v62
	v_exp_f32_e32 v142, v63
	v_exp_f32_e32 v144, v1
	v_exp_f32_e32 v145, v2
	v_exp_f32_e32 v146, v3
	v_cvt_pk_bf16_f32 v1, v66, v67
	v_cvt_pk_bf16_f32 v2, v68, v69
	v_cvt_pk_bf16_f32 v3, v70, v71
	v_cvt_pk_bf16_f32 v4, v72, v73
	v_cvt_pk_bf16_f32 v5, v74, v75
	v_cvt_pk_bf16_f32 v6, v76, v77
	v_cvt_pk_bf16_f32 v7, v78, v79
	v_cvt_pk_bf16_f32 v8, v90, v91
	v_cvt_pk_bf16_f32 v9, v101, v102
	v_cvt_pk_bf16_f32 v10, v103, v104
	v_cvt_pk_bf16_f32 v11, v105, v106
	v_cvt_pk_bf16_f32 v12, v107, v108
	v_cvt_pk_bf16_f32 v13, v109, v110
	v_cvt_pk_bf16_f32 v14, v111, v112
	v_cvt_pk_bf16_f32 v15, v113, v114
	v_cvt_pk_bf16_f32 v16, v115, v116
	v_cvt_pk_bf16_f32 v17, v117, v118
	v_cvt_pk_bf16_f32 v18, v119, v120
	v_cvt_pk_bf16_f32 v19, v121, v122
	v_cvt_pk_bf16_f32 v24, v123, v124
	v_cvt_pk_bf16_f32 v25, v125, v126
	v_cvt_pk_bf16_f32 v26, v127, v128
	v_cvt_pk_bf16_f32 v27, v129, v130
	v_cvt_pk_bf16_f32 v28, v131, v132
	v_cvt_pk_bf16_f32 v29, v133, v134
	v_cvt_pk_bf16_f32 v30, v135, v136
	v_cvt_pk_bf16_f32 v31, v137, v138
	v_cvt_pk_bf16_f32 v20, v139, v140
	v_cvt_pk_bf16_f32 v21, v141, v142
	v_cvt_pk_bf16_f32 v22, v143, v144
	v_cvt_pk_bf16_f32 v23, v145, v146
	s_nop 7
	s_nop 1
	ds_read_b64_tr_b16 v[52:53], v64 offset:43520
	ds_read_b64_tr_b16 v[54:55], v64 offset:47872
	ds_read_b64_tr_b16 v[56:57], v64 offset:52224
	ds_read_b64_tr_b16 v[58:59], v64 offset:56576
	ds_read_b64_tr_b16 v[60:61], v64 offset:60928
	ds_read_b64_tr_b16 v[62:63], v64 offset:65280
	v_add_f32_e32 v65, v73, v65
	s_nop 0
	v_mfma_f32_16x16x32_bf16 v[32:35], v[198:201], v[0:3], 0
	v_add_f32_e32 v65, v74, v65
	v_add_f32_e32 v65, v75, v65
	v_add_f32_e32 v65, v76, v65
	v_add_f32_e32 v65, v77, v65
	s_nop 0
	v_mfma_f32_16x16x32_bf16 v[32:35], v[202:205], v[4:7], v[32:35]
	v_add_f32_e32 v36, v78, v65
	v_add_f32_e32 v36, v79, v36
	v_add_f32_e32 v36, v90, v36
	v_add_f32_e32 v36, v91, v36
	s_nop 0
	v_mfma_f32_16x16x32_bf16 v[32:35], v[206:209], v[8:11], v[32:35]
	v_add_f32_e32 v36, v101, v36
	v_add_f32_e32 v36, v102, v36
	v_add_f32_e32 v36, v103, v36
	v_add_f32_e32 v36, v104, v36
	s_nop 0
	v_mfma_f32_16x16x32_bf16 v[32:35], v[210:213], v[12:15], v[32:35]
	v_add_f32_e32 v36, v105, v36
	v_add_f32_e32 v36, v106, v36
	v_add_f32_e32 v36, v107, v36
	v_add_f32_e32 v36, v108, v36
	s_nop 0
	ds_read_b64_tr_b16 v[186:187], v64 offset:52256
	ds_read_b64_tr_b16 v[188:189], v64 offset:56608
	ds_read_b64_tr_b16 v[190:191], v64 offset:60960
	ds_read_b64_tr_b16 v[192:193], v64 offset:65312
	ds_read_b64_tr_b16 v[194:195], v64 offset:64
	ds_read_b64_tr_b16 v[196:197], v64 offset:4416
	ds_read_b64_tr_b16 v[198:199], v64 offset:8768
	ds_read_b64_tr_b16 v[200:201], v64 offset:13120
	ds_read_b64_tr_b16 v[202:203], v64 offset:17472
	ds_read_b64_tr_b16 v[204:205], v64 offset:21824
	ds_read_b64_tr_b16 v[206:207], v64 offset:26176
	ds_read_b64_tr_b16 v[208:209], v64 offset:30528
	ds_read_b64_tr_b16 v[210:211], v64 offset:34880
	ds_read_b64_tr_b16 v[212:213], v64 offset:39232
	v_mfma_f32_16x16x32_bf16 v[32:35], v[218:221], v[16:19], v[32:35]
	v_add_f32_e32 v36, v109, v36
	v_add_f32_e32 v36, v110, v36
	v_add_f32_e32 v36, v111, v36
	v_add_f32_e32 v36, v112, v36
	s_waitcnt lgkmcnt(15)
	v_mfma_f32_16x16x32_bf16 v[32:35], v[52:55], v[24:27], v[32:35]
	v_add_f32_e32 v36, v113, v36
	v_add_f32_e32 v36, v114, v36
	v_add_f32_e32 v36, v115, v36
	v_add_f32_e32 v36, v116, v36
	s_waitcnt lgkmcnt(15)
	v_mfma_f32_16x16x32_bf16 v[32:35], v[56:59], v[28:31], v[32:35]
	v_add_f32_e32 v36, v117, v36
	v_add_f32_e32 v36, v118, v36
	v_add_f32_e32 v36, v119, v36
	v_add_f32_e32 v40, v120, v36
	s_waitcnt lgkmcnt(14)
	v_mfma_f32_16x16x32_bf16 v[36:39], v[60:63], v[20:23], v[32:35]
	s_nop 2
	v_add_f32_e32 v32, v121, v40
	v_add_f32_e32 v32, v122, v32
	v_add_f32_e32 v32, v123, v32
	v_add_f32_e32 v32, v124, v32
	v_add_f32_e32 v32, v125, v32
	v_add_f32_e32 v32, v126, v32
	v_add_f32_e32 v32, v127, v32
	v_add_f32_e32 v32, v128, v32
	v_add_f32_e32 v32, v129, v32
	v_add_f32_e32 v32, v130, v32
	v_add_f32_e32 v32, v131, v32
	v_add_f32_e32 v32, v132, v32
	v_add_f32_e32 v32, v133, v32
	v_add_f32_e32 v32, v134, v32
	v_add_f32_e32 v32, v135, v32
	v_add_f32_e32 v32, v136, v32
	v_add_f32_e32 v32, v137, v32
	v_add_f32_e32 v32, v138, v32
	v_add_f32_e32 v32, v139, v32
	v_add_f32_e32 v32, v140, v32
	v_add_f32_e32 v32, v141, v32
	v_add_f32_e32 v32, v142, v32
	v_add_f32_e32 v32, v143, v32
	v_add_f32_e32 v32, v144, v32
	v_add_f32_e32 v32, v145, v32
	v_add_f32_e32 v32, v146, v32
	ds_bpermute_b32 v33, v82, v32
	s_waitcnt lgkmcnt(0)
	v_add_f32_e32 v32, v32, v33
	ds_bpermute_b32 v33, v100, v32
	s_waitcnt lgkmcnt(0)
; #define LAS __attribute__((address_space(3)))
; __device__ __forceinline__ unsigned pk2(float lo, float hi) { return pg8::cvt_pk_bf16(lo, hi); }
; __device__ __forceinline__ bf16x8 pack8(const float (&o)[8]) { v4u w; w.x = pk2(o[0], o[1]); w.y = pk2(o[2], o[3]); w.z = pk2(o[4], o[5]); w.w = pk2(o[6], o[7]); return __builtin_bit_cast(bf16x8, w); }
; __device__ __forceinline__ v2u vtr(const LAS bf16* p) { return __builtin_bit_cast(v2u, __builtin_amdgcn_ds_read_tr16_b64_v4i16((LAS v4i16_t*)p)); }
; template <bool SAMPLE>
; __device__ __forceinline__ void mem_unit(const Params& p, int l, LAS unsigned char* lds, int unit, int tid, int wave, int lane) {
;     ...
;         den += __shfl_xor(den, 16); den += __shfl_xor(den, 32);
;         const float rden = 1.f / den;
;         bf16x8 pf[8];
; #pragma unroll
;         for (int cc = 0; cc < 8; ++cc) { float t8[8];
; #pragma unroll
;             for (int e = 0; e < 4; ++e) { t8[e] = S[cc][0][e]; t8[4 + e] = S[cc][1][e]; }
;             pf[cc] = pack8(t8); }
; #pragma unroll
;         for (int dt = 0; dt < 8; ++dt) { f32x4 o = (f32x4){0.f, 0.f, 0.f, 0.f};
; #pragma unroll
;             for (int cc = 0; cc < 8; ++cc) { const LAS bf16* vp = Vt + (32 * cc + 4 * kq + (q16 >> 2)) * MEM_VS + 16 * dt + 4 * (q16 & 3);
;                 const v2u lo = vtr(vp), hi = vtr(vp + 16 * MEM_VS);
;                 v4u av; av.x = lo.x; av.y = lo.y; av.z = hi.x; av.w = hi.y;
;                 o = __builtin_amdgcn_mfma_f32_16x16x32_bf16(__builtin_bit_cast(bf16x8, av), pf[cc], o, 0, 0, 0); }
;             if (st) { v2u w; w.x = pk2(o[0] * rden, o[1] * rden); w.y = pk2(o[2] * rden, o[3] * rden);
;                 *(v2u*)(MO + row * 512 + h * 128 + 16 * dt + 4 * kq) = w; } }
	v_add_f32_e32 v32, v32, v33
	v_div_scale_f32 v33, s[16:17], v32, v32, 1.0
	v_rcp_f32_e32 v35, v33
	v_div_scale_f32 v34, vcc, 1.0, v32, 1.0
	v_fma_f32 v40, -v33, v35, 1.0
	v_fmac_f32_e32 v35, v40, v35
	v_mul_f32_e32 v40, v34, v35
	v_fma_f32 v41, -v33, v40, v34
	v_fmac_f32_e32 v40, v41, v35
	v_fma_f32 v33, -v33, v40, v34
	v_div_fmas_f32 v33, v33, v35, v40
	v_div_fixup_f32 v34, v33, v32, 1.0
	v_mul_f32_e32 v32, v36, v34
	v_mul_f32_e32 v36, v39, v34
	v_mul_f32_e32 v33, v37, v34
	v_mul_f32_e32 v35, v38, v34
	v_cvt_pk_bf16_f32 v52, v32, v33
	v_cvt_pk_bf16_f32 v53, v35, v36
	s_nop 5
	v_mfma_f32_16x16x32_bf16 v[36:39], v[222:225], v[0:3], 0
	s_nop 1
	v_lshl_add_u64 v[32:33], s[2:3], 0, v[88:89]
	v_lshl_add_u64 v[32:33], v[92:93], 1, v[32:33]
	s_nop 0
	v_mfma_f32_16x16x32_bf16 v[36:39], v[226:229], v[4:7], v[36:39]
	s_nop 2
	v_mfma_f32_16x16x32_bf16 v[36:39], v[230:233], v[8:11], v[36:39]
	s_nop 2
	v_mfma_f32_16x16x32_bf16 v[36:39], v[234:237], v[12:15], v[36:39]
	s_nop 2
	v_mfma_f32_16x16x32_bf16 v[36:39], v[242:245], v[16:19], v[36:39]
	s_nop 2
	global_store_dwordx2 v[32:33], v[52:53], off
	s_nop 0
	v_mfma_f32_16x16x32_bf16 v[36:39], v[246:249], v[24:27], v[36:39]
	s_nop 0
	ds_read_b64_tr_b16 v[218:219], v64 offset:43584
	ds_read_b64_tr_b16 v[220:221], v64 offset:47936
	ds_read_b64_tr_b16 v[222:223], v64 offset:52288
	ds_read_b64_tr_b16 v[224:225], v64 offset:56640
	ds_read_b64_tr_b16 v[226:227], v64 offset:60992
	ds_read_b64_tr_b16 v[228:229], v64 offset:65344
	ds_read_b64_tr_b16 v[230:231], v64 offset:96
	ds_read_b64_tr_b16 v[232:233], v64 offset:4448
	ds_read_b64_tr_b16 v[234:235], v64 offset:8800
	ds_read_b64_tr_b16 v[236:237], v64 offset:13152
	ds_read_b64_tr_b16 v[242:243], v64 offset:17504
	ds_read_b64_tr_b16 v[244:245], v64 offset:21856
	ds_read_b64_tr_b16 v[246:247], v64 offset:26208
	ds_read_b64_tr_b16 v[248:249], v64 offset:30560
	v_mfma_f32_16x16x32_bf16 v[36:39], v[186:189], v[28:31], v[36:39]
	s_nop 0
	v_mfma_f32_16x16x32_bf16 v[36:39], v[190:193], v[20:23], v[36:39]
	s_nop 7
	v_mul_f32_e32 v35, v34, v36
	v_mul_f32_e32 v36, v34, v37
	v_mul_f32_e32 v37, v34, v38
	v_mul_f32_e32 v38, v34, v39
	v_cvt_pk_bf16_f32 v52, v35, v36
	v_cvt_pk_bf16_f32 v53, v37, v38
	s_nop 5
	v_mfma_f32_16x16x32_bf16 v[36:39], v[194:197], v[0:3], 0
	s_nop 2
	v_mfma_f32_16x16x32_bf16 v[36:39], v[198:201], v[4:7], v[36:39]
	s_nop 2
	v_mfma_f32_16x16x32_bf16 v[36:39], v[202:205], v[8:11], v[36:39]
	s_nop 2
	v_mfma_f32_16x16x32_bf16 v[36:39], v[206:209], v[12:15], v[36:39]
	s_nop 2
	v_mfma_f32_16x16x32_bf16 v[36:39], v[210:213], v[16:19], v[36:39]
	s_nop 2
	global_store_dwordx2 v[32:33], v[52:53], off offset:32
	s_waitcnt lgkmcnt(12)
	ds_read_b64_tr_b16 v[186:187], v64 offset:34912
	ds_read_b64_tr_b16 v[188:189], v64 offset:39264
	ds_read_b64_tr_b16 v[190:191], v64 offset:43616
	ds_read_b64_tr_b16 v[192:193], v64 offset:47968
	ds_read_b64_tr_b16 v[194:195], v64 offset:52320
	ds_read_b64_tr_b16 v[196:197], v64 offset:56672
	ds_read_b64_tr_b16 v[198:199], v64 offset:61024
	ds_read_b64_tr_b16 v[200:201], v64 offset:65376
	ds_read_b64_tr_b16 v[202:203], v64 offset:128
	ds_read_b64_tr_b16 v[204:205], v64 offset:4480
	ds_read_b64_tr_b16 v[206:207], v64 offset:8832
	ds_read_b64_tr_b16 v[208:209], v64 offset:13184
	ds_read_b64_tr_b16 v[210:211], v64 offset:17536
	ds_read_b64_tr_b16 v[212:213], v64 offset:21888
	v_mfma_f32_16x16x32_bf16 v[36:39], v[218:221], v[24:27], v[36:39]
	s_waitcnt lgkmcnt(15)
	v_mfma_f32_16x16x32_bf16 v[36:39], v[222:225], v[28:31], v[36:39]
	s_waitcnt lgkmcnt(15)
	v_mfma_f32_16x16x32_bf16 v[36:39], v[226:229], v[20:23], v[36:39]
	s_nop 7
	v_mul_f32_e32 v35, v34, v36
	v_mul_f32_e32 v36, v34, v37
	v_mul_f32_e32 v37, v34, v38
	v_mul_f32_e32 v38, v34, v39
	v_cvt_pk_bf16_f32 v52, v35, v36
	v_cvt_pk_bf16_f32 v53, v37, v38
	s_nop 4
	s_waitcnt lgkmcnt(15)
	v_mfma_f32_16x16x32_bf16 v[36:39], v[230:233], v[0:3], 0
	s_nop 1
	s_waitcnt lgkmcnt(15)
	v_mfma_f32_16x16x32_bf16 v[36:39], v[234:237], v[4:7], v[36:39]
	s_nop 1
	s_waitcnt lgkmcnt(15)
	v_mfma_f32_16x16x32_bf16 v[36:39], v[242:245], v[8:11], v[36:39]
	s_nop 1
	s_waitcnt lgkmcnt(14)
	v_mfma_f32_16x16x32_bf16 v[36:39], v[246:249], v[12:15], v[36:39]
	s_nop 1
	s_waitcnt lgkmcnt(12)
	ds_read_b64_tr_b16 v[218:219], v64 offset:26240
	ds_read_b64_tr_b16 v[220:221], v64 offset:30592
	ds_read_b64_tr_b16 v[222:223], v64 offset:34944
	ds_read_b64_tr_b16 v[224:225], v64 offset:39296
	ds_read_b64_tr_b16 v[226:227], v64 offset:43648
	ds_read_b64_tr_b16 v[228:229], v64 offset:48000
	ds_read_b64_tr_b16 v[230:231], v64 offset:52352
	ds_read_b64_tr_b16 v[232:233], v64 offset:56704
	ds_read_b64_tr_b16 v[234:235], v64 offset:61056
	ds_read_b64_tr_b16 v[236:237], v64 offset:65408
	ds_read_b64_tr_b16 v[242:243], v64 offset:160
	ds_read_b64_tr_b16 v[244:245], v64 offset:4512
	ds_read_b64_tr_b16 v[246:247], v64 offset:8864
	ds_read_b64_tr_b16 v[248:249], v64 offset:13216
	v_mfma_f32_16x16x32_bf16 v[36:39], v[186:189], v[16:19], v[36:39]
	s_nop 2
	global_store_dwordx2 v[32:33], v[52:53], off offset:64
	s_waitcnt lgkmcnt(15)
	v_mfma_f32_16x16x32_bf16 v[36:39], v[190:193], v[24:27], v[36:39]
	s_waitcnt lgkmcnt(15)
	v_mfma_f32_16x16x32_bf16 v[36:39], v[194:197], v[28:31], v[36:39]
	s_waitcnt lgkmcnt(15)
	v_mfma_f32_16x16x32_bf16 v[36:39], v[198:201], v[20:23], v[36:39]
	s_nop 7
	v_mul_f32_e32 v35, v34, v36
	v_mul_f32_e32 v36, v34, v37
	v_mul_f32_e32 v37, v34, v38
	v_mul_f32_e32 v38, v34, v39
	v_cvt_pk_bf16_f32 v52, v35, v36
	v_cvt_pk_bf16_f32 v53, v37, v38
	s_nop 4
	s_waitcnt lgkmcnt(15)
	v_mfma_f32_16x16x32_bf16 v[36:39], v[202:205], v[0:3], 0
	s_nop 1
	s_waitcnt lgkmcnt(15)
	v_mfma_f32_16x16x32_bf16 v[36:39], v[206:209], v[4:7], v[36:39]
	s_nop 1
	s_waitcnt lgkmcnt(14)
; #define LAS __attribute__((address_space(3)))
; __device__ __forceinline__ unsigned pk2(float lo, float hi) { return pg8::cvt_pk_bf16(lo, hi); }
; __device__ __forceinline__ v2u vtr(const LAS bf16* p) { return __builtin_bit_cast(v2u, __builtin_amdgcn_ds_read_tr16_b64_v4i16((LAS v4i16_t*)p)); }
; template <bool SAMPLE>
; __device__ __forceinline__ void mem_unit(const Params& p, int l, LAS unsigned char* lds, int unit, int tid, int wave, int lane) {
;     ...
; #pragma unroll
;         for (int dt = 0; dt < 8; ++dt) { f32x4 o = (f32x4){0.f, 0.f, 0.f, 0.f};
; #pragma unroll
;             for (int cc = 0; cc < 8; ++cc) { const LAS bf16* vp = Vt + (32 * cc + 4 * kq + (q16 >> 2)) * MEM_VS + 16 * dt + 4 * (q16 & 3);
;                 const v2u lo = vtr(vp), hi = vtr(vp + 16 * MEM_VS);
;                 v4u av; av.x = lo.x; av.y = lo.y; av.z = hi.x; av.w = hi.y;
;                 o = __builtin_amdgcn_mfma_f32_16x16x32_bf16(__builtin_bit_cast(bf16x8, av), pf[cc], o, 0, 0, 0); }
;             if (st) { v2u w; w.x = pk2(o[0] * rden, o[1] * rden); w.y = pk2(o[2] * rden, o[3] * rden);
;                 *(v2u*)(MO + row * 512 + h * 128 + 16 * dt + 4 * kq) = w; } }
	v_mfma_f32_16x16x32_bf16 v[36:39], v[210:213], v[8:11], v[36:39]
	s_nop 1
	s_waitcnt lgkmcnt(12)
	ds_read_b64_tr_b16 v[186:187], v64 offset:17568
	ds_read_b64_tr_b16 v[188:189], v64 offset:21920
	ds_read_b64_tr_b16 v[190:191], v64 offset:26272
	ds_read_b64_tr_b16 v[192:193], v64 offset:30624
	ds_read_b64_tr_b16 v[194:195], v64 offset:34976
	ds_read_b64_tr_b16 v[196:197], v64 offset:39328
	ds_read_b64_tr_b16 v[198:199], v64 offset:43680
	ds_read_b64_tr_b16 v[200:201], v64 offset:48032
	ds_read_b64_tr_b16 v[202:203], v64 offset:52384
	ds_read_b64_tr_b16 v[204:205], v64 offset:56736
	ds_read_b64_tr_b16 v[206:207], v64 offset:61088
	ds_read_b64_tr_b16 v[208:209], v64 offset:65440
	ds_read_b64_tr_b16 v[210:211], v64 offset:192
	ds_read_b64_tr_b16 v[212:213], v64 offset:4544
	v_mfma_f32_16x16x32_bf16 v[36:39], v[218:221], v[12:15], v[36:39]
	s_nop 1
	s_waitcnt lgkmcnt(15)
	v_mfma_f32_16x16x32_bf16 v[36:39], v[222:225], v[16:19], v[36:39]
	s_nop 2
	global_store_dwordx2 v[32:33], v[52:53], off offset:96
	s_waitcnt lgkmcnt(15)
	v_mfma_f32_16x16x32_bf16 v[36:39], v[226:229], v[24:27], v[36:39]
	s_waitcnt lgkmcnt(15)
	v_mfma_f32_16x16x32_bf16 v[36:39], v[230:233], v[28:31], v[36:39]
	s_waitcnt lgkmcnt(15)
	v_mfma_f32_16x16x32_bf16 v[36:39], v[234:237], v[20:23], v[36:39]
	s_nop 7
	v_mul_f32_e32 v35, v34, v36
	v_mul_f32_e32 v36, v34, v37
	v_mul_f32_e32 v37, v34, v38
	v_mul_f32_e32 v38, v34, v39
	v_cvt_pk_bf16_f32 v52, v35, v36
	v_cvt_pk_bf16_f32 v53, v37, v38
	s_nop 4
	s_waitcnt lgkmcnt(15)
	v_mfma_f32_16x16x32_bf16 v[36:39], v[242:245], v[0:3], 0
	s_nop 1
	s_waitcnt lgkmcnt(14)
	v_mfma_f32_16x16x32_bf16 v[36:39], v[246:249], v[4:7], v[36:39]
	s_nop 1
	s_waitcnt lgkmcnt(12)
	ds_read_b64_tr_b16 v[218:219], v64 offset:8896
	ds_read_b64_tr_b16 v[220:221], v64 offset:13248
	ds_read_b64_tr_b16 v[222:223], v64 offset:17600
	ds_read_b64_tr_b16 v[224:225], v64 offset:21952
	ds_read_b64_tr_b16 v[226:227], v64 offset:26304
	ds_read_b64_tr_b16 v[228:229], v64 offset:30656
	ds_read_b64_tr_b16 v[230:231], v64 offset:35008
	ds_read_b64_tr_b16 v[232:233], v64 offset:39360
	ds_read_b64_tr_b16 v[234:235], v64 offset:43712
	ds_read_b64_tr_b16 v[236:237], v64 offset:48064
	ds_read_b64_tr_b16 v[242:243], v64 offset:61120
	ds_read_b64_tr_b16 v[244:245], v64 offset:65472
	ds_read_b64_tr_b16 v[246:247], v64 offset:224
	ds_read_b64_tr_b16 v[248:249], v64 offset:4576
	v_mfma_f32_16x16x32_bf16 v[36:39], v[186:189], v[8:11], v[36:39]
	s_nop 1
	s_waitcnt lgkmcnt(15)
	v_mfma_f32_16x16x32_bf16 v[36:39], v[190:193], v[12:15], v[36:39]
	s_nop 1
	s_waitcnt lgkmcnt(15)
	v_mfma_f32_16x16x32_bf16 v[36:39], v[194:197], v[16:19], v[36:39]
	s_nop 2
	global_store_dwordx2 v[32:33], v[52:53], off offset:128
	s_waitcnt lgkmcnt(15)
	v_mfma_f32_16x16x32_bf16 v[36:39], v[198:201], v[24:27], v[36:39]
	s_waitcnt lgkmcnt(15)
	v_mfma_f32_16x16x32_bf16 v[36:39], v[202:205], v[28:31], v[36:39]
	s_waitcnt lgkmcnt(15)
	v_mfma_f32_16x16x32_bf16 v[36:39], v[206:209], v[20:23], v[36:39]
	s_nop 7
	v_mul_f32_e32 v35, v34, v36
	v_mul_f32_e32 v36, v34, v37
	v_mul_f32_e32 v37, v34, v38
	v_mul_f32_e32 v38, v34, v39
	v_cvt_pk_bf16_f32 v52, v35, v36
	v_cvt_pk_bf16_f32 v53, v37, v38
	s_nop 4
	s_waitcnt lgkmcnt(14)
	v_mfma_f32_16x16x32_bf16 v[36:39], v[210:213], v[0:3], 0
	s_nop 1
	s_waitcnt lgkmcnt(12)
	ds_read_b64_tr_b16 v[186:187], v64 offset:35040
	ds_read_b64_tr_b16 v[188:189], v64 offset:39392
	v_mfma_f32_16x16x32_bf16 v[36:39], v[218:221], v[4:7], v[36:39]
	s_nop 1
	s_waitcnt lgkmcnt(12)
	v_mfma_f32_16x16x32_bf16 v[36:39], v[222:225], v[8:11], v[36:39]
	s_nop 1
	s_waitcnt lgkmcnt(10)
	v_mfma_f32_16x16x32_bf16 v[36:39], v[226:229], v[12:15], v[36:39]
	s_nop 0
	ds_read_b64_tr_b16 v[48:49], v64 offset:52416
	s_waitcnt lgkmcnt(9)
	v_mfma_f32_16x16x32_bf16 v[36:39], v[230:233], v[16:19], v[36:39]
	ds_read_b64_tr_b16 v[50:51], v64 offset:56768
	s_nop 1
	global_store_dwordx2 v[32:33], v[52:53], off offset:160
	s_waitcnt lgkmcnt(8)
	v_mfma_f32_16x16x32_bf16 v[36:39], v[234:237], v[24:27], v[36:39]
	s_waitcnt lgkmcnt(0)
	v_mfma_f32_16x16x32_bf16 v[36:39], v[48:51], v[28:31], v[36:39]
	s_nop 0
	v_mfma_f32_16x16x32_bf16 v[36:39], v[242:245], v[20:23], v[36:39]
	s_nop 7
	v_mul_f32_e32 v35, v34, v36
	v_mul_f32_e32 v36, v34, v37
	v_mul_f32_e32 v37, v34, v38
	v_mul_f32_e32 v38, v34, v39
	v_cvt_pk_bf16_f32 v48, v35, v36
	v_cvt_pk_bf16_f32 v49, v37, v38
	s_nop 1
	ds_read_b64_tr_b16 v[40:41], v64 offset:8928
	ds_read_b64_tr_b16 v[42:43], v64 offset:13280
	ds_read_b64_tr_b16 v[44:45], v64 offset:17632
	s_nop 0
	v_mfma_f32_16x16x32_bf16 v[0:3], v[246:249], v[0:3], 0
	ds_read_b64_tr_b16 v[46:47], v64 offset:21984
	ds_read_b64_tr_b16 v[36:37], v64 offset:26336
	s_waitcnt lgkmcnt(3)
	v_mfma_f32_16x16x32_bf16 v[0:3], v[40:43], v[4:7], v[0:3]
	ds_read_b64_tr_b16 v[38:39], v64 offset:30688
	s_nop 0
	s_waitcnt lgkmcnt(2)
	v_mfma_f32_16x16x32_bf16 v[0:3], v[44:47], v[8:11], v[0:3]
	s_nop 0
	ds_read_b64_tr_b16 v[8:9], v64 offset:43744
	s_waitcnt lgkmcnt(1)
	v_mfma_f32_16x16x32_bf16 v[0:3], v[36:39], v[12:15], v[0:3]
	ds_read_b64_tr_b16 v[10:11], v64 offset:48096
	ds_read_b64_tr_b16 v[12:13], v64 offset:52448
	s_nop 0
	v_mfma_f32_16x16x32_bf16 v[0:3], v[186:189], v[16:19], v[0:3]
	ds_read_b64_tr_b16 v[14:15], v64 offset:56800
	ds_read_b64_tr_b16 v[4:5], v64 offset:61152
	ds_read_b64_tr_b16 v[6:7], v64 offset:65504
	global_store_dwordx2 v[32:33], v[48:49], off offset:192
	s_waitcnt lgkmcnt(4)
	v_mfma_f32_16x16x32_bf16 v[0:3], v[8:11], v[24:27], v[0:3]
	s_waitcnt lgkmcnt(2)
	v_mfma_f32_16x16x32_bf16 v[0:3], v[12:15], v[28:31], v[0:3]
	s_waitcnt lgkmcnt(0)
	v_mfma_f32_16x16x32_bf16 v[0:3], v[4:7], v[20:23], v[0:3]
	s_nop 7
	v_mul_f32_e32 v0, v34, v0
	v_mul_f32_e32 v1, v34, v1
	v_mul_f32_e32 v2, v34, v2
	v_mul_f32_e32 v3, v34, v3
	v_cvt_pk_bf16_f32 v0, v0, v1
	v_cvt_pk_bf16_f32 v1, v2, v3
	global_store_dwordx2 v[32:33], v[0:1], off offset:224
	s_cbranch_scc1 .LBB0_631
	s_barrier
	s_branch .LBB0_596

; template <bool SAMPLE>
; __device__ __forceinline__ void swa_unit(const Params& p, LAS unsigned char* lds, int unit, int tid, int wave, int lane) {
;     ...
;                     const int rel = (kb >> 4) - wave;
;                     const bool full = !SAMPLE && rel >= 1 && rel <= 7 && (nb > 0 || kb >= 128);
;                     if (!full) {
; #pragma unroll
;                         for (int e = 0; e < 4; ++e) { const int s = kb + 4 * kq + e; const bool ok = (s > i) && (s <= i + 128) && (SAMPLE || nb > 0 || s >= 128);
;                             a[e] = ok ? a[e] : -INFINITY; } }
; #pragma unroll
;                     for (int e = 0; e < 4; ++e) mx = fmaxf(mx, a[e]);
;                     S[cc][tt] = a; }
;             mx = fmaxf(mx, __shfl_xor(mx, 16)); mx = fmaxf(mx, __shfl_xor(mx, 32));
;             float den = 0.f;
; #pragma unroll
;             for (int cc = 0; cc < 5; ++cc)
; #pragma unroll
;                 for (int tt = 0; tt < 2; ++tt)
; #pragma unroll
;                     for (int e = 0; e < 4; ++e) { const float pe = __expf(S[cc][tt][e] - mx); S[cc][tt][e] = pe; den += pe; }
;             den += __shfl_xor(den, 16); den += __shfl_xor(den, 32);
;             den += __expf(sink - mx);
.LBB0_2087:
	v_add_u32_e32 v44, s53, v74
	v_cmp_gt_i32_e32 vcc, v44, v72
	v_cmp_le_i32_e64 s[0:1], v44, v96
	s_and_b64 s[0:1], vcc, s[0:1]
	v_cmp_lt_i32_e32 vcc, s12, v44
	s_or_b64 s[68:69], s[2:3], vcc
	s_and_b64 vcc, s[0:1], s[68:69]
	v_cndmask_b32_e32 v24, v170, v24, vcc
	v_cmp_ge_i32_e32 vcc, v44, v72
	v_cmp_lt_i32_e64 s[0:1], v44, v96
	s_and_b64 s[0:1], vcc, s[0:1]
	v_cmp_lt_i32_e32 vcc, s13, v44
	s_or_b64 s[68:69], s[2:3], vcc
	s_and_b64 vcc, s[0:1], s[68:69]
	v_or_b32_e32 v45, 2, v44
	v_cndmask_b32_e32 v25, v170, v25, vcc
	v_cmp_gt_i32_e32 vcc, v45, v72
	v_cmp_le_i32_e64 s[0:1], v45, v96
	s_and_b64 s[0:1], vcc, s[0:1]
	v_cmp_lt_i32_e32 vcc, s12, v45
	s_or_b64 s[68:69], s[2:3], vcc
	s_and_b64 vcc, s[0:1], s[68:69]
	v_or_b32_e32 v44, 3, v44
	v_cndmask_b32_e32 v26, v170, v26, vcc
	v_cmp_gt_i32_e32 vcc, v44, v72
	v_cmp_le_i32_e64 s[0:1], v44, v96
	s_and_b64 s[0:1], vcc, s[0:1]
	v_cmp_lt_i32_e32 vcc, s12, v44
	s_or_b64 s[68:69], s[2:3], vcc
	s_and_b64 vcc, s[0:1], s[68:69]
	v_cndmask_b32_e32 v27, v170, v27, vcc
	s_waitcnt vmcnt(0)
	v_max3_f32 v44, v95, v24, v25
	v_max3_f32 v44, v44, v26, v27
	v_max3_f32 v44, v44, v8, v9
	v_max3_f32 v44, v44, v10, v11
	v_max3_f32 v44, v44, v12, v13
	v_max3_f32 v44, v44, v14, v15
	v_max3_f32 v44, v44, v16, v17
	v_max3_f32 v44, v44, v18, v19
	v_max3_f32 v44, v44, v20, v21
	v_max3_f32 v44, v44, v22, v23
	v_max3_f32 v44, v44, v28, v29
	v_max3_f32 v44, v44, v30, v31
	v_max3_f32 v44, v44, v32, v33
	v_max3_f32 v44, v44, v34, v35
	v_max3_f32 v44, v44, v36, v37
	v_max3_f32 v44, v44, v38, v39
	v_max3_f32 v44, v44, v48, v49
	v_max3_f32 v44, v44, v50, v51
	v_max3_f32 v44, v44, v40, v41
	v_max3_f32 v44, v44, v42, v43
	ds_bpermute_b32 v45, v108, v44
	s_waitcnt lgkmcnt(0)
	v_max_f32_e32 v45, v45, v45
	v_max_f32_e32 v44, v44, v45
	ds_bpermute_b32 v45, v109, v44
	s_waitcnt lgkmcnt(0)
	v_max_f32_e32 v45, v45, v45
	v_max_f32_e32 v44, v44, v45
	v_sub_f32_e32 v24, v24, v44
	v_mul_f32_e32 v24, 0x3fb8aa3b, v24
	v_sub_f32_e32 v25, v25, v44
	v_exp_f32_e32 v24, v24
	v_mul_f32_e32 v25, 0x3fb8aa3b, v25
	v_sub_f32_e32 v26, v26, v44
	v_exp_f32_e32 v25, v25
	v_mul_f32_e32 v26, 0x3fb8aa3b, v26
	v_sub_f32_e32 v27, v27, v44
	v_exp_f32_e32 v26, v26
	v_mul_f32_e32 v27, 0x3fb8aa3b, v27
	v_sub_f32_e32 v8, v8, v44
	v_exp_f32_e32 v27, v27
	v_mul_f32_e32 v8, 0x3fb8aa3b, v8
	v_sub_f32_e32 v9, v9, v44
	v_add_f32_e32 v45, 0, v24
	v_exp_f32_e32 v8, v8
	v_mul_f32_e32 v9, 0x3fb8aa3b, v9
	v_sub_f32_e32 v10, v10, v44
	v_add_f32_e32 v45, v25, v45
	v_exp_f32_e32 v9, v9
	v_mul_f32_e32 v10, 0x3fb8aa3b, v10
	v_sub_f32_e32 v11, v11, v44
	v_add_f32_e32 v45, v26, v45
	v_exp_f32_e32 v10, v10
	v_mul_f32_e32 v11, 0x3fb8aa3b, v11
	v_sub_f32_e32 v12, v12, v44
	v_add_f32_e32 v45, v27, v45
	v_exp_f32_e32 v11, v11
	v_mul_f32_e32 v12, 0x3fb8aa3b, v12
	v_sub_f32_e32 v13, v13, v44
	v_add_f32_e32 v45, v8, v45
	v_exp_f32_e32 v12, v12
	v_mul_f32_e32 v13, 0x3fb8aa3b, v13
	v_sub_f32_e32 v14, v14, v44
	v_add_f32_e32 v45, v9, v45
	v_exp_f32_e32 v13, v13
	v_mul_f32_e32 v14, 0x3fb8aa3b, v14
	v_sub_f32_e32 v15, v15, v44
	v_add_f32_e32 v45, v10, v45
	v_exp_f32_e32 v14, v14
	v_mul_f32_e32 v15, 0x3fb8aa3b, v15
	v_sub_f32_e32 v16, v16, v44
	v_add_f32_e32 v45, v11, v45
	v_exp_f32_e32 v15, v15
	v_mul_f32_e32 v16, 0x3fb8aa3b, v16
	v_sub_f32_e32 v17, v17, v44
	v_add_f32_e32 v45, v12, v45
	v_exp_f32_e32 v16, v16
	v_mul_f32_e32 v17, 0x3fb8aa3b, v17
	v_sub_f32_e32 v18, v18, v44
	v_add_f32_e32 v45, v13, v45
	v_exp_f32_e32 v17, v17
	v_mul_f32_e32 v18, 0x3fb8aa3b, v18
	v_sub_f32_e32 v19, v19, v44
	v_add_f32_e32 v45, v14, v45
	v_exp_f32_e32 v18, v18
	v_mul_f32_e32 v19, 0x3fb8aa3b, v19
	v_sub_f32_e32 v20, v20, v44
	v_add_f32_e32 v45, v15, v45
	v_exp_f32_e32 v19, v19
	v_mul_f32_e32 v20, 0x3fb8aa3b, v20
	v_add_f32_e32 v45, v16, v45
	v_exp_f32_e32 v46, v20
	v_add_f32_e32 v45, v17, v45
	v_add_f32_e32 v45, v18, v45
	v_sub_f32_e32 v21, v21, v44
	v_add_f32_e32 v45, v19, v45
	v_mul_f32_e32 v21, 0x3fb8aa3b, v21
	v_add_f32_e32 v20, v46, v45
	v_exp_f32_e32 v45, v21
	v_sub_f32_e32 v21, v22, v44
	v_mul_f32_e32 v21, 0x3fb8aa3b, v21
	v_exp_f32_e32 v47, v21
	v_sub_f32_e32 v21, v23, v44
	v_mul_f32_e32 v21, 0x3fb8aa3b, v21
	v_exp_f32_e32 v72, v21
	v_sub_f32_e32 v21, v28, v44
	v_mul_f32_e32 v21, 0x3fb8aa3b, v21
	v_exp_f32_e32 v28, v21
	v_sub_f32_e32 v21, v29, v44
	v_mul_f32_e32 v21, 0x3fb8aa3b, v21
	v_exp_f32_e32 v29, v21
	v_sub_f32_e32 v21, v30, v44
	v_mul_f32_e32 v21, 0x3fb8aa3b, v21
	v_exp_f32_e32 v30, v21
	v_sub_f32_e32 v21, v31, v44
	v_mul_f32_e32 v21, 0x3fb8aa3b, v21
	v_exp_f32_e32 v31, v21
	v_sub_f32_e32 v21, v32, v44
	v_mul_f32_e32 v21, 0x3fb8aa3b, v21
	v_exp_f32_e32 v32, v21
	v_sub_f32_e32 v21, v33, v44
	v_mul_f32_e32 v21, 0x3fb8aa3b, v21
	v_exp_f32_e32 v33, v21
	v_sub_f32_e32 v21, v34, v44
	v_mul_f32_e32 v21, 0x3fb8aa3b, v21
	v_exp_f32_e32 v34, v21
	v_sub_f32_e32 v21, v35, v44
	v_mul_f32_e32 v21, 0x3fb8aa3b, v21
	v_exp_f32_e32 v35, v21
	v_sub_f32_e32 v21, v36, v44
	v_mul_f32_e32 v21, 0x3fb8aa3b, v21
	v_exp_f32_e32 v36, v21
	v_sub_f32_e32 v21, v37, v44
	v_mul_f32_e32 v21, 0x3fb8aa3b, v21
	v_exp_f32_e32 v37, v21
	v_sub_f32_e32 v21, v38, v44
	v_mul_f32_e32 v21, 0x3fb8aa3b, v21
	v_add_f32_e32 v20, v45, v20
	v_exp_f32_e32 v38, v21
	v_sub_f32_e32 v21, v39, v44
	v_add_f32_e32 v20, v47, v20
	v_mul_f32_e32 v21, 0x3fb8aa3b, v21
	v_add_f32_e32 v20, v72, v20
	v_exp_f32_e32 v39, v21
	v_sub_f32_e32 v21, v48, v44
	v_add_f32_e32 v20, v28, v20
	v_mul_f32_e32 v21, 0x3fb8aa3b, v21
	v_add_f32_e32 v20, v29, v20
	v_exp_f32_e32 v48, v21
	v_sub_f32_e32 v21, v49, v44
	v_add_f32_e32 v20, v30, v20
	v_mul_f32_e32 v21, 0x3fb8aa3b, v21
	v_add_f32_e32 v20, v31, v20
	v_exp_f32_e32 v49, v21
	v_sub_f32_e32 v21, v50, v44
	v_add_f32_e32 v20, v32, v20
	v_mul_f32_e32 v21, 0x3fb8aa3b, v21
	v_add_f32_e32 v20, v33, v20
	v_exp_f32_e32 v50, v21
	v_sub_f32_e32 v21, v51, v44
	v_add_f32_e32 v20, v34, v20
	v_mul_f32_e32 v21, 0x3fb8aa3b, v21
	v_add_f32_e32 v20, v35, v20
	v_exp_f32_e32 v51, v21
	v_sub_f32_e32 v21, v40, v44
	v_add_f32_e32 v20, v36, v20
	v_mul_f32_e32 v21, 0x3fb8aa3b, v21
	v_add_f32_e32 v20, v37, v20
	v_exp_f32_e32 v40, v21
	v_sub_f32_e32 v21, v41, v44
	v_add_f32_e32 v20, v38, v20
	v_mul_f32_e32 v21, 0x3fb8aa3b, v21
	v_add_f32_e32 v20, v39, v20
	v_exp_f32_e32 v41, v21
	v_sub_f32_e32 v21, v42, v44
	v_add_f32_e32 v20, v48, v20
	v_mul_f32_e32 v21, 0x3fb8aa3b, v21
	v_add_f32_e32 v20, v49, v20
	v_exp_f32_e32 v42, v21
	v_sub_f32_e32 v21, v43, v44
	v_add_f32_e32 v20, v50, v20
	v_mul_f32_e32 v21, 0x3fb8aa3b, v21
	v_add_f32_e32 v20, v51, v20
	v_exp_f32_e32 v43, v21
	v_add_f32_e32 v20, v40, v20
	v_add_f32_e32 v20, v41, v20
	v_add_f32_e32 v20, v42, v20
	v_add_f32_e32 v20, v43, v20
	ds_bpermute_b32 v21, v108, v20
	v_cvt_pk_bf16_f32 v24, v24, v25
	v_cvt_pk_bf16_f32 v25, v26, v27
	v_cvt_pk_bf16_f32 v26, v8, v9
	v_cvt_pk_bf16_f32 v27, v10, v11
	s_waitcnt lgkmcnt(0)
; #define LAS __attribute__((address_space(3)))
; __device__ __forceinline__ unsigned pk2(float lo, float hi) { return pg8::cvt_pk_bf16(lo, hi); }
; __device__ __forceinline__ bf16x8 pack8(const float (&o)[8]) { v4u w; w.x = pk2(o[0], o[1]); w.y = pk2(o[2], o[3]); w.z = pk2(o[4], o[5]); w.w = pk2(o[6], o[7]); return __builtin_bit_cast(bf16x8, w); }
; __device__ __forceinline__ v2u vtr(const LAS bf16* p) { return __builtin_bit_cast(v2u, __builtin_amdgcn_ds_read_tr16_b64_v4i16((LAS v4i16_t*)p)); }
; template <bool SAMPLE>
; __device__ __forceinline__ void swa_unit(const Params& p, LAS unsigned char* lds, int unit, int tid, int wave, int lane) {
;     ...
;             den += __shfl_xor(den, 16); den += __shfl_xor(den, 32);
;             den += __expf(sink - mx);
;             const float rden = 1.f / den;
;             bf16x8 pf[5];
; #pragma unroll
;             for (int cc = 0; cc < 5; ++cc) { float t8[8];
; #pragma unroll
;                 for (int e = 0; e < 4; ++e) { t8[e] = S[cc][0][e]; t8[4 + e] = S[cc][1][e]; }
;                 pf[cc] = pack8(t8); }
; #pragma unroll
;             for (int dt = 0; dt < 4; ++dt) { f32x4 o = (f32x4){0.f, 0.f, 0.f, 0.f};
; #pragma unroll
;                 for (int cc = 0; cc < 5; ++cc) { const LAS bf16* vp = Vt + (32 * (c0 + cc) + 4 * kq + (q16 >> 2)) * SWA_VS + 16 * dt + 4 * (q16 & 3);
;                     const v2u lo = vtr(vp), hi = vtr(vp + 16 * SWA_VS);
;                     v4u av; av.x = lo.x; av.y = lo.y; av.z = hi.x; av.w = hi.y;
;                     o = __builtin_amdgcn_mfma_f32_16x16x32_bf16(__builtin_bit_cast(bf16x8, av), pf[cc], o, 0, 0, 0); }
;                 v2u w; w.x = pk2(o[0] * rden, o[1] * rden); w.y = pk2(o[2] * rden, o[3] * rden);
;                 *(v2u*)(AO + row * 1024 + h * 64 + 16 * dt + 4 * kq) = w; }
	v_add_f32_e32 v20, v20, v21
	ds_bpermute_b32 v21, v109, v20
	s_waitcnt lgkmcnt(0)
	v_add_f32_e32 v20, v20, v21
	v_sub_f32_e32 v21, v95, v44
	v_mul_f32_e32 v21, 0x3fb8aa3b, v21
	v_exp_f32_e32 v21, v21
	s_nop 0
	v_add_f32_e32 v44, v21, v20
	v_cvt_pk_bf16_f32 v20, v12, v13
	v_cvt_pk_bf16_f32 v21, v14, v15
	v_cvt_pk_bf16_f32 v22, v16, v17
	v_cvt_pk_bf16_f32 v23, v18, v19
	v_cvt_pk_bf16_f32 v16, v46, v45
	v_cvt_pk_bf16_f32 v17, v47, v72
	v_cvt_pk_bf16_f32 v18, v28, v29
	v_div_scale_f32 v28, s[0:1], v44, v44, 1.0
	v_rcp_f32_e32 v29, v28
	v_cvt_pk_bf16_f32 v19, v30, v31
	v_cvt_pk_bf16_f32 v12, v32, v33
	v_cvt_pk_bf16_f32 v13, v34, v35
	v_cvt_pk_bf16_f32 v14, v36, v37
	v_cvt_pk_bf16_f32 v15, v38, v39
	s_nop 0
	v_fma_f32 v30, -v28, v29, 1.0
	v_fmac_f32_e32 v29, v30, v29
	v_div_scale_f32 v30, vcc, 1.0, v44, 1.0
	v_mul_f32_e32 v31, v30, v29
	v_fma_f32 v32, -v28, v31, v30
	v_fmac_f32_e32 v31, v32, v29
	v_fma_f32 v28, -v28, v31, v30
	v_div_fmas_f32 v28, v28, v29, v31
	v_cvt_pk_bf16_f32 v8, v48, v49
	v_div_fixup_f32 v48, v28, v44, 1.0
	v_ashrrev_i32_e32 v28, 2, v75
	v_add_u32_e32 v45, v28, v74
	v_lshlrev_b32_e32 v28, 3, v75
	v_and_b32_e32 v28, 24, v28
	v_ashrrev_i32_e32 v75, 31, v74
	s_add_u32 s0, s4, s54
	v_add_u32_e32 v44, 0, v28
	v_lshl_add_u64 v[28:29], v[74:75], 1, v[70:71]
	s_addc_u32 s1, s5, s55
	v_lshl_add_u64 v[46:47], s[0:1], 0, v[28:29]
	v_add_u32_e32 v28, s53, v45
	v_mad_u64_u32 v[28:29], s[0:1], v28, s7, v[44:45]
	v_cvt_pk_bf16_f32 v9, v50, v51
	v_cvt_pk_bf16_f32 v10, v40, v41
	v_cvt_pk_bf16_f32 v11, v42, v43
	ds_read_b64_tr_b16 v[184:185], v28 offset:36864
	ds_read_b64_tr_b16 v[186:187], v28 offset:39168
	s_nop 1
	v_add_u32_e32 v29, s51, v45
	s_waitcnt lgkmcnt(0)
	ds_read_b64_tr_b16 v[222:223], v28 offset:36896
	ds_read_b64_tr_b16 v[224:225], v28 offset:39200
	v_mfma_f32_16x16x32_bf16 v[32:35], v[184:187], v[24:27], 0
	v_mad_u64_u32 v[30:31], s[0:1], v29, s7, v[44:45]
	ds_read_b64_tr_b16 v[188:189], v30 offset:36864
	ds_read_b64_tr_b16 v[190:191], v30 offset:39168
	ds_read_b64_tr_b16 v[226:227], v30 offset:36896
	ds_read_b64_tr_b16 v[228:229], v30 offset:39200
	s_nop 1
	v_add_u32_e32 v29, s85, v45
	s_waitcnt lgkmcnt(2)
	v_mfma_f32_16x16x32_bf16 v[34:37], v[188:191], v[20:23], v[32:35]
	s_nop 2
	v_mad_u64_u32 v[32:33], s[0:1], v29, s7, v[44:45]
	ds_read_b64_tr_b16 v[206:207], v32 offset:36864
	ds_read_b64_tr_b16 v[208:209], v32 offset:39168
	ds_read_b64_tr_b16 v[230:231], v32 offset:36896
	ds_read_b64_tr_b16 v[232:233], v32 offset:39200
	s_nop 1
	v_add_u32_e32 v29, s41, v45
	s_waitcnt lgkmcnt(2)
	v_mfma_f32_16x16x32_bf16 v[36:39], v[206:209], v[16:19], v[34:37]
	s_nop 2
	v_mad_u64_u32 v[34:35], s[0:1], v29, s7, v[44:45]
	ds_read_b64_tr_b16 v[210:211], v34 offset:36864
	ds_read_b64_tr_b16 v[212:213], v34 offset:39168
	ds_read_b64_tr_b16 v[234:235], v34 offset:36896
	ds_read_b64_tr_b16 v[236:237], v34 offset:39200
	s_nop 1
	v_add_u32_e32 v29, s43, v45
	s_waitcnt lgkmcnt(2)
	v_mfma_f32_16x16x32_bf16 v[38:41], v[210:213], v[12:15], v[36:39]
	s_nop 2
	v_mad_u64_u32 v[36:37], s[0:1], v29, s7, v[44:45]
	ds_read_b64_tr_b16 v[218:219], v36 offset:36864
	ds_read_b64_tr_b16 v[220:221], v36 offset:39168
	ds_read_b64_tr_b16 v[242:243], v36 offset:36896
	ds_read_b64_tr_b16 v[244:245], v36 offset:39200
	s_nop 1
	s_waitcnt lgkmcnt(2)
	v_mfma_f32_16x16x32_bf16 v[38:41], v[218:221], v[8:11], v[38:41]
	s_mov_b32 s0, 0xed00000
	s_add_u32 s54, s54, 0x80
	s_addc_u32 s55, s55, 0
	s_nop 4
	v_mul_f32_e32 v29, v38, v48
	v_add_co_u32_e32 v38, vcc, s0, v46
	v_mul_f32_e32 v31, v39, v48
	s_nop 0
	v_addc_co_u32_e32 v39, vcc, 0, v47, vcc
	v_cvt_pk_bf16_f32 v42, v29, v31
	v_mul_f32_e32 v29, v40, v48
	v_mul_f32_e32 v31, v41, v48
	v_cvt_pk_bf16_f32 v43, v29, v31
	global_store_dwordx2 v[38:39], v[42:43], off
	s_nop 4
	ds_read_b64_tr_b16 v[184:185], v28 offset:36928
	ds_read_b64_tr_b16 v[186:187], v28 offset:39232
	ds_read_b64_tr_b16 v[188:189], v30 offset:36928
	ds_read_b64_tr_b16 v[190:191], v30 offset:39232
	ds_read_b64_tr_b16 v[206:207], v32 offset:36928
	ds_read_b64_tr_b16 v[208:209], v32 offset:39232
	ds_read_b64_tr_b16 v[210:211], v34 offset:36928
	ds_read_b64_tr_b16 v[212:213], v34 offset:39232
	v_mfma_f32_16x16x32_bf16 v[40:43], v[222:225], v[24:27], 0
	s_add_u32 s28, s28, 4
	s_addc_u32 s29, s29, 0
	s_cmpk_lg_i32 s54, 0x200
	s_nop 0
	v_mfma_f32_16x16x32_bf16 v[40:43], v[226:229], v[20:23], v[40:43]
	s_nop 2
	v_mfma_f32_16x16x32_bf16 v[40:43], v[230:233], v[16:19], v[40:43]
	s_nop 2
	v_mfma_f32_16x16x32_bf16 v[40:43], v[234:237], v[12:15], v[40:43]
	s_nop 1
	s_waitcnt lgkmcnt(8)
	v_mfma_f32_16x16x32_bf16 v[40:43], v[242:245], v[8:11], v[40:43]
	s_nop 7
	v_mul_f32_e32 v29, v48, v40
	v_mul_f32_e32 v31, v48, v41
	v_cvt_pk_bf16_f32 v40, v29, v31
	v_mul_f32_e32 v29, v48, v42
	v_mul_f32_e32 v31, v48, v43
	v_cvt_pk_bf16_f32 v41, v29, v31
	global_store_dwordx2 v[38:39], v[40:41], off offset:32
	s_nop 3
	s_waitcnt lgkmcnt(6)
	v_mfma_f32_16x16x32_bf16 v[40:43], v[184:187], v[24:27], 0
	s_waitcnt lgkmcnt(4)
	v_mfma_f32_16x16x32_bf16 v[40:43], v[188:191], v[20:23], v[40:43]
	s_nop 1
	s_waitcnt lgkmcnt(2)
	v_mfma_f32_16x16x32_bf16 v[40:43], v[206:209], v[16:19], v[40:43]
	s_nop 1
	s_waitcnt lgkmcnt(0)
	v_mfma_f32_16x16x32_bf16 v[40:43], v[210:213], v[12:15], v[40:43]
	ds_read_b64_tr_b16 v[44:45], v36 offset:36928
	ds_read_b64_tr_b16 v[46:47], v36 offset:39232
	s_waitcnt lgkmcnt(0)
	v_mfma_f32_16x16x32_bf16 v[40:43], v[44:47], v[8:11], v[40:43]
	s_nop 7
	v_mul_f32_e32 v29, v48, v40
	v_mul_f32_e32 v31, v48, v41
	v_cvt_pk_bf16_f32 v40, v29, v31
	v_mul_f32_e32 v29, v48, v42
	v_mul_f32_e32 v31, v48, v43
	v_cvt_pk_bf16_f32 v41, v29, v31
	global_store_dwordx2 v[38:39], v[40:41], off offset:64
	ds_read_b64_tr_b16 v[40:41], v28 offset:36960
	ds_read_b64_tr_b16 v[42:43], v28 offset:39264
	ds_read_b64_tr_b16 v[28:29], v30 offset:36960
	ds_read_b64_tr_b16 v[30:31], v30 offset:39264
	s_waitcnt lgkmcnt(2)
	v_mfma_f32_16x16x32_bf16 v[24:27], v[40:43], v[24:27], 0
	s_waitcnt lgkmcnt(0)
	v_mfma_f32_16x16x32_bf16 v[20:23], v[28:31], v[20:23], v[24:27]
	s_nop 5
	ds_read_b64_tr_b16 v[24:25], v32 offset:36960
	ds_read_b64_tr_b16 v[26:27], v32 offset:39264
	s_waitcnt lgkmcnt(0)
	v_mfma_f32_16x16x32_bf16 v[16:19], v[24:27], v[16:19], v[20:23]
	s_nop 2
	ds_read_b64_tr_b16 v[20:21], v34 offset:36960
	ds_read_b64_tr_b16 v[22:23], v34 offset:39264
	s_waitcnt lgkmcnt(0)
	v_mfma_f32_16x16x32_bf16 v[12:15], v[20:23], v[12:15], v[16:19]
	s_nop 2
	ds_read_b64_tr_b16 v[16:17], v36 offset:36960
	ds_read_b64_tr_b16 v[18:19], v36 offset:39264
	s_waitcnt lgkmcnt(0)
	v_mfma_f32_16x16x32_bf16 v[8:11], v[16:19], v[8:11], v[12:15]
	s_nop 2
	v_mov_b64_e32 v[14:15], v[6:7]
	v_mov_b64_e32 v[12:13], v[4:5]
	s_nop 2
	v_mul_f32_e32 v8, v48, v8
	v_mul_f32_e32 v9, v48, v9
	v_cvt_pk_bf16_f32 v8, v8, v9
	v_mul_f32_e32 v9, v48, v10
	v_mul_f32_e32 v10, v48, v11
	v_cvt_pk_bf16_f32 v9, v9, v10
	global_store_dwordx2 v[38:39], v[8:9], off offset:96
	v_mov_b64_e32 v[10:11], v[2:3]
	v_mov_b64_e32 v[8:9], v[0:1]
	s_cbranch_scc0 .LBB0_1859
	s_nop 0
	s_nop 0
	s_nop 0
	s_nop 0
	s_nop 0
	s_nop 0
	s_nop 0

; #define LAS __attribute__((address_space(3)))
; __device__ __forceinline__ bf16x8 pack8(const float (&o)[8]) { v4u w; w.x = pk2(o[0], o[1]); w.y = pk2(o[2], o[3]); w.z = pk2(o[4], o[5]); w.w = pk2(o[6], o[7]); return __builtin_bit_cast(bf16x8, w); }
; template <bool SAMPLE>
; __device__ __forceinline__ void swa_unit(const Params& p, LAS unsigned char* lds, int unit, int tid, int wave, int lane) {
;     ...
;             const float rs = rsqrtf(ss * (1.f / 64.f) + EPS);
; #pragma unroll
;             for (int dc = 0; dc < 2; ++dc) {
; #pragma unroll
;                 for (int e = 0; e < 8; ++e) qv[dc][e] *= rs * qgs[dc][e]; }
; #pragma unroll
;             for (int e = 0; e < 8; ++e) { const float pk = __shfl_xor(qv[0][e], 16); const float cs = rc[e], sn = rsn[e];
;                 if (kq == 0) qv[0][e] = qv[0][e] * cs - pk * sn; else if (kq == 1) qv[0][e] = qv[0][e] * cs + pk * sn; }
;             bf16x8 qf[2];
; #pragma unroll
;             for (int dc = 0; dc < 2; ++dc) qf[dc] = pack8(qv[dc]);
;             f32x4 S[5][2];
;             const float sink = p.in[I_CSINK][h];
;             float mx = sink;
; #pragma unroll
;             for (int cc = 0; cc < 5; ++cc)
; #pragma unroll
;                 for (int tt = 0; tt < 2; ++tt) { const int kb = 32 * (c0 + cc) + 16 * tt; f32x4 a = (f32x4){0.f, 0.f, 0.f, 0.f};
; #pragma unroll
;                     for (int dc = 0; dc < 2; ++dc) { const bf16x8 kf = *(const LAS bf16x8*)(Kl + (kb + q16) * SWA_KS + 32 * dc + 8 * kq);
;                         a = __builtin_amdgcn_mfma_f32_16x16x32_bf16(kf, qf[dc], a, 0, 0, 0); }
;                     const int rel = (kb >> 4) - wave;
;                     const bool full = !SAMPLE && rel >= 1 && rel <= 7 && (nb > 0 || kb >= 128);
;                     if (!full) {
; #pragma unroll
;                         for (int e = 0; e < 4; ++e) { const int s = kb + 4 * kq + e; const bool ok = (s > i) && (s <= i + 128) && (SAMPLE || nb > 0 || s >= 128);
;                             a[e] = ok ? a[e] : -INFINITY; } }
; #pragma unroll
;                     for (int e = 0; e < 4; ++e) mx = fmaxf(mx, a[e]);
;                     S[cc][tt] = a; }
.LBB0_2174:
	s_or_b64 exec, exec, s[2:3]
	v_mul_f32_e32 v4, 0x3e000000, v4
	v_mul_f32_e32 v5, 0x3e000000, v5
	v_mul_f32_e32 v4, v4, v38
	v_mul_f32_e32 v6, 0x3e000000, v6
	v_mul_f32_e32 v13, v4, v19
	v_mul_f32_e32 v4, v5, v38
	v_mul_f32_e32 v7, 0x3e000000, v7
	v_mul_f32_e32 v0, 0x3e000000, v0
	v_mul_f32_e32 v15, v4, v18
	v_mul_f32_e32 v4, v6, v38
	v_mul_f32_e32 v1, 0x3e000000, v1
	v_mul_f32_e32 v18, v4, v21
	v_mul_f32_e32 v4, v7, v38
	v_mul_f32_e32 v0, v0, v38
	v_mul_f32_e32 v2, 0x3e000000, v2
	v_mul_f32_e32 v19, v4, v20
	v_mul_f32_e32 v20, v0, v25
	v_mul_f32_e32 v0, v1, v38
	v_mul_f32_e32 v3, 0x3e000000, v3
	v_mul_f32_e32 v21, v0, v24
	v_mul_f32_e32 v0, v2, v38
	v_mul_f32_e32 v24, v0, v27
	v_mul_f32_e32 v0, v3, v38
	s_waitcnt lgkmcnt(0)
	v_ashrrev_i32_e32 v11, 3, v17
	v_mul_f32_e32 v3, v0, v26
	v_cvt_pk_bf16_f32 v4, v28, v12
	v_cvt_pk_bf16_f32 v5, v30, v14
	v_cvt_pk_bf16_f32 v6, v32, v8
	v_cvt_pk_bf16_f32 v7, v34, v10
	v_cvt_pk_bf16_f32 v0, v13, v15
	v_cvt_pk_bf16_f32 v1, v18, v19
	v_cvt_pk_bf16_f32 v2, v20, v21
	v_cvt_pk_bf16_f32 v3, v24, v3
	v_add_u32_e32 v24, s5, v11
	v_ashrrev_i32_e32 v25, 31, v24
	v_lshl_add_u64 v[10:11], v[24:25], 2, s[26:27]
	global_load_dword v8, v[10:11], off
	v_lshlrev_b32_e32 v11, 4, v36
	v_mul_lo_u32 v12, v17, s8
	v_add3_u32 v15, 0, v11, v12
	ds_read_b128 v[116:119], v15
	ds_read_b128 v[120:123], v15 offset:64
	ds_read_b128 v[128:131], v15 offset:2368
	ds_read_b128 v[124:127], v15 offset:2304
	ds_read_b128 v[132:135], v15 offset:4608
	s_nop 1
	s_waitcnt lgkmcnt(4)
	ds_read_b128 v[136:139], v15 offset:4672
	ds_read_b128 v[140:143], v15 offset:6912
	ds_read_b128 v[144:147], v15 offset:6976
	ds_read_b128 v[148:151], v15 offset:9216
	ds_read_b128 v[156:159], v15 offset:9280
	v_mfma_f32_16x16x32_bf16 v[18:21], v[116:119], v[4:7], 0
	v_and_b32_e32 v9, 7, v17
	v_lshlrev_b32_e32 v26, 2, v36
	v_or_b32_e32 v10, 0x80, v9
	s_waitcnt lgkmcnt(8)
	v_mfma_f32_16x16x32_bf16 v[18:21], v[120:123], v[0:3], v[18:21]
	v_or_b32_e32 v22, s0, v9
	v_mov_b32_e32 v23, s1
	v_cmp_gt_i32_e32 vcc, v26, v9
	v_cmp_le_i32_e64 s[0:1], v26, v10
	s_and_b64 vcc, vcc, s[0:1]
	s_nop 2
	v_cndmask_b32_e32 v11, v114, v18, vcc
	v_cmp_ge_i32_e32 vcc, v26, v9
	v_cmp_lt_i32_e64 s[0:1], v26, v10
	s_and_b64 vcc, vcc, s[0:1]
	v_or_b32_e32 v13, 2, v26
	v_cndmask_b32_e32 v12, v114, v19, vcc
	v_cmp_gt_i32_e32 vcc, v13, v9
	v_cmp_le_i32_e64 s[0:1], v13, v10
	s_and_b64 vcc, vcc, s[0:1]
	v_or_b32_e32 v14, 3, v26
	v_cndmask_b32_e32 v13, v114, v20, vcc
	v_cmp_gt_i32_e32 vcc, v14, v9
	v_cmp_le_i32_e64 s[0:1], v14, v10
	s_and_b64 vcc, vcc, s[0:1]
	v_cndmask_b32_e32 v14, v114, v21, vcc
	v_lshlrev_b64 v[22:23], 11, v[22:23]
	v_lshlrev_b32_e32 v24, 6, v24
	v_lshl_add_u64 v[22:23], s[44:45], 0, v[22:23]
	s_nop 1
	s_waitcnt vmcnt(0)
	v_max3_f32 v18, v8, v11, v12
	v_max3_f32 v25, v18, v13, v14
	s_nop 0
	s_waitcnt lgkmcnt(6)
	v_mfma_f32_16x16x32_bf16 v[18:21], v[124:127], v[4:7], 0
	v_mfma_f32_16x16x32_bf16 v[28:31], v[128:131], v[0:3], v[18:21]
	s_nop 6
	v_add_u32_e32 v18, 16, v26
	v_cmp_gt_i32_e32 vcc, v18, v9
	v_cmp_le_i32_e64 s[0:1], v18, v10
	s_and_b64 vcc, vcc, s[0:1]
	v_add_u32_e32 v19, 17, v26
	v_cndmask_b32_e32 v18, v114, v28, vcc
	v_cmp_gt_i32_e32 vcc, v19, v9
	v_cmp_le_i32_e64 s[0:1], v19, v10
	s_and_b64 vcc, vcc, s[0:1]
	v_add_u32_e32 v20, 18, v26
	v_cndmask_b32_e32 v19, v114, v29, vcc
	v_cmp_gt_i32_e32 vcc, v20, v9
	v_cmp_le_i32_e64 s[0:1], v20, v10
	s_and_b64 vcc, vcc, s[0:1]
	v_add_u32_e32 v20, 19, v26
	v_cndmask_b32_e32 v21, v114, v30, vcc
	v_cmp_gt_i32_e32 vcc, v20, v9
	v_cmp_le_i32_e64 s[0:1], v20, v10
	s_and_b64 vcc, vcc, s[0:1]
	v_cndmask_b32_e32 v20, v114, v31, vcc
	s_nop 0
	s_waitcnt lgkmcnt(5)
	v_mfma_f32_16x16x32_bf16 v[28:31], v[132:135], v[4:7], 0
	v_max3_f32 v25, v25, v18, v19
	v_max3_f32 v36, v25, v21, v20
	v_add_u32_e32 v25, 32, v26
	ds_read_b128 v[116:119], v15 offset:11520
	ds_read_b128 v[120:123], v15 offset:11584
	ds_read_b128 v[124:127], v15 offset:13824
	ds_read_b128 v[128:131], v15 offset:13888
	ds_read_b128 v[132:135], v15 offset:16128
	s_waitcnt lgkmcnt(9)
	v_mfma_f32_16x16x32_bf16 v[30:33], v[136:139], v[0:3], v[28:31]
	v_cmp_gt_i32_e32 vcc, v25, v9
	v_cmp_le_i32_e64 s[0:1], v25, v10
	s_and_b64 vcc, vcc, s[0:1]
	v_add_u32_e32 v25, 33, v26
	v_cmp_le_i32_e64 s[0:1], v25, v10
	s_nop 2
	v_cndmask_b32_e32 v29, v114, v30, vcc
	v_cmp_gt_i32_e32 vcc, v25, v9
	s_and_b64 vcc, vcc, s[0:1]
	v_add_u32_e32 v25, 34, v26
	v_cndmask_b32_e32 v28, v114, v31, vcc
	v_cmp_gt_i32_e32 vcc, v25, v9
	v_cmp_le_i32_e64 s[0:1], v25, v10
	s_and_b64 vcc, vcc, s[0:1]
	v_add_u32_e32 v25, 35, v26
	v_cndmask_b32_e32 v27, v114, v32, vcc
	v_cmp_gt_i32_e32 vcc, v25, v9
	v_cmp_le_i32_e64 s[0:1], v25, v10
	s_and_b64 vcc, vcc, s[0:1]
	v_cndmask_b32_e32 v25, v114, v33, vcc
	v_max3_f32 v30, v36, v29, v28
	v_max3_f32 v38, v30, v27, v25
	s_nop 1
	s_waitcnt lgkmcnt(8)
	v_mfma_f32_16x16x32_bf16 v[30:33], v[140:143], v[4:7], 0
	s_waitcnt lgkmcnt(7)
	v_mfma_f32_16x16x32_bf16 v[34:37], v[144:147], v[0:3], v[30:33]
	s_nop 5
	v_add_u32_e32 v30, 48, v26
	v_cmp_gt_i32_e32 vcc, v30, v9
	v_cmp_le_i32_e64 s[0:1], v30, v10
	s_and_b64 vcc, vcc, s[0:1]
	v_add_u32_e32 v30, 49, v26
	v_cndmask_b32_e32 v33, v114, v34, vcc
	v_cmp_gt_i32_e32 vcc, v30, v9
	v_cmp_le_i32_e64 s[0:1], v30, v10
	s_and_b64 vcc, vcc, s[0:1]
	v_add_u32_e32 v30, 50, v26
	v_cndmask_b32_e32 v32, v114, v35, vcc
	v_cmp_gt_i32_e32 vcc, v30, v9
	v_cmp_le_i32_e64 s[0:1], v30, v10
	s_and_b64 vcc, vcc, s[0:1]
	v_add_u32_e32 v30, 51, v26
	v_cndmask_b32_e32 v31, v114, v36, vcc
	v_cmp_gt_i32_e32 vcc, v30, v9
	v_cmp_le_i32_e64 s[0:1], v30, v10
	s_and_b64 vcc, vcc, s[0:1]
	v_cndmask_b32_e32 v30, v114, v37, vcc
	v_max3_f32 v34, v38, v33, v32
	v_max3_f32 v42, v34, v31, v30
	s_nop 1
	s_waitcnt lgkmcnt(6)
; #define LAS __attribute__((address_space(3)))
; template <bool SAMPLE>
; __device__ __forceinline__ void swa_unit(const Params& p, LAS unsigned char* lds, int unit, int tid, int wave, int lane) {
;     ...
;                 for (int tt = 0; tt < 2; ++tt) { const int kb = 32 * (c0 + cc) + 16 * tt; f32x4 a = (f32x4){0.f, 0.f, 0.f, 0.f};
; #pragma unroll
;                     for (int dc = 0; dc < 2; ++dc) { const bf16x8 kf = *(const LAS bf16x8*)(Kl + (kb + q16) * SWA_KS + 32 * dc + 8 * kq);
;                         a = __builtin_amdgcn_mfma_f32_16x16x32_bf16(kf, qf[dc], a, 0, 0, 0); }
;                     const int rel = (kb >> 4) - wave;
;                     const bool full = !SAMPLE && rel >= 1 && rel <= 7 && (nb > 0 || kb >= 128);
;                     if (!full) {
; #pragma unroll
;                         for (int e = 0; e < 4; ++e) { const int s = kb + 4 * kq + e; const bool ok = (s > i) && (s <= i + 128) && (SAMPLE || nb > 0 || s >= 128);
;                             a[e] = ok ? a[e] : -INFINITY; } }
; #pragma unroll
;                     for (int e = 0; e < 4; ++e) mx = fmaxf(mx, a[e]);
;                     S[cc][tt] = a; }
;             mx = fmaxf(mx, __shfl_xor(mx, 16)); mx = fmaxf(mx, __shfl_xor(mx, 32));
	v_mfma_f32_16x16x32_bf16 v[34:37], v[148:151], v[4:7], 0
	s_waitcnt lgkmcnt(5)
	v_mfma_f32_16x16x32_bf16 v[38:41], v[156:159], v[0:3], v[34:37]
	s_nop 5
	v_add_u32_e32 v34, 64, v26
	v_cmp_gt_i32_e32 vcc, v34, v9
	v_cmp_le_i32_e64 s[0:1], v34, v10
	s_and_b64 vcc, vcc, s[0:1]
	v_add_u32_e32 v34, 0x41, v26
	v_cndmask_b32_e32 v37, v114, v38, vcc
	v_cmp_gt_i32_e32 vcc, v34, v9
	v_cmp_le_i32_e64 s[0:1], v34, v10
	s_and_b64 vcc, vcc, s[0:1]
	v_add_u32_e32 v34, 0x42, v26
	v_cndmask_b32_e32 v36, v114, v39, vcc
	v_cmp_gt_i32_e32 vcc, v34, v9
	v_cmp_le_i32_e64 s[0:1], v34, v10
	s_and_b64 vcc, vcc, s[0:1]
	v_add_u32_e32 v34, 0x43, v26
	v_cndmask_b32_e32 v35, v114, v40, vcc
	v_cmp_gt_i32_e32 vcc, v34, v9
	v_cmp_le_i32_e64 s[0:1], v34, v10
	s_and_b64 vcc, vcc, s[0:1]
	v_cndmask_b32_e32 v34, v114, v41, vcc
	v_max3_f32 v38, v42, v37, v36
	v_max3_f32 v46, v38, v35, v34
	s_nop 1
	s_waitcnt lgkmcnt(4)
	ds_read_b128 v[136:139], v15 offset:16192
	ds_read_b128 v[144:147], v15 offset:18496
	ds_read_b128 v[140:143], v15 offset:18432
	ds_read_b128 v[148:151], v15 offset:20736
	ds_read_b128 v[156:159], v15 offset:20800
	v_mfma_f32_16x16x32_bf16 v[38:41], v[116:119], v[4:7], 0
	s_waitcnt lgkmcnt(8)
	v_mfma_f32_16x16x32_bf16 v[42:45], v[120:123], v[0:3], v[38:41]
	s_nop 5
	v_add_u32_e32 v38, 0x50, v26
	v_cmp_gt_i32_e32 vcc, v38, v9
	v_cmp_le_i32_e64 s[0:1], v38, v10
	s_and_b64 vcc, vcc, s[0:1]
	v_add_u32_e32 v38, 0x51, v26
	v_cndmask_b32_e32 v41, v114, v42, vcc
	v_cmp_gt_i32_e32 vcc, v38, v9
	v_cmp_le_i32_e64 s[0:1], v38, v10
	s_and_b64 vcc, vcc, s[0:1]
	v_add_u32_e32 v38, 0x52, v26
	v_cndmask_b32_e32 v40, v114, v43, vcc
	v_cmp_gt_i32_e32 vcc, v38, v9
	v_cmp_le_i32_e64 s[0:1], v38, v10
	s_and_b64 vcc, vcc, s[0:1]
	v_add_u32_e32 v38, 0x53, v26
	v_cndmask_b32_e32 v39, v114, v44, vcc
	v_cmp_gt_i32_e32 vcc, v38, v9
	v_cmp_le_i32_e64 s[0:1], v38, v10
	s_and_b64 vcc, vcc, s[0:1]
	v_cndmask_b32_e32 v38, v114, v45, vcc
	v_max3_f32 v42, v46, v41, v40
	v_max3_f32 v50, v42, v39, v38
	s_nop 1
	s_waitcnt lgkmcnt(7)
	v_mfma_f32_16x16x32_bf16 v[42:45], v[124:127], v[4:7], 0
	s_waitcnt lgkmcnt(6)
	v_mfma_f32_16x16x32_bf16 v[46:49], v[128:131], v[0:3], v[42:45]
	s_nop 5
	v_add_u32_e32 v42, 0x60, v26
	v_cmp_gt_i32_e32 vcc, v42, v9
	v_cmp_le_i32_e64 s[0:1], v42, v10
	s_and_b64 vcc, vcc, s[0:1]
	v_add_u32_e32 v42, 0x61, v26
	v_cndmask_b32_e32 v45, v114, v46, vcc
	v_cmp_gt_i32_e32 vcc, v42, v9
	v_cmp_le_i32_e64 s[0:1], v42, v10
	s_and_b64 vcc, vcc, s[0:1]
	v_add_u32_e32 v42, 0x62, v26
	v_cndmask_b32_e32 v44, v114, v47, vcc
	v_cmp_gt_i32_e32 vcc, v42, v9
	v_cmp_le_i32_e64 s[0:1], v42, v10
	s_and_b64 vcc, vcc, s[0:1]
	v_add_u32_e32 v42, 0x63, v26
	v_cndmask_b32_e32 v43, v114, v48, vcc
	v_cmp_gt_i32_e32 vcc, v42, v9
	v_cmp_le_i32_e64 s[0:1], v42, v10
	s_and_b64 vcc, vcc, s[0:1]
	v_cndmask_b32_e32 v42, v114, v49, vcc
	v_max3_f32 v46, v50, v45, v44
	v_max3_f32 v54, v46, v43, v42
	s_nop 1
	s_waitcnt lgkmcnt(5)
	v_mfma_f32_16x16x32_bf16 v[46:49], v[132:135], v[4:7], 0
	s_waitcnt lgkmcnt(4)
	v_mfma_f32_16x16x32_bf16 v[46:49], v[136:139], v[0:3], v[46:49]
	v_add_u32_e32 v50, 0x70, v26
	v_cmp_gt_i32_e32 vcc, v50, v9
	v_cmp_le_i32_e64 s[0:1], v50, v10
	s_and_b64 vcc, vcc, s[0:1]
	s_nop 0
	s_nop 2
	v_cndmask_b32_e32 v55, v114, v46, vcc
	v_add_u32_e32 v46, 0x71, v26
	v_cmp_gt_i32_e32 vcc, v46, v9
	v_cmp_le_i32_e64 s[0:1], v46, v10
	s_and_b64 vcc, vcc, s[0:1]
	v_add_u32_e32 v46, 0x72, v26
	v_cndmask_b32_e32 v56, v114, v47, vcc
	v_cmp_gt_i32_e32 vcc, v46, v9
	v_cmp_le_i32_e64 s[0:1], v46, v10
	s_and_b64 vcc, vcc, s[0:1]
	v_add_u32_e32 v46, 0x73, v26
	v_cndmask_b32_e32 v57, v114, v48, vcc
	v_cmp_gt_i32_e32 vcc, v46, v9
	v_cmp_le_i32_e64 s[0:1], v46, v10
	s_and_b64 vcc, vcc, s[0:1]
	v_cndmask_b32_e32 v58, v114, v49, vcc
	v_max3_f32 v46, v54, v55, v56
	v_max3_f32 v54, v46, v57, v58
	s_nop 0
	s_waitcnt lgkmcnt(2)
	v_mfma_f32_16x16x32_bf16 v[46:49], v[140:143], v[4:7], 0
	v_cmp_le_i32_e64 s[0:1], v26, v9
	v_mfma_f32_16x16x32_bf16 v[46:49], v[144:147], v[0:3], v[46:49]
	v_add_u32_e32 v50, 0x80, v26
	v_cmp_gt_i32_e32 vcc, v50, v9
	s_and_b64 vcc, s[0:1], vcc
	s_nop 4
	v_cndmask_b32_e32 v50, v114, v46, vcc
	v_add_u32_e32 v46, 0x81, v26
	v_cmp_gt_i32_e32 vcc, v46, v9
	v_cmp_le_i32_e64 s[0:1], v46, v10
	s_and_b64 vcc, vcc, s[0:1]
	v_add_u32_e32 v46, 0x82, v26
	v_cndmask_b32_e32 v51, v114, v47, vcc
	v_cmp_gt_i32_e32 vcc, v46, v9
	v_cmp_le_i32_e64 s[0:1], v46, v10
	s_and_b64 vcc, vcc, s[0:1]
	v_add_u32_e32 v46, 0x83, v26
	v_cndmask_b32_e32 v52, v114, v48, vcc
	v_cmp_gt_i32_e32 vcc, v46, v9
	v_cmp_le_i32_e64 s[0:1], v46, v10
	s_and_b64 vcc, vcc, s[0:1]
	v_cndmask_b32_e32 v53, v114, v49, vcc
	v_max3_f32 v46, v54, v50, v51
	v_max3_f32 v54, v46, v52, v53
	s_nop 0
	s_waitcnt lgkmcnt(1)
	v_mfma_f32_16x16x32_bf16 v[4:7], v[148:151], v[4:7], 0
	s_nop 0
	s_waitcnt lgkmcnt(0)
	v_mfma_f32_16x16x32_bf16 v[0:3], v[156:159], v[0:3], v[4:7]
	s_nop 4
	v_add_u32_e32 v4, 0x90, v26
	v_cmp_gt_i32_e32 vcc, v4, v9
	v_cmp_le_i32_e64 s[0:1], v4, v10
	s_and_b64 vcc, vcc, s[0:1]
	v_add_u32_e32 v4, 0x91, v26
	v_cndmask_b32_e32 v0, v114, v0, vcc
	v_cmp_gt_i32_e32 vcc, v4, v9
	v_cmp_le_i32_e64 s[0:1], v4, v10
	s_and_b64 vcc, vcc, s[0:1]
	v_add_u32_e32 v4, 0x92, v26
	v_cndmask_b32_e32 v1, v114, v1, vcc
	v_cmp_gt_i32_e32 vcc, v4, v9
	v_cmp_le_i32_e64 s[0:1], v4, v10
	s_and_b64 vcc, vcc, s[0:1]
	v_add_u32_e32 v4, 0x93, v26
	v_cndmask_b32_e32 v2, v114, v2, vcc
	v_cmp_gt_i32_e32 vcc, v4, v9
	v_cmp_le_i32_e64 s[0:1], v4, v10
	s_and_b64 vcc, vcc, s[0:1]
	v_cndmask_b32_e32 v3, v114, v3, vcc
	v_max3_f32 v4, v54, v0, v1
	v_max3_f32 v4, v4, v2, v3
	ds_bpermute_b32 v5, v108, v4
	s_waitcnt lgkmcnt(0)
; __device__ __forceinline__ bf16x8 pack8(const float (&o)[8]) { v4u w; w.x = pk2(o[0], o[1]); w.y = pk2(o[2], o[3]); w.z = pk2(o[4], o[5]); w.w = pk2(o[6], o[7]); return __builtin_bit_cast(bf16x8, w); }
; template <bool SAMPLE>
; __device__ __forceinline__ void swa_unit(const Params& p, LAS unsigned char* lds, int unit, int tid, int wave, int lane) {
;     ...
;             mx = fmaxf(mx, __shfl_xor(mx, 16)); mx = fmaxf(mx, __shfl_xor(mx, 32));
;             float den = 0.f;
; #pragma unroll
;             for (int cc = 0; cc < 5; ++cc)
; #pragma unroll
;                 for (int tt = 0; tt < 2; ++tt)
; #pragma unroll
;                     for (int e = 0; e < 4; ++e) { const float pe = __expf(S[cc][tt][e] - mx); S[cc][tt][e] = pe; den += pe; }
;             den += __shfl_xor(den, 16); den += __shfl_xor(den, 32);
;             den += __expf(sink - mx);
;             const float rden = 1.f / den;
;             bf16x8 pf[5];
; #pragma unroll
;             for (int cc = 0; cc < 5; ++cc) { float t8[8];
; #pragma unroll
;                 for (int e = 0; e < 4; ++e) { t8[e] = S[cc][0][e]; t8[4 + e] = S[cc][1][e]; }
;                 pf[cc] = pack8(t8); }
	v_max_f32_e32 v5, v5, v5
	v_max_f32_e32 v4, v4, v5
	ds_bpermute_b32 v5, v109, v4
	s_waitcnt lgkmcnt(0)
	v_max_f32_e32 v5, v5, v5
	v_max_f32_e32 v4, v4, v5
	v_sub_f32_e32 v5, v11, v4
	v_sub_f32_e32 v11, v18, v4
	v_sub_f32_e32 v18, v28, v4
	v_mul_f32_e32 v18, 0x3fb8aa3b, v18
	v_exp_f32_e32 v28, v18
	v_sub_f32_e32 v18, v27, v4
	v_mul_f32_e32 v18, 0x3fb8aa3b, v18
	v_exp_f32_e32 v27, v18
	v_sub_f32_e32 v18, v25, v4
	v_mul_f32_e32 v18, 0x3fb8aa3b, v18
	v_exp_f32_e32 v25, v18
	v_sub_f32_e32 v18, v33, v4
	v_mul_f32_e32 v18, 0x3fb8aa3b, v18
	v_sub_f32_e32 v15, v29, v4
	v_exp_f32_e32 v29, v18
	v_sub_f32_e32 v18, v32, v4
	v_mul_f32_e32 v18, 0x3fb8aa3b, v18
	v_exp_f32_e32 v32, v18
	v_sub_f32_e32 v18, v31, v4
	v_mul_f32_e32 v18, 0x3fb8aa3b, v18
	v_exp_f32_e32 v31, v18
	v_sub_f32_e32 v18, v30, v4
	v_mul_f32_e32 v18, 0x3fb8aa3b, v18
	v_exp_f32_e32 v30, v18
	v_sub_f32_e32 v18, v37, v4
	v_mul_f32_e32 v18, 0x3fb8aa3b, v18
	v_exp_f32_e32 v33, v18
	v_sub_f32_e32 v18, v36, v4
	v_mul_f32_e32 v18, 0x3fb8aa3b, v18
	v_mul_f32_e32 v5, 0x3fb8aa3b, v5
	v_sub_f32_e32 v7, v12, v4
	v_exp_f32_e32 v36, v18
	v_sub_f32_e32 v18, v35, v4
	v_exp_f32_e32 v5, v5
	v_mul_f32_e32 v7, 0x3fb8aa3b, v7
	v_sub_f32_e32 v9, v13, v4
	v_mul_f32_e32 v18, 0x3fb8aa3b, v18
	v_exp_f32_e32 v7, v7
	v_mul_f32_e32 v9, 0x3fb8aa3b, v9
	v_sub_f32_e32 v10, v14, v4
	v_exp_f32_e32 v35, v18
	v_sub_f32_e32 v18, v34, v4
	v_exp_f32_e32 v9, v9
	v_mul_f32_e32 v10, 0x3fb8aa3b, v10
	v_mul_f32_e32 v18, 0x3fb8aa3b, v18
	v_exp_f32_e32 v10, v10
	v_mul_f32_e32 v11, 0x3fb8aa3b, v11
	v_sub_f32_e32 v12, v19, v4
	v_exp_f32_e32 v34, v18
	v_sub_f32_e32 v18, v41, v4
	v_add_f32_e32 v6, 0, v5
	v_exp_f32_e32 v11, v11
	v_mul_f32_e32 v12, 0x3fb8aa3b, v12
	v_sub_f32_e32 v13, v21, v4
	v_mul_f32_e32 v18, 0x3fb8aa3b, v18
	v_add_f32_e32 v6, v7, v6
	v_exp_f32_e32 v12, v12
	v_mul_f32_e32 v13, 0x3fb8aa3b, v13
	v_sub_f32_e32 v14, v20, v4
	v_exp_f32_e32 v37, v18
	v_sub_f32_e32 v18, v40, v4
	v_add_f32_e32 v6, v9, v6
	v_exp_f32_e32 v13, v13
	v_mul_f32_e32 v14, 0x3fb8aa3b, v14
	v_mul_f32_e32 v18, 0x3fb8aa3b, v18
	v_add_f32_e32 v6, v10, v6
	v_exp_f32_e32 v14, v14
	v_mul_f32_e32 v15, 0x3fb8aa3b, v15
	v_exp_f32_e32 v40, v18
	v_sub_f32_e32 v18, v39, v4
	v_add_f32_e32 v6, v11, v6
	v_exp_f32_e32 v15, v15
	v_mul_f32_e32 v18, 0x3fb8aa3b, v18
	v_add_f32_e32 v6, v12, v6
	v_exp_f32_e32 v39, v18
	v_sub_f32_e32 v18, v38, v4
	v_add_f32_e32 v6, v13, v6
	v_mul_f32_e32 v18, 0x3fb8aa3b, v18
	v_add_f32_e32 v6, v14, v6
	v_exp_f32_e32 v38, v18
	v_sub_f32_e32 v18, v45, v4
	v_add_f32_e32 v6, v15, v6
	v_mul_f32_e32 v18, 0x3fb8aa3b, v18
	v_add_f32_e32 v6, v28, v6
	v_exp_f32_e32 v41, v18
	v_sub_f32_e32 v18, v44, v4
	v_add_f32_e32 v6, v27, v6
	v_mul_f32_e32 v18, 0x3fb8aa3b, v18
	v_add_f32_e32 v6, v25, v6
	v_exp_f32_e32 v44, v18
	v_sub_f32_e32 v18, v43, v4
	v_add_f32_e32 v6, v29, v6
	v_mul_f32_e32 v18, 0x3fb8aa3b, v18
	v_add_f32_e32 v6, v32, v6
	v_exp_f32_e32 v43, v18
	v_sub_f32_e32 v18, v42, v4
	v_add_f32_e32 v6, v31, v6
	v_mul_f32_e32 v18, 0x3fb8aa3b, v18
	v_add_f32_e32 v6, v30, v6
	v_exp_f32_e32 v42, v18
	v_sub_f32_e32 v18, v55, v4
	v_add_f32_e32 v6, v33, v6
	v_mul_f32_e32 v18, 0x3fb8aa3b, v18
	v_add_f32_e32 v6, v36, v6
	v_exp_f32_e32 v45, v18
	v_sub_f32_e32 v18, v56, v4
	v_add_f32_e32 v6, v35, v6
	v_mul_f32_e32 v18, 0x3fb8aa3b, v18
	v_add_f32_e32 v6, v34, v6
	v_exp_f32_e32 v46, v18
	v_sub_f32_e32 v18, v57, v4
	v_add_f32_e32 v6, v37, v6
	v_mul_f32_e32 v18, 0x3fb8aa3b, v18
	v_add_f32_e32 v6, v40, v6
	v_exp_f32_e32 v47, v18
	v_sub_f32_e32 v18, v58, v4
	v_add_f32_e32 v6, v39, v6
	v_mul_f32_e32 v18, 0x3fb8aa3b, v18
	v_add_f32_e32 v6, v38, v6
	v_exp_f32_e32 v48, v18
	v_sub_f32_e32 v18, v50, v4
	v_add_f32_e32 v6, v41, v6
	v_mul_f32_e32 v18, 0x3fb8aa3b, v18
	v_add_f32_e32 v6, v44, v6
	v_exp_f32_e32 v49, v18
	v_sub_f32_e32 v18, v51, v4
	v_add_f32_e32 v6, v43, v6
	v_mul_f32_e32 v18, 0x3fb8aa3b, v18
	v_add_f32_e32 v6, v42, v6
	v_exp_f32_e32 v50, v18
	v_sub_f32_e32 v18, v52, v4
	v_add_f32_e32 v6, v45, v6
	v_mul_f32_e32 v18, 0x3fb8aa3b, v18
	v_add_f32_e32 v6, v46, v6
	v_exp_f32_e32 v51, v18
	v_sub_f32_e32 v18, v53, v4
	v_sub_f32_e32 v1, v1, v4
	v_add_f32_e32 v6, v47, v6
	v_mul_f32_e32 v18, 0x3fb8aa3b, v18
	v_sub_f32_e32 v0, v0, v4
	v_mul_f32_e32 v1, 0x3fb8aa3b, v1
	v_add_f32_e32 v6, v48, v6
	v_exp_f32_e32 v52, v18
	v_mul_f32_e32 v0, 0x3fb8aa3b, v0
	v_exp_f32_e32 v54, v1
	v_sub_f32_e32 v1, v2, v4
	v_add_f32_e32 v6, v49, v6
	v_exp_f32_e32 v53, v0
	v_mul_f32_e32 v1, 0x3fb8aa3b, v1
	v_add_f32_e32 v6, v50, v6
	v_exp_f32_e32 v55, v1
	v_sub_f32_e32 v1, v3, v4
	v_add_f32_e32 v6, v51, v6
	v_mul_f32_e32 v1, 0x3fb8aa3b, v1
	v_add_f32_e32 v6, v52, v6
	v_exp_f32_e32 v3, v1
	v_add_f32_e32 v0, v53, v6
	v_add_f32_e32 v0, v54, v0
	v_add_f32_e32 v0, v55, v0
	v_add_f32_e32 v0, v3, v0
	ds_bpermute_b32 v1, v108, v0
	v_cvt_pk_bf16_f32 v18, v5, v7
	v_cvt_pk_bf16_f32 v19, v9, v10
	v_cvt_pk_bf16_f32 v20, v11, v12
	v_cvt_pk_bf16_f32 v21, v13, v14
	s_waitcnt lgkmcnt(0)
	v_add_f32_e32 v0, v0, v1
	ds_bpermute_b32 v1, v109, v0
	v_cvt_pk_bf16_f32 v12, v15, v28
	v_cvt_pk_bf16_f32 v13, v27, v25
	v_cvt_pk_bf16_f32 v14, v29, v32
	v_cvt_pk_bf16_f32 v15, v31, v30
	s_waitcnt lgkmcnt(0)
; #define LAS __attribute__((address_space(3)))
; __device__ __forceinline__ unsigned pk2(float lo, float hi) { return pg8::cvt_pk_bf16(lo, hi); }
; __device__ __forceinline__ bf16x8 pack8(const float (&o)[8]) { v4u w; w.x = pk2(o[0], o[1]); w.y = pk2(o[2], o[3]); w.z = pk2(o[4], o[5]); w.w = pk2(o[6], o[7]); return __builtin_bit_cast(bf16x8, w); }
; __device__ __forceinline__ v2u vtr(const LAS bf16* p) { return __builtin_bit_cast(v2u, __builtin_amdgcn_ds_read_tr16_b64_v4i16((LAS v4i16_t*)p)); }
; template <bool SAMPLE>
; __device__ __forceinline__ void swa_unit(const Params& p, LAS unsigned char* lds, int unit, int tid, int wave, int lane) {
;     ...
;             den += __shfl_xor(den, 16); den += __shfl_xor(den, 32);
;             den += __expf(sink - mx);
;             const float rden = 1.f / den;
;             bf16x8 pf[5];
; #pragma unroll
;             for (int cc = 0; cc < 5; ++cc) { float t8[8];
; #pragma unroll
;                 for (int e = 0; e < 4; ++e) { t8[e] = S[cc][0][e]; t8[4 + e] = S[cc][1][e]; }
;                 pf[cc] = pack8(t8); }
; #pragma unroll
;             for (int dt = 0; dt < 4; ++dt) { f32x4 o = (f32x4){0.f, 0.f, 0.f, 0.f};
; #pragma unroll
;                 for (int cc = 0; cc < 5; ++cc) { const LAS bf16* vp = Vt + (32 * (c0 + cc) + 4 * kq + (q16 >> 2)) * SWA_VS + 16 * dt + 4 * (q16 & 3);
;                     const v2u lo = vtr(vp), hi = vtr(vp + 16 * SWA_VS);
;                     v4u av; av.x = lo.x; av.y = lo.y; av.z = hi.x; av.w = hi.y;
;                     o = __builtin_amdgcn_mfma_f32_16x16x32_bf16(__builtin_bit_cast(bf16x8, av), pf[cc], o, 0, 0, 0); }
;                 v2u w; w.x = pk2(o[0] * rden, o[1] * rden); w.y = pk2(o[2] * rden, o[3] * rden);
;                 *(v2u*)(AO + row * 1024 + h * 64 + 16 * dt + 4 * kq) = w; }
;         }
;     }
;     __syncthreads();
	v_add_f32_e32 v0, v0, v1
	v_sub_f32_e32 v1, v8, v4
	v_mul_f32_e32 v1, 0x3fb8aa3b, v1
	v_exp_f32_e32 v1, v1
	v_cvt_pk_bf16_f32 v8, v33, v36
	v_cvt_pk_bf16_f32 v9, v35, v34
	v_cvt_pk_bf16_f32 v10, v37, v40
	v_cvt_pk_bf16_f32 v11, v39, v38
	v_cvt_pk_bf16_f32 v4, v41, v44
	s_nop 0
	v_add_f32_e32 v56, v1, v0
	v_div_scale_f32 v25, s[0:1], v56, v56, 1.0
	v_rcp_f32_e32 v27, v25
	v_cvt_pk_bf16_f32 v5, v43, v42
	v_cvt_pk_bf16_f32 v6, v45, v46
	v_cvt_pk_bf16_f32 v7, v47, v48
	v_cvt_pk_bf16_f32 v0, v49, v50
	v_cvt_pk_bf16_f32 v1, v51, v52
	s_nop 0
	v_fma_f32 v28, -v25, v27, 1.0
	v_fmac_f32_e32 v27, v28, v27
	v_div_scale_f32 v28, vcc, 1.0, v56, 1.0
	v_mul_f32_e32 v29, v28, v27
	v_fma_f32 v30, -v25, v29, v28
	v_fmac_f32_e32 v29, v30, v27
	v_fma_f32 v25, -v25, v29, v28
	v_div_fmas_f32 v25, v25, v27, v29
	v_div_fixup_f32 v32, v25, v56, 1.0
	v_lshrrev_b32_e32 v25, 2, v17
	v_add_u32_e32 v28, v25, v26
	v_lshlrev_b32_e32 v17, 3, v17
	v_ashrrev_i32_e32 v25, 31, v24
	v_and_b32_e32 v17, 24, v17
	v_lshl_add_u64 v[22:23], v[24:25], 1, v[22:23]
	v_mul_lo_u32 v24, v28, s8
	v_ashrrev_i32_e32 v27, 31, v26
	v_add3_u32 v17, 0, v17, v24
	ds_read_b64_tr_b16 v[116:117], v17 offset:36864
	ds_read_b64_tr_b16 v[118:119], v17 offset:39168
	ds_read_b64_tr_b16 v[120:121], v17 offset:41472
	ds_read_b64_tr_b16 v[122:123], v17 offset:43776
	ds_read_b64_tr_b16 v[124:125], v17 offset:46080
	ds_read_b64_tr_b16 v[126:127], v17 offset:48384
	ds_read_b64_tr_b16 v[128:129], v17 offset:50688
	ds_read_b64_tr_b16 v[130:131], v17 offset:52992
	ds_read_b64_tr_b16 v[132:133], v17 offset:55296
	ds_read_b64_tr_b16 v[134:135], v17 offset:57600
	v_cvt_pk_bf16_f32 v2, v53, v54
	v_cvt_pk_bf16_f32 v3, v55, v3
	v_lshl_add_u64 v[22:23], v[26:27], 1, v[22:23]
	s_nop 3
	s_waitcnt lgkmcnt(8)
	ds_read_b64_tr_b16 v[136:137], v17 offset:36896
	ds_read_b64_tr_b16 v[138:139], v17 offset:39200
	ds_read_b64_tr_b16 v[140:141], v17 offset:41504
	ds_read_b64_tr_b16 v[142:143], v17 offset:43808
	ds_read_b64_tr_b16 v[144:145], v17 offset:46112
	ds_read_b64_tr_b16 v[146:147], v17 offset:48416
	ds_read_b64_tr_b16 v[148:149], v17 offset:50720
	ds_read_b64_tr_b16 v[150:151], v17 offset:53024
	ds_read_b64_tr_b16 v[156:157], v17 offset:55328
	ds_read_b64_tr_b16 v[158:159], v17 offset:57632
	v_mfma_f32_16x16x32_bf16 v[24:27], v[116:119], v[18:21], 0
	s_waitcnt lgkmcnt(15)
	v_mfma_f32_16x16x32_bf16 v[24:27], v[120:123], v[12:15], v[24:27]
	s_nop 1
	s_waitcnt lgkmcnt(14)
	v_mfma_f32_16x16x32_bf16 v[24:27], v[124:127], v[8:11], v[24:27]
	s_nop 1
	s_waitcnt lgkmcnt(12)
	v_mfma_f32_16x16x32_bf16 v[24:27], v[128:131], v[4:7], v[24:27]
	s_nop 1
	s_waitcnt lgkmcnt(10)
	v_mfma_f32_16x16x32_bf16 v[24:27], v[132:135], v[0:3], v[24:27]
	s_nop 7
	v_mul_f32_e32 v24, v24, v32
	v_mul_f32_e32 v25, v25, v32
	v_cvt_pk_bf16_f32 v24, v24, v25
	v_mul_f32_e32 v25, v26, v32
	v_mul_f32_e32 v26, v27, v32
	v_cvt_pk_bf16_f32 v25, v25, v26
	global_store_dwordx2 v[22:23], v[24:25], off
	s_nop 3
	s_waitcnt lgkmcnt(8)
	ds_read_b64_tr_b16 v[116:117], v17 offset:36928
	ds_read_b64_tr_b16 v[118:119], v17 offset:39232
	ds_read_b64_tr_b16 v[120:121], v17 offset:41536
	ds_read_b64_tr_b16 v[122:123], v17 offset:43840
	ds_read_b64_tr_b16 v[124:125], v17 offset:46144
	ds_read_b64_tr_b16 v[126:127], v17 offset:48448
	ds_read_b64_tr_b16 v[128:129], v17 offset:50752
	ds_read_b64_tr_b16 v[130:131], v17 offset:53056
	ds_read_b64_tr_b16 v[132:133], v17 offset:36960
	ds_read_b64_tr_b16 v[134:135], v17 offset:39264
	v_mfma_f32_16x16x32_bf16 v[24:27], v[136:139], v[18:21], 0
	s_waitcnt lgkmcnt(15)
	v_mfma_f32_16x16x32_bf16 v[24:27], v[140:143], v[12:15], v[24:27]
	s_nop 1
	s_waitcnt lgkmcnt(14)
	v_mfma_f32_16x16x32_bf16 v[24:27], v[144:147], v[8:11], v[24:27]
	s_nop 1
	s_waitcnt lgkmcnt(12)
	v_mfma_f32_16x16x32_bf16 v[24:27], v[148:151], v[4:7], v[24:27]
	s_nop 1
	s_waitcnt lgkmcnt(10)
	v_mfma_f32_16x16x32_bf16 v[24:27], v[156:159], v[0:3], v[24:27]
	s_nop 7
	v_mul_f32_e32 v24, v32, v24
	v_mul_f32_e32 v25, v32, v25
	v_cvt_pk_bf16_f32 v24, v24, v25
	v_mul_f32_e32 v25, v32, v26
	v_mul_f32_e32 v26, v32, v27
	v_cvt_pk_bf16_f32 v25, v25, v26
	global_store_dwordx2 v[22:23], v[24:25], off offset:32
	s_nop 3
	s_waitcnt lgkmcnt(8)
	v_mfma_f32_16x16x32_bf16 v[24:27], v[116:119], v[18:21], 0
	s_waitcnt lgkmcnt(6)
	v_mfma_f32_16x16x32_bf16 v[24:27], v[120:123], v[12:15], v[24:27]
	s_nop 1
	s_waitcnt lgkmcnt(4)
	v_mfma_f32_16x16x32_bf16 v[24:27], v[124:127], v[8:11], v[24:27]
	s_nop 1
	s_waitcnt lgkmcnt(2)
	v_mfma_f32_16x16x32_bf16 v[24:27], v[128:131], v[4:7], v[24:27]
	ds_read_b64_tr_b16 v[28:29], v17 offset:55360
	ds_read_b64_tr_b16 v[30:31], v17 offset:57664
	s_waitcnt lgkmcnt(0)
	v_mfma_f32_16x16x32_bf16 v[24:27], v[28:31], v[0:3], v[24:27]
	s_nop 7
	v_mul_f32_e32 v24, v32, v24
	v_mul_f32_e32 v25, v32, v25
	v_cvt_pk_bf16_f32 v24, v24, v25
	v_mul_f32_e32 v25, v32, v26
	v_mul_f32_e32 v26, v32, v27
	v_cvt_pk_bf16_f32 v25, v25, v26
	global_store_dwordx2 v[22:23], v[24:25], off offset:64
	s_nop 2
	v_mfma_f32_16x16x32_bf16 v[18:21], v[132:135], v[18:21], 0
	ds_read_b64_tr_b16 v[24:25], v17 offset:41568
	ds_read_b64_tr_b16 v[26:27], v17 offset:43872
	s_waitcnt lgkmcnt(0)
	v_mfma_f32_16x16x32_bf16 v[12:15], v[24:27], v[12:15], v[18:21]
	s_nop 3
	ds_read_b64_tr_b16 v[18:19], v17 offset:46176
	ds_read_b64_tr_b16 v[20:21], v17 offset:48480
	s_waitcnt lgkmcnt(0)
	v_mfma_f32_16x16x32_bf16 v[8:11], v[18:21], v[8:11], v[12:15]
	s_nop 2
	ds_read_b64_tr_b16 v[12:13], v17 offset:50784
	ds_read_b64_tr_b16 v[14:15], v17 offset:53088
	s_waitcnt lgkmcnt(0)
	v_mfma_f32_16x16x32_bf16 v[4:7], v[12:15], v[4:7], v[8:11]
	s_nop 2
	ds_read_b64_tr_b16 v[8:9], v17 offset:55392
	ds_read_b64_tr_b16 v[10:11], v17 offset:57696
	s_waitcnt lgkmcnt(0)
	v_mfma_f32_16x16x32_bf16 v[0:3], v[8:11], v[0:3], v[4:7]
	s_nop 7
	v_mul_f32_e32 v0, v32, v0
	v_mul_f32_e32 v1, v32, v1
	v_cvt_pk_bf16_f32 v0, v0, v1
	v_mul_f32_e32 v1, v32, v2
	v_mul_f32_e32 v2, v32, v3
	v_cvt_pk_bf16_f32 v1, v1, v2
	global_store_dwordx2 v[22:23], v[0:1], off offset:96
.LBB0_2175:
	s_nop 0
	s_nop 0
	s_nop 0
	s_nop 0
	s_nop 0
	s_nop 0
	s_nop 0
	s_mov_b32 s0, 32
	s_mov_b64 s[36:37], 0
	s_and_b64 vcc, exec, s[34:35]
	s_barrier
	s_cbranch_vccnz .LBB0_2421

; #define LAS __attribute__((address_space(3)))
; template <bool SAMPLE>
; __device__ __forceinline__ void mem_unit(const Params& p, int l, LAS unsigned char* lds, int unit, int tid, int wave, int lane) {
;     ...
;             for (int it = 0; it < 4; ++it) { const int s = (tid >> 4) + 32 * (4 * hb + it);
;                 const float* kp; const float* vp;
;                 if (!SAMPLE) { kp = (const float*)(p.ws + W_MKV) + ((size_t)l * 1024 + b * 256 + s) * 1024 + h * 128 + sub * 8; vp = kp + 512; }
;                 else { const size_t o = ((((size_t)l * 128 + b) * 256 + s) * 4 + h) * 128 + sub * 8; kp = p.in[I_CMK] + o; vp = p.in[I_CMV] + o; }
;                 if (SAMPLE) { pg8::ld8f_nt(kp, kk[it]); pg8::ld8f_nt(vp, vv[it]); } else { pg8::ld8f(kp, kk[it]); pg8::ld8f(vp, vv[it]); } }
; #pragma unroll
;             for (int it = 0; it < 4; ++it) { const int s = (tid >> 4) + 32 * (4 * hb + it);
;                 float (&k)[8] = kk[it]; float (&v)[8] = vv[it];
;                 if (!SAMPLE) { float ss = 0.f;
; #pragma unroll
;                     for (int e = 0; e < 8; ++e) ss += k[e] * k[e];
;                     ss += __shfl_xor(ss, 1); ss += __shfl_xor(ss, 2); ss += __shfl_xor(ss, 4); ss += __shfl_xor(ss, 8);
;                     const float rs = rsqrtf(ss * (1.f / 128.f) + EPS);
; #pragma unroll
;                     for (int e = 0; e < 8; ++e) k[e] *= rs * kg[e];
;                     if (qt == 0) { const size_t o = ((((size_t)l * 4 + b) * 256 + s) * 4 + h) * 128 + sub * 8;
;                         *(f32x4*)(p.out + O_MKP + o) = (f32x4){k[0], k[1], k[2], k[3]}; *(f32x4*)(p.out + O_MKP + o + 4) = (f32x4){k[4], k[5], k[6], k[7]};
;                         *(f32x4*)(p.out + O_MVP + o) = (f32x4){v[0], v[1], v[2], v[3]}; *(f32x4*)(p.out + O_MVP + o + 4) = (f32x4){v[4], v[5], v[6], v[7]}; }
;                 }
;                 *(LAS bf16x8*)(Kl + s * MEM_KS + sub * 8) = pack8(k);
;                 *(LAS bf16x8*)(Vt + s * MEM_VS + sub * 8) = pack8(v);
;     ...
;         int q16 = lane & 15, kq = lane >> 4; asm volatile("" : "+v"(q16), "+v"(kq));
;         size_t row; bool st;
;         if (!SAMPLE) { row = (size_t)b * 8192 + (qt * 4 + qq) * 128 + 16 * wave + q16; st = true; } else { row = (size_t)MP + 8 * b + (q16 & 7); st = q16 < 8; }
;         bf16x8 qf[4];
;         {
;             float qv[4][8]; float ss = 0.f;
; #pragma unroll
.LBB0_2730:
	v_add_u32_e32 v66, s8, v81
	v_ashrrev_i32_e32 v67, 31, v66
	v_add_u32_e32 v6, 0x60, v66
	v_lshl_add_u64 v[8:9], v[66:67], 0, s[10:11]
	v_add_u32_e32 v2, 32, v66
	v_add_u32_e32 v4, 64, v66
	v_ashrrev_i32_e32 v7, 31, v6
	v_lshlrev_b64 v[8:9], 11, v[8:9]
	v_ashrrev_i32_e32 v3, 31, v2
	v_ashrrev_i32_e32 v5, 31, v4
	v_lshl_add_u64 v[6:7], v[6:7], 0, s[10:11]
	v_or_b32_e32 v8, v8, v0
	v_lshl_add_u64 v[2:3], v[2:3], 0, s[10:11]
	v_lshl_add_u64 v[4:5], v[4:5], 0, s[10:11]
	v_lshlrev_b64 v[22:23], 11, v[6:7]
	v_lshl_add_u64 v[6:7], s[78:79], 0, v[8:9]
	v_lshl_add_u64 v[14:15], s[80:81], 0, v[8:9]
	v_lshlrev_b64 v[18:19], 11, v[2:3]
	v_lshlrev_b64 v[20:21], 11, v[4:5]
	global_load_dwordx4 v[2:5], v[6:7], off nt
	s_nop 0
	global_load_dwordx4 v[6:9], v[6:7], off offset:16 nt
	s_nop 0
	global_load_dwordx4 v[10:13], v[14:15], off offset:16 nt
	s_nop 0
	global_load_dwordx4 v[14:17], v[14:15], off nt
	v_or_b32_e32 v18, v18, v0
	v_or_b32_e32 v20, v20, v0
	v_or_b32_e32 v22, v22, v0
	v_lshl_add_u64 v[24:25], s[78:79], 0, v[18:19]
	v_lshl_add_u64 v[30:31], s[80:81], 0, v[18:19]
	v_lshl_add_u64 v[38:39], s[78:79], 0, v[20:21]
	v_lshl_add_u64 v[46:47], s[80:81], 0, v[20:21]
	v_lshl_add_u64 v[54:55], s[78:79], 0, v[22:23]
	v_lshl_add_u64 v[62:63], s[80:81], 0, v[22:23]
	global_load_dwordx4 v[18:21], v[24:25], off nt
	s_nop 0
	global_load_dwordx4 v[22:25], v[24:25], off offset:16 nt
	s_nop 0
	global_load_dwordx4 v[26:29], v[30:31], off nt
	s_nop 0
	global_load_dwordx4 v[30:33], v[30:31], off offset:16 nt
	s_nop 0
	global_load_dwordx4 v[34:37], v[38:39], off nt
	s_nop 0
	global_load_dwordx4 v[38:41], v[38:39], off offset:16 nt
	s_nop 0
	global_load_dwordx4 v[42:45], v[46:47], off nt
	s_nop 0
	global_load_dwordx4 v[46:49], v[46:47], off offset:16 nt
	s_nop 0
	global_load_dwordx4 v[50:53], v[54:55], off nt
	s_nop 0
	global_load_dwordx4 v[54:57], v[54:55], off offset:16 nt
	s_nop 0
	global_load_dwordx4 v[58:61], v[62:63], off nt
	s_nop 0
	global_load_dwordx4 v[62:65], v[62:63], off offset:16 nt
	v_cndmask_b32_e64 v1, 0, 1, s[0:1]
	v_cmp_ne_u32_e32 vcc, 1, v1
	v_mul_lo_u32 v1, v66, s22
	v_add_u32_e32 v66, v96, v1
	v_add_u32_e32 v1, v97, v1
	s_movk_i32 s8, 0x80
	s_mov_b64 s[0:1], 0
	s_and_b64 vcc, exec, vcc
	s_waitcnt vmcnt(15)
	v_cvt_pk_bf16_f32 v2, v2, v3
	v_cvt_pk_bf16_f32 v3, v4, v5
	s_waitcnt vmcnt(14)
	v_cvt_pk_bf16_f32 v4, v6, v7
	v_cvt_pk_bf16_f32 v5, v8, v9
	ds_write_b128 v66, v[2:5]
	s_waitcnt vmcnt(12)
	v_cvt_pk_bf16_f32 v2, v14, v15
	v_cvt_pk_bf16_f32 v3, v16, v17
	v_cvt_pk_bf16_f32 v4, v10, v11
	v_cvt_pk_bf16_f32 v5, v12, v13
	ds_write_b128 v1, v[2:5]
	s_waitcnt vmcnt(11)
	v_cvt_pk_bf16_f32 v2, v18, v19
	v_cvt_pk_bf16_f32 v3, v20, v21
	s_waitcnt vmcnt(10)
	v_cvt_pk_bf16_f32 v4, v22, v23
	v_cvt_pk_bf16_f32 v5, v24, v25
	ds_write_b128 v66, v[2:5] offset:8704
	s_waitcnt vmcnt(9)
	v_cvt_pk_bf16_f32 v2, v26, v27
	v_cvt_pk_bf16_f32 v3, v28, v29
	s_waitcnt vmcnt(8)
	v_cvt_pk_bf16_f32 v4, v30, v31
	v_cvt_pk_bf16_f32 v5, v32, v33
	ds_write_b128 v1, v[2:5] offset:8704
	s_waitcnt vmcnt(7)
	v_cvt_pk_bf16_f32 v2, v34, v35
	v_cvt_pk_bf16_f32 v3, v36, v37
	s_waitcnt vmcnt(6)
	v_cvt_pk_bf16_f32 v4, v38, v39
	v_cvt_pk_bf16_f32 v5, v40, v41
	ds_write_b128 v66, v[2:5] offset:17408
	s_waitcnt vmcnt(5)
	v_cvt_pk_bf16_f32 v2, v42, v43
	v_cvt_pk_bf16_f32 v3, v44, v45
	s_waitcnt vmcnt(4)
	v_cvt_pk_bf16_f32 v4, v46, v47
	v_cvt_pk_bf16_f32 v5, v48, v49
	ds_write_b128 v1, v[2:5] offset:17408
	s_waitcnt vmcnt(3)
	v_cvt_pk_bf16_f32 v2, v50, v51
	v_cvt_pk_bf16_f32 v3, v52, v53
	s_waitcnt vmcnt(2)
	v_cvt_pk_bf16_f32 v4, v54, v55
	v_cvt_pk_bf16_f32 v5, v56, v57
	ds_write_b128 v66, v[2:5] offset:26112
	s_waitcnt vmcnt(1)
	v_cvt_pk_bf16_f32 v2, v58, v59
	v_cvt_pk_bf16_f32 v3, v60, v61
	s_waitcnt vmcnt(0)
	v_cvt_pk_bf16_f32 v4, v62, v63
	v_cvt_pk_bf16_f32 v5, v64, v65
	ds_write_b128 v1, v[2:5] offset:26112
	s_cbranch_vccz .LBB0_2730
	s_andn2_b64 vcc, exec, s[6:7]
	s_waitcnt lgkmcnt(0)
	s_barrier
	s_cbranch_vccnz .LBB0_2749
	s_lshl_b32 s0, s2, 3
	s_add_i32 s1, s0, 0x8000
	s_lshl_b32 s0, s3, 1
	v_mov_b32_e32 v37, v95
	v_mov_b32_e32 v36, v94
	s_add_u32 s2, s64, s0
	s_addc_u32 s3, s65, 0
	v_and_or_b32 v0, v36, 7, s1
	v_lshlrev_b32_e32 v82, 10, v0
	v_lshlrev_b32_e32 v16, 3, v37
	v_lshl_add_u64 v[0:1], s[2:3], 0, v[82:83]
	v_ashrrev_i32_e32 v17, 31, v16
	v_lshl_add_u64 v[12:13], v[16:17], 1, v[0:1]
	global_load_dwordx4 v[0:3], v[12:13], off
	global_load_dwordx4 v[4:7], v[12:13], off offset:64
	global_load_dwordx4 v[8:11], v[12:13], off offset:128
	s_nop 0
	global_load_dwordx4 v[12:15], v[12:13], off offset:192
	v_and_b32_e32 v19, 64, v99
	v_xor_b32_e32 v18, 16, v99
	v_add_u32_e32 v34, 64, v19
	v_cmp_lt_i32_e32 vcc, v18, v34
	v_lshl_add_u64 v[24:25], v[16:17], 2, s[46:47]
	s_waitcnt vmcnt(3)
	v_and_b32_e32 v40, 0xffff0000, v0
	v_cndmask_b32_e32 v18, v99, v18, vcc
	v_lshlrev_b32_e32 v38, 2, v18
	global_load_dwordx4 v[16:19], v[24:25], off offset:528
	global_load_dwordx4 v[20:23], v[24:25], off offset:512
	v_lshlrev_b32_e32 v35, 16, v0
	s_waitcnt vmcnt(3)
; __device__ __forceinline__ void unpack8(const v4u w, float (&o)[8]) { o[0] = bflo(w.x); o[1] = bfhi(w.x); o[2] = bflo(w.y); o[3] = bfhi(w.y); o[4] = bflo(w.z); o[5] = bfhi(w.z); o[6] = bflo(w.w); o[7] = bfhi(w.w); }
; __device__ __forceinline__ bf16x8 pack8(const float (&o)[8]) { v4u w; w.x = pk2(o[0], o[1]); w.y = pk2(o[2], o[3]); w.z = pk2(o[4], o[5]); w.w = pk2(o[6], o[7]); return __builtin_bit_cast(bf16x8, w); }
; template <bool SAMPLE>
; __device__ __forceinline__ void mem_unit(const Params& p, int l, LAS unsigned char* lds, int unit, int tid, int wave, int lane) {
;     ...
;             float qv[4][8]; float ss = 0.f;
; #pragma unroll
;             for (int dc = 0; dc < 4; ++dc) { unpack8(*(const v4u*)(MQ + row * 512 + h * 128 + 32 * dc + 8 * kq), qv[dc]);
; #pragma unroll
;                 for (int e = 0; e < 8; ++e) ss += qv[dc][e] * qv[dc][e]; }
;             ss += __shfl_xor(ss, 16); ss += __shfl_xor(ss, 32);
;             const float rs = rsqrtf(ss * (1.f / 128.f) + EPS) * 0.08838834764831845f;
; #pragma unroll
;             for (int dc = 0; dc < 4; ++dc) { float qg[8]; pg8::ld8f(p.in[I_MQG] + l * 128 + 32 * dc + 8 * kq, qg);
; #pragma unroll
;                 for (int e = 0; e < 8; ++e) qv[dc][e] *= rs * qg[e];
;                 qf[dc] = pack8(qv[dc]); }
	v_lshlrev_b32_e32 v55, 16, v8
	v_and_b32_e32 v56, 0xffff0000, v8
	v_mul_f32_e32 v8, v40, v40
	v_lshlrev_b32_e32 v41, 16, v1
	v_fmac_f32_e32 v8, v35, v35
	v_and_b32_e32 v42, 0xffff0000, v1
	v_fmac_f32_e32 v8, v41, v41
	v_lshlrev_b32_e32 v43, 16, v2
	v_fmac_f32_e32 v8, v42, v42
	v_and_b32_e32 v44, 0xffff0000, v2
	v_fmac_f32_e32 v8, v43, v43
	v_lshlrev_b32_e32 v45, 16, v3
	v_fmac_f32_e32 v8, v44, v44
	v_and_b32_e32 v46, 0xffff0000, v3
	v_fmac_f32_e32 v8, v45, v45
	v_lshlrev_b32_e32 v47, 16, v4
	v_fmac_f32_e32 v8, v46, v46
	v_and_b32_e32 v48, 0xffff0000, v4
	v_fmac_f32_e32 v8, v47, v47
	v_lshlrev_b32_e32 v49, 16, v5
	v_fmac_f32_e32 v8, v48, v48
	v_and_b32_e32 v50, 0xffff0000, v5
	v_fmac_f32_e32 v8, v49, v49
	v_lshlrev_b32_e32 v51, 16, v6
	v_fmac_f32_e32 v8, v50, v50
	v_and_b32_e32 v52, 0xffff0000, v6
	v_fmac_f32_e32 v8, v51, v51
	v_lshlrev_b32_e32 v53, 16, v7
	v_fmac_f32_e32 v8, v52, v52
	v_and_b32_e32 v54, 0xffff0000, v7
	v_fmac_f32_e32 v8, v53, v53
	v_fmac_f32_e32 v8, v54, v54
	v_fmac_f32_e32 v8, v55, v55
	v_lshlrev_b32_e32 v57, 16, v9
	v_fmac_f32_e32 v8, v56, v56
	v_and_b32_e32 v58, 0xffff0000, v9
	v_fmac_f32_e32 v8, v57, v57
	v_lshlrev_b32_e32 v59, 16, v10
	v_fmac_f32_e32 v8, v58, v58
	v_and_b32_e32 v60, 0xffff0000, v10
	v_fmac_f32_e32 v8, v59, v59
	v_lshlrev_b32_e32 v61, 16, v11
	v_fmac_f32_e32 v8, v60, v60
	v_and_b32_e32 v62, 0xffff0000, v11
	s_waitcnt vmcnt(2)
	v_and_b32_e32 v26, 0xffff0000, v12
	v_lshlrev_b32_e32 v27, 16, v12
	v_fmac_f32_e32 v8, v61, v61
	v_pk_mul_f32 v[0:1], v[26:27], v[26:27]
	v_fmac_f32_e32 v8, v62, v62
	v_and_b32_e32 v28, 0xffff0000, v13
	v_lshlrev_b32_e32 v29, 16, v13
	v_add_f32_e32 v1, v1, v8
	v_pk_mul_f32 v[2:3], v[28:29], v[28:29]
	v_add_f32_e32 v0, v0, v1
	v_and_b32_e32 v30, 0xffff0000, v14
	v_lshlrev_b32_e32 v31, 16, v14
	v_add_f32_e32 v0, v3, v0
	v_pk_mul_f32 v[4:5], v[30:31], v[30:31]
	v_add_f32_e32 v0, v2, v0
	v_and_b32_e32 v32, 0xffff0000, v15
	v_lshlrev_b32_e32 v33, 16, v15
	v_add_f32_e32 v0, v5, v0
	v_pk_mul_f32 v[6:7], v[32:33], v[32:33]
	v_add_f32_e32 v0, v4, v0
	v_add_f32_e32 v0, v7, v0
	v_add_f32_e32 v0, v6, v0
	ds_bpermute_b32 v1, v38, v0
	v_xor_b32_e32 v2, 32, v99
	v_cmp_lt_i32_e32 vcc, v2, v34
	s_waitcnt lgkmcnt(0)
	v_add_f32_e32 v0, v0, v1
	v_cndmask_b32_e32 v2, v99, v2, vcc
	v_lshlrev_b32_e32 v39, 2, v2
	ds_bpermute_b32 v1, v39, v0
	s_waitcnt lgkmcnt(0)
	v_add_f32_e32 v0, v0, v1
	v_fmamk_f32 v0, v0, 0x3c000000, v98
	v_mul_f32_e32 v1, 0x4b800000, v0
	v_cmp_gt_f32_e32 vcc, s23, v0
	s_nop 1
	v_cndmask_b32_e32 v0, v0, v1, vcc
	v_rsq_f32_e32 v0, v0
	s_nop 0
	v_mul_f32_e32 v1, 0x45800000, v0
	v_cndmask_b32_e32 v0, v0, v1, vcc
	v_mul_f32_e32 v34, 0x3db504f3, v0
	s_waitcnt vmcnt(0)
	v_mul_f32_e32 v0, v20, v34
	v_mul_f32_e32 v1, v21, v34
	v_mul_f32_e32 v2, v22, v34
	v_mul_f32_e32 v3, v23, v34
	v_mul_f32_e32 v4, v16, v34
	v_mul_f32_e32 v5, v17, v34
	v_mul_f32_e32 v6, v18, v34
	v_mul_f32_e32 v7, v19, v34
	v_mul_f32_e32 v0, v0, v35
	v_mul_f32_e32 v1, v1, v40
	v_mul_f32_e32 v2, v2, v41
	v_mul_f32_e32 v3, v3, v42
	v_mul_f32_e32 v4, v4, v43
	v_mul_f32_e32 v5, v5, v44
	v_mul_f32_e32 v6, v6, v45
	v_mul_f32_e32 v7, v7, v46
	v_cvt_pk_bf16_f32 v0, v0, v1
	v_cvt_pk_bf16_f32 v1, v2, v3
	v_cvt_pk_bf16_f32 v2, v4, v5
	v_cvt_pk_bf16_f32 v3, v6, v7
	global_load_dwordx4 v[4:7], v[24:25], off offset:640
	global_load_dwordx4 v[8:11], v[24:25], off offset:656
	v_lshlrev_b32_e32 v20, 4, v37
	v_mul_lo_u32 v21, v36, s22
	v_add3_u32 v92, 0, v20, v21
	s_waitcnt vmcnt(1)
	v_mul_f32_e32 v4, v4, v34
	v_mul_f32_e32 v5, v5, v34
	v_mul_f32_e32 v6, v6, v34
	v_mul_f32_e32 v7, v7, v34
	s_waitcnt vmcnt(0)
	v_mul_f32_e32 v8, v8, v34
	v_mul_f32_e32 v9, v9, v34
	v_mul_f32_e32 v10, v10, v34
	v_mul_f32_e32 v11, v11, v34
	v_mul_f32_e32 v4, v4, v47
	v_mul_f32_e32 v5, v5, v48
	v_mul_f32_e32 v6, v6, v49
	v_mul_f32_e32 v7, v7, v50
	v_mul_f32_e32 v12, v8, v51
	v_mul_f32_e32 v13, v9, v52
	v_mul_f32_e32 v14, v10, v53
	v_mul_f32_e32 v11, v11, v54
	v_cvt_pk_bf16_f32 v8, v4, v5
	v_cvt_pk_bf16_f32 v9, v6, v7
	v_cvt_pk_bf16_f32 v10, v12, v13
	v_cvt_pk_bf16_f32 v11, v14, v11
	global_load_dwordx4 v[4:7], v[24:25], off offset:768
	global_load_dwordx4 v[12:15], v[24:25], off offset:784
	s_waitcnt vmcnt(1)
	v_mul_f32_e32 v4, v4, v34
	v_mul_f32_e32 v5, v5, v34
	v_mul_f32_e32 v6, v6, v34
	v_mul_f32_e32 v7, v7, v34
	s_waitcnt vmcnt(0)
	v_mul_f32_e32 v12, v12, v34
	v_mul_f32_e32 v13, v13, v34
	v_mul_f32_e32 v14, v14, v34
	v_mul_f32_e32 v15, v15, v34
	v_mul_f32_e32 v4, v4, v55
	v_mul_f32_e32 v5, v5, v56
	v_mul_f32_e32 v6, v6, v57
	v_mul_f32_e32 v7, v7, v58
	v_mul_f32_e32 v12, v12, v59
	v_mul_f32_e32 v13, v13, v60
	v_mul_f32_e32 v14, v14, v61
	v_mul_f32_e32 v15, v15, v62
	v_cvt_pk_bf16_f32 v4, v4, v5
	v_cvt_pk_bf16_f32 v5, v6, v7
	v_cvt_pk_bf16_f32 v6, v12, v13
	v_cvt_pk_bf16_f32 v7, v14, v15
	global_load_dwordx4 v[12:15], v[24:25], off offset:896
	global_load_dwordx4 v[16:19], v[24:25], off offset:912
	s_waitcnt vmcnt(1)
	v_mul_f32_e32 v12, v12, v34
	v_mul_f32_e32 v13, v13, v34
	v_mul_f32_e32 v14, v14, v34
	v_mul_f32_e32 v15, v15, v34
	s_waitcnt vmcnt(0)
; #define LAS __attribute__((address_space(3)))
; template <bool SAMPLE>
; __device__ __forceinline__ void mem_unit(const Params& p, int l, LAS unsigned char* lds, int unit, int tid, int wave, int lane) {
;     ...
;         f32x4 S[8][2]; float mx = -INFINITY;
; #pragma unroll
;         for (int cc = 0; cc < 8; ++cc)
; #pragma unroll
;             for (int tt = 0; tt < 2; ++tt) { const int kb = 32 * cc + 16 * tt; f32x4 a = (f32x4){0.f, 0.f, 0.f, 0.f};
; #pragma unroll
;                 for (int dc = 0; dc < 4; ++dc) { const bf16x8 kf = *(const LAS bf16x8*)(Kl + (kb + q16) * MEM_KS + 32 * dc + 8 * kq);
;                     a = __builtin_amdgcn_mfma_f32_16x16x32_bf16(kf, qf[dc], a, 0, 0, 0); }
; #pragma unroll
;                 for (int e = 0; e < 4; ++e) mx = fmaxf(mx, a[e]);
;                 S[cc][tt] = a; }
	v_mul_f32_e32 v16, v16, v34
	v_mul_f32_e32 v17, v17, v34
	v_mul_f32_e32 v18, v18, v34
	v_mul_f32_e32 v19, v19, v34
	v_mul_f32_e32 v12, v12, v27
	v_mul_f32_e32 v13, v13, v26
	v_mul_f32_e32 v14, v14, v29
	v_mul_f32_e32 v15, v15, v28
	v_mul_f32_e32 v16, v16, v31
	v_mul_f32_e32 v17, v17, v30
	v_mul_f32_e32 v18, v18, v33
	v_mul_f32_e32 v19, v19, v32
	v_cvt_pk_bf16_f32 v32, v12, v13
	v_cvt_pk_bf16_f32 v33, v14, v15
	v_cvt_pk_bf16_f32 v34, v16, v17
	v_cvt_pk_bf16_f32 v35, v18, v19
	ds_read_b128 v[186:189], v92
	ds_read_b128 v[190:193], v92 offset:4352
	ds_read_b128 v[194:197], v92 offset:8704
	ds_read_b128 v[198:201], v92 offset:13056
	ds_read_b128 v[202:205], v92 offset:17408
	ds_read_b128 v[206:209], v92 offset:21760
	ds_read_b128 v[210:213], v92 offset:26112
	s_nop 0
	ds_read_b128 v[16:19], v92 offset:64
	s_nop 0
	ds_read_b128 v[24:27], v92 offset:4416
	s_nop 0
	ds_read_b128 v[40:43], v92 offset:8768
	s_nop 0
	ds_read_b128 v[48:51], v92 offset:13120
	s_nop 0
	ds_read_b128 v[56:59], v92 offset:17472
	s_nop 0
	ds_read_b128 v[64:67], v92 offset:21824
	s_nop 0
	ds_read_b128 v[72:75], v92 offset:26176
	ds_read_b128 v[76:79], v92 offset:30464
	ds_read_b128 v[88:91], v92 offset:30528
	ds_read_b128 v[100:103], v92 offset:34816
	ds_read_b128 v[104:107], v92 offset:34880
	ds_read_b128 v[108:111], v92 offset:39168
	ds_read_b128 v[112:115], v92 offset:39232
	ds_read_b128 v[116:119], v92 offset:43520
	ds_read_b128 v[120:123], v92 offset:43584
	ds_read_b128 v[124:127], v92 offset:47872
	ds_read_b128 v[128:131], v92 offset:47936
	ds_read_b128 v[132:135], v92 offset:52224
	ds_read_b128 v[136:139], v92 offset:52288
	ds_read_b128 v[140:143], v92 offset:56576
	ds_read_b128 v[144:147], v92 offset:56640
	ds_read_b128 v[148:151], v92 offset:60928
	ds_read_b128 v[152:155], v92 offset:60992
	ds_read_b128 v[156:159], v92 offset:65280
	ds_read_b128 v[160:163], v92 offset:65344
	s_waitcnt lgkmcnt(14)
	v_mfma_f32_16x16x32_bf16 v[12:15], v[186:189], v[0:3], 0
	v_mfma_f32_16x16x32_bf16 v[20:23], v[190:193], v[0:3], 0
	v_mfma_f32_16x16x32_bf16 v[28:31], v[194:197], v[0:3], 0
	v_mfma_f32_16x16x32_bf16 v[44:47], v[198:201], v[0:3], 0
	v_mfma_f32_16x16x32_bf16 v[52:55], v[202:205], v[0:3], 0
	v_mfma_f32_16x16x32_bf16 v[60:63], v[206:209], v[0:3], 0
	v_mfma_f32_16x16x32_bf16 v[68:71], v[210:213], v[0:3], 0
	v_mfma_f32_16x16x32_bf16 v[76:79], v[76:79], v[0:3], 0
	v_mfma_f32_16x16x32_bf16 v[100:103], v[100:103], v[0:3], 0
	s_waitcnt lgkmcnt(13)
	v_mfma_f32_16x16x32_bf16 v[108:111], v[108:111], v[0:3], 0
	s_waitcnt lgkmcnt(11)
	v_mfma_f32_16x16x32_bf16 v[116:119], v[116:119], v[0:3], 0
	s_waitcnt lgkmcnt(9)
	v_mfma_f32_16x16x32_bf16 v[124:127], v[124:127], v[0:3], 0
	s_waitcnt lgkmcnt(7)
	v_mfma_f32_16x16x32_bf16 v[132:135], v[132:135], v[0:3], 0
	s_waitcnt lgkmcnt(5)
	v_mfma_f32_16x16x32_bf16 v[140:143], v[140:143], v[0:3], 0
	s_waitcnt lgkmcnt(3)
	v_mfma_f32_16x16x32_bf16 v[148:151], v[148:151], v[0:3], 0
	s_waitcnt lgkmcnt(1)
	v_mfma_f32_16x16x32_bf16 v[0:3], v[156:159], v[0:3], 0
	v_mfma_f32_16x16x32_bf16 v[12:15], v[16:19], v[8:11], v[12:15]
	v_mfma_f32_16x16x32_bf16 v[16:19], v[24:27], v[8:11], v[20:23]
	v_mfma_f32_16x16x32_bf16 v[20:23], v[40:43], v[8:11], v[28:31]
	v_mfma_f32_16x16x32_bf16 v[24:27], v[48:51], v[8:11], v[44:47]
	v_mfma_f32_16x16x32_bf16 v[28:31], v[56:59], v[8:11], v[52:55]
	ds_read_b128 v[198:201], v92 offset:128
	ds_read_b128 v[202:205], v92 offset:4480
	ds_read_b128 v[206:209], v92 offset:8832
	ds_read_b128 v[210:213], v92 offset:13184
	v_mfma_f32_16x16x32_bf16 v[40:43], v[64:67], v[8:11], v[60:63]
	v_mfma_f32_16x16x32_bf16 v[44:47], v[72:75], v[8:11], v[68:71]
	v_mfma_f32_16x16x32_bf16 v[48:51], v[88:91], v[8:11], v[76:79]
	v_mfma_f32_16x16x32_bf16 v[52:55], v[104:107], v[8:11], v[100:103]
	v_mfma_f32_16x16x32_bf16 v[56:59], v[112:115], v[8:11], v[108:111]
	v_mfma_f32_16x16x32_bf16 v[60:63], v[120:123], v[8:11], v[116:119]
	v_mfma_f32_16x16x32_bf16 v[64:67], v[128:131], v[8:11], v[124:127]
	ds_read_b128 v[218:221], v92 offset:17536
	ds_read_b128 v[222:225], v92 offset:21888
	ds_read_b128 v[226:229], v92 offset:26240
	ds_read_b128 v[230:233], v92 offset:30592
	ds_read_b128 v[234:237], v92 offset:34944
	ds_read_b128 v[242:245], v92 offset:39296
	ds_read_b128 v[246:249], v92 offset:43648
	v_mfma_f32_16x16x32_bf16 v[68:71], v[136:139], v[8:11], v[132:135]
	v_mfma_f32_16x16x32_bf16 v[72:75], v[144:147], v[8:11], v[140:143]
	v_mfma_f32_16x16x32_bf16 v[76:79], v[152:155], v[8:11], v[148:151]
	s_waitcnt lgkmcnt(11)
	v_mfma_f32_16x16x32_bf16 v[0:3], v[160:163], v[8:11], v[0:3]
	s_nop 0
	ds_read_b128 v[88:91], v92 offset:192
	s_waitcnt lgkmcnt(11)
	v_mfma_f32_16x16x32_bf16 v[8:11], v[198:201], v[4:7], v[12:15]
	s_nop 2
	s_nop 0
	ds_read_b128 v[100:103], v92 offset:4544
	s_waitcnt lgkmcnt(11)
	v_mfma_f32_16x16x32_bf16 v[12:15], v[202:205], v[4:7], v[16:19]
	s_nop 2
	s_nop 0
	ds_read_b128 v[104:107], v92 offset:8896
	s_waitcnt lgkmcnt(11)
	v_mfma_f32_16x16x32_bf16 v[16:19], v[206:209], v[4:7], v[20:23]
	s_nop 2
	s_nop 0
	ds_read_b128 v[108:111], v92 offset:13248
	s_waitcnt lgkmcnt(11)
	v_mfma_f32_16x16x32_bf16 v[20:23], v[210:213], v[4:7], v[24:27]
	s_nop 2
	s_nop 0
	ds_read_b128 v[112:115], v92 offset:17600
	s_waitcnt lgkmcnt(11)
	ds_read_b128 v[186:189], v92 offset:48000
	ds_read_b128 v[190:193], v92 offset:52352
	ds_read_b128 v[194:197], v92 offset:56704
	ds_read_b128 v[198:201], v92 offset:61056
	ds_read_b128 v[202:205], v92 offset:65408
	v_mfma_f32_16x16x32_bf16 v[24:27], v[218:221], v[4:7], v[28:31]
	s_nop 2
	s_nop 0
	ds_read_b128 v[116:119], v92 offset:21952
	s_waitcnt lgkmcnt(15)
; #define LAS __attribute__((address_space(3)))
; template <bool SAMPLE>
; __device__ __forceinline__ void mem_unit(const Params& p, int l, LAS unsigned char* lds, int unit, int tid, int wave, int lane) {
;     ...
;             for (int tt = 0; tt < 2; ++tt) { const int kb = 32 * cc + 16 * tt; f32x4 a = (f32x4){0.f, 0.f, 0.f, 0.f};
; #pragma unroll
;                 for (int dc = 0; dc < 4; ++dc) { const bf16x8 kf = *(const LAS bf16x8*)(Kl + (kb + q16) * MEM_KS + 32 * dc + 8 * kq);
;                     a = __builtin_amdgcn_mfma_f32_16x16x32_bf16(kf, qf[dc], a, 0, 0, 0); }
; #pragma unroll
;                 for (int e = 0; e < 4; ++e) mx = fmaxf(mx, a[e]);
;                 S[cc][tt] = a; }
;         mx = fmaxf(mx, __shfl_xor(mx, 16)); mx = fmaxf(mx, __shfl_xor(mx, 32));
;         float den = 0.f;
; #pragma unroll
;         for (int cc = 0; cc < 8; ++cc)
; #pragma unroll
;             for (int tt = 0; tt < 2; ++tt)
; #pragma unroll
;                 for (int e = 0; e < 4; ++e) { const float pe = __expf(S[cc][tt][e] - mx); S[cc][tt][e] = pe; den += pe; }
	v_mfma_f32_16x16x32_bf16 v[28:31], v[222:225], v[4:7], v[40:43]
	s_nop 2
	s_nop 0
	ds_read_b128 v[120:123], v92 offset:26304
	s_waitcnt lgkmcnt(15)
	v_mfma_f32_16x16x32_bf16 v[40:43], v[226:229], v[4:7], v[44:47]
	s_nop 2
	s_nop 0
	ds_read_b128 v[124:127], v92 offset:30656
	s_waitcnt lgkmcnt(15)
	v_mfma_f32_16x16x32_bf16 v[44:47], v[230:233], v[4:7], v[48:51]
	s_nop 2
	s_nop 0
	ds_read_b128 v[128:131], v92 offset:35008
	s_waitcnt lgkmcnt(15)
	v_mfma_f32_16x16x32_bf16 v[48:51], v[234:237], v[4:7], v[52:55]
	s_nop 2
	s_nop 0
	ds_read_b128 v[132:135], v92 offset:39360
	s_waitcnt lgkmcnt(15)
	v_mfma_f32_16x16x32_bf16 v[52:55], v[242:245], v[4:7], v[56:59]
	s_nop 2
	s_nop 0
	ds_read_b128 v[136:139], v92 offset:43712
	s_waitcnt lgkmcnt(15)
	v_mfma_f32_16x16x32_bf16 v[56:59], v[246:249], v[4:7], v[60:63]
	s_nop 2
	s_nop 0
	ds_read_b128 v[140:143], v92 offset:48064
	s_waitcnt lgkmcnt(11)
	v_mfma_f32_16x16x32_bf16 v[60:63], v[186:189], v[4:7], v[64:67]
	s_nop 2
	s_nop 0
	ds_read_b128 v[144:147], v92 offset:52416
	s_waitcnt lgkmcnt(11)
	v_mfma_f32_16x16x32_bf16 v[64:67], v[190:193], v[4:7], v[68:71]
	s_nop 2
	s_nop 0
	ds_read_b128 v[148:151], v92 offset:56768
	s_waitcnt lgkmcnt(11)
	v_mfma_f32_16x16x32_bf16 v[68:71], v[194:197], v[4:7], v[72:75]
	s_nop 2
	s_nop 0
	ds_read_b128 v[152:155], v92 offset:61120
	s_waitcnt lgkmcnt(11)
	v_mfma_f32_16x16x32_bf16 v[72:75], v[198:201], v[4:7], v[76:79]
	s_nop 2
	s_nop 0
	ds_read_b128 v[156:159], v92 offset:65472
	s_waitcnt lgkmcnt(11)
	v_mfma_f32_16x16x32_bf16 v[0:3], v[202:205], v[4:7], v[0:3]
	v_mfma_f32_16x16x32_bf16 v[76:79], v[88:91], v[32:35], v[8:11]
	v_mfma_f32_16x16x32_bf16 v[88:91], v[100:103], v[32:35], v[12:15]
	v_mfma_f32_16x16x32_bf16 v[100:103], v[104:107], v[32:35], v[16:19]
	v_mfma_f32_16x16x32_bf16 v[104:107], v[108:111], v[32:35], v[20:23]
	v_mfma_f32_16x16x32_bf16 v[108:111], v[112:115], v[32:35], v[24:27]
	v_mfma_f32_16x16x32_bf16 v[112:115], v[116:119], v[32:35], v[28:31]
	v_mfma_f32_16x16x32_bf16 v[40:43], v[120:123], v[32:35], v[40:43]
	v_mfma_f32_16x16x32_bf16 v[44:47], v[124:127], v[32:35], v[44:47]
	v_mfma_f32_16x16x32_bf16 v[28:31], v[128:131], v[32:35], v[48:51]
	v_mfma_f32_16x16x32_bf16 v[24:27], v[132:135], v[32:35], v[52:55]
	v_mfma_f32_16x16x32_bf16 v[20:23], v[136:139], v[32:35], v[56:59]
	v_mfma_f32_16x16x32_bf16 v[16:19], v[140:143], v[32:35], v[60:63]
	v_mfma_f32_16x16x32_bf16 v[12:15], v[144:147], v[32:35], v[64:67]
	v_mfma_f32_16x16x32_bf16 v[8:11], v[148:151], v[32:35], v[68:71]
	v_mfma_f32_16x16x32_bf16 v[4:7], v[152:155], v[32:35], v[72:75]
	s_waitcnt lgkmcnt(0)
	v_mfma_f32_16x16x32_bf16 v[0:3], v[156:159], v[32:35], v[0:3]
	v_max3_f32 v32, v76, s24, v77
	v_max3_f32 v32, v32, v78, v79
	v_max3_f32 v32, v32, v88, v89
	v_max3_f32 v32, v32, v90, v91
	v_max3_f32 v32, v32, v100, v101
	v_max3_f32 v32, v32, v102, v103
	v_max3_f32 v32, v32, v104, v105
	v_max3_f32 v32, v32, v106, v107
	v_max3_f32 v32, v32, v108, v109
	v_max3_f32 v32, v32, v110, v111
	v_max3_f32 v32, v32, v112, v113
	v_max3_f32 v32, v32, v114, v115
	v_max3_f32 v32, v32, v40, v41
	v_max3_f32 v32, v32, v42, v43
	v_max3_f32 v32, v32, v44, v45
	v_max3_f32 v32, v32, v46, v47
	v_max3_f32 v32, v32, v28, v29
	v_max3_f32 v32, v32, v30, v31
	v_max3_f32 v32, v32, v24, v25
	v_max3_f32 v32, v32, v26, v27
	v_max3_f32 v32, v32, v20, v21
	v_max3_f32 v32, v32, v22, v23
	v_max3_f32 v32, v32, v16, v17
	v_max3_f32 v32, v32, v18, v19
	v_max3_f32 v32, v32, v12, v13
	v_max3_f32 v32, v32, v14, v15
	v_max3_f32 v32, v32, v8, v9
	v_max3_f32 v32, v32, v10, v11
	v_max3_f32 v32, v32, v4, v5
	v_max3_f32 v32, v32, v6, v7
	v_max3_f32 v32, v32, v0, v1
	v_max3_f32 v32, v32, v2, v3
	ds_bpermute_b32 v33, v38, v32
	s_waitcnt lgkmcnt(0)
	v_max_f32_e32 v33, v33, v33
	v_max_f32_e32 v32, v32, v33
	ds_bpermute_b32 v33, v39, v32
	s_waitcnt lgkmcnt(0)
	v_max_f32_e32 v33, v33, v33
	v_max_f32_e32 v32, v32, v33
	v_sub_f32_e32 v33, v76, v32
	v_sub_f32_e32 v34, v77, v32
	v_mul_f32_e32 v33, 0x3fb8aa3b, v33
	v_sub_f32_e32 v35, v78, v32
	v_mul_f32_e32 v34, 0x3fb8aa3b, v34
	v_exp_f32_e32 v33, v33
	v_sub_f32_e32 v48, v79, v32
	v_mul_f32_e32 v35, 0x3fb8aa3b, v35
	v_exp_f32_e32 v34, v34
	v_sub_f32_e32 v49, v88, v32
	v_mul_f32_e32 v48, 0x3fb8aa3b, v48
	v_exp_f32_e32 v35, v35
	v_sub_f32_e32 v50, v89, v32
	v_mul_f32_e32 v49, 0x3fb8aa3b, v49
	v_exp_f32_e32 v48, v48
	v_sub_f32_e32 v51, v90, v32
	v_mul_f32_e32 v50, 0x3fb8aa3b, v50
	v_exp_f32_e32 v49, v49
	v_add_f32_e32 v69, 0, v33
	v_sub_f32_e32 v52, v91, v32
	v_mul_f32_e32 v51, 0x3fb8aa3b, v51
	v_exp_f32_e32 v50, v50
	v_add_f32_e32 v69, v34, v69
	v_sub_f32_e32 v53, v100, v32
	v_mul_f32_e32 v52, 0x3fb8aa3b, v52
	v_exp_f32_e32 v51, v51
	v_add_f32_e32 v69, v35, v69
	v_sub_f32_e32 v54, v101, v32
	v_mul_f32_e32 v53, 0x3fb8aa3b, v53
	v_exp_f32_e32 v52, v52
	v_add_f32_e32 v69, v48, v69
	v_sub_f32_e32 v55, v102, v32
	v_mul_f32_e32 v54, 0x3fb8aa3b, v54
	v_exp_f32_e32 v53, v53
	v_add_f32_e32 v69, v49, v69
	v_sub_f32_e32 v56, v103, v32
	v_mul_f32_e32 v55, 0x3fb8aa3b, v55
	v_exp_f32_e32 v54, v54
	v_add_f32_e32 v69, v50, v69
	v_sub_f32_e32 v57, v104, v32
	v_mul_f32_e32 v56, 0x3fb8aa3b, v56
	v_exp_f32_e32 v55, v55
	v_add_f32_e32 v69, v51, v69
	v_sub_f32_e32 v58, v105, v32
	v_mul_f32_e32 v57, 0x3fb8aa3b, v57
	v_exp_f32_e32 v56, v56
	v_add_f32_e32 v69, v52, v69
	v_sub_f32_e32 v59, v106, v32
	v_mul_f32_e32 v58, 0x3fb8aa3b, v58
	v_exp_f32_e32 v57, v57
	v_add_f32_e32 v69, v53, v69
	v_sub_f32_e32 v60, v107, v32
	v_mul_f32_e32 v59, 0x3fb8aa3b, v59
	v_exp_f32_e32 v58, v58
	v_add_f32_e32 v69, v54, v69
	v_sub_f32_e32 v61, v108, v32
	v_mul_f32_e32 v60, 0x3fb8aa3b, v60
	v_exp_f32_e32 v59, v59
	v_add_f32_e32 v69, v55, v69
	v_sub_f32_e32 v62, v109, v32
; __device__ __forceinline__ bf16x8 pack8(const float (&o)[8]) { v4u w; w.x = pk2(o[0], o[1]); w.y = pk2(o[2], o[3]); w.z = pk2(o[4], o[5]); w.w = pk2(o[6], o[7]); return __builtin_bit_cast(bf16x8, w); }
; template <bool SAMPLE>
; __device__ __forceinline__ void mem_unit(const Params& p, int l, LAS unsigned char* lds, int unit, int tid, int wave, int lane) {
;     ...
;         float den = 0.f;
; #pragma unroll
;         for (int cc = 0; cc < 8; ++cc)
; #pragma unroll
;             for (int tt = 0; tt < 2; ++tt)
; #pragma unroll
;                 for (int e = 0; e < 4; ++e) { const float pe = __expf(S[cc][tt][e] - mx); S[cc][tt][e] = pe; den += pe; }
;         den += __shfl_xor(den, 16); den += __shfl_xor(den, 32);
;         const float rden = 1.f / den;
;         bf16x8 pf[8];
; #pragma unroll
;         for (int cc = 0; cc < 8; ++cc) { float t8[8];
; #pragma unroll
;             for (int e = 0; e < 4; ++e) { t8[e] = S[cc][0][e]; t8[4 + e] = S[cc][1][e]; }
;             pf[cc] = pack8(t8); }
	v_mul_f32_e32 v61, 0x3fb8aa3b, v61
	v_exp_f32_e32 v60, v60
	v_add_f32_e32 v69, v56, v69
	v_sub_f32_e32 v63, v110, v32
	v_mul_f32_e32 v62, 0x3fb8aa3b, v62
	v_exp_f32_e32 v61, v61
	v_add_f32_e32 v69, v57, v69
	v_sub_f32_e32 v64, v111, v32
	v_mul_f32_e32 v63, 0x3fb8aa3b, v63
	v_exp_f32_e32 v62, v62
	v_add_f32_e32 v69, v58, v69
	v_sub_f32_e32 v65, v112, v32
	v_mul_f32_e32 v64, 0x3fb8aa3b, v64
	v_exp_f32_e32 v63, v63
	v_add_f32_e32 v69, v59, v69
	v_sub_f32_e32 v66, v113, v32
	v_mul_f32_e32 v65, 0x3fb8aa3b, v65
	v_exp_f32_e32 v64, v64
	v_add_f32_e32 v69, v60, v69
	v_sub_f32_e32 v67, v114, v32
	v_mul_f32_e32 v66, 0x3fb8aa3b, v66
	v_exp_f32_e32 v65, v65
	v_add_f32_e32 v69, v61, v69
	v_sub_f32_e32 v68, v115, v32
	v_mul_f32_e32 v67, 0x3fb8aa3b, v67
	v_exp_f32_e32 v66, v66
	v_add_f32_e32 v69, v62, v69
	v_sub_f32_e32 v40, v40, v32
	v_mul_f32_e32 v68, 0x3fb8aa3b, v68
	v_exp_f32_e32 v67, v67
	v_add_f32_e32 v69, v63, v69
	v_sub_f32_e32 v41, v41, v32
	v_mul_f32_e32 v40, 0x3fb8aa3b, v40
	v_exp_f32_e32 v68, v68
	v_add_f32_e32 v69, v64, v69
	v_sub_f32_e32 v42, v42, v32
	v_mul_f32_e32 v41, 0x3fb8aa3b, v41
	v_exp_f32_e32 v40, v40
	v_add_f32_e32 v69, v65, v69
	v_sub_f32_e32 v43, v43, v32
	v_mul_f32_e32 v42, 0x3fb8aa3b, v42
	v_exp_f32_e32 v41, v41
	v_add_f32_e32 v69, v66, v69
	v_sub_f32_e32 v44, v44, v32
	v_mul_f32_e32 v43, 0x3fb8aa3b, v43
	v_exp_f32_e32 v42, v42
	v_add_f32_e32 v69, v67, v69
	v_sub_f32_e32 v45, v45, v32
	v_mul_f32_e32 v44, 0x3fb8aa3b, v44
	v_exp_f32_e32 v43, v43
	v_add_f32_e32 v69, v68, v69
	v_sub_f32_e32 v46, v46, v32
	v_mul_f32_e32 v45, 0x3fb8aa3b, v45
	v_exp_f32_e32 v44, v44
	v_add_f32_e32 v69, v40, v69
	v_sub_f32_e32 v47, v47, v32
	v_mul_f32_e32 v46, 0x3fb8aa3b, v46
	v_exp_f32_e32 v45, v45
	v_add_f32_e32 v69, v41, v69
	v_sub_f32_e32 v28, v28, v32
	v_mul_f32_e32 v47, 0x3fb8aa3b, v47
	v_exp_f32_e32 v46, v46
	v_add_f32_e32 v69, v42, v69
	v_sub_f32_e32 v29, v29, v32
	v_mul_f32_e32 v28, 0x3fb8aa3b, v28
	v_exp_f32_e32 v47, v47
	v_add_f32_e32 v69, v43, v69
	v_exp_f32_e32 v28, v28
	v_add_f32_e32 v69, v44, v69
	v_mul_f32_e32 v29, 0x3fb8aa3b, v29
	v_sub_f32_e32 v30, v30, v32
	v_sub_f32_e32 v24, v24, v32
	v_add_f32_e32 v69, v45, v69
	v_exp_f32_e32 v29, v29
	v_mul_f32_e32 v30, 0x3fb8aa3b, v30
	v_sub_f32_e32 v31, v31, v32
	v_mul_f32_e32 v24, 0x3fb8aa3b, v24
	v_add_f32_e32 v69, v46, v69
	v_exp_f32_e32 v30, v30
	v_mul_f32_e32 v31, 0x3fb8aa3b, v31
	v_exp_f32_e32 v70, v24
	v_sub_f32_e32 v24, v25, v32
	v_add_f32_e32 v69, v47, v69
	v_exp_f32_e32 v31, v31
	v_mul_f32_e32 v24, 0x3fb8aa3b, v24
	v_add_f32_e32 v69, v28, v69
	v_exp_f32_e32 v71, v24
	v_sub_f32_e32 v24, v26, v32
	v_add_f32_e32 v69, v29, v69
	v_mul_f32_e32 v24, 0x3fb8aa3b, v24
	v_add_f32_e32 v69, v30, v69
	v_exp_f32_e32 v72, v24
	v_sub_f32_e32 v24, v27, v32
	v_sub_f32_e32 v20, v20, v32
	v_add_f32_e32 v69, v31, v69
	v_mul_f32_e32 v24, 0x3fb8aa3b, v24
	v_mul_f32_e32 v20, 0x3fb8aa3b, v20
	v_exp_f32_e32 v73, v24
	v_add_f32_e32 v24, v70, v69
	v_exp_f32_e32 v69, v20
	v_sub_f32_e32 v20, v21, v32
	v_mul_f32_e32 v20, 0x3fb8aa3b, v20
	v_exp_f32_e32 v74, v20
	v_sub_f32_e32 v20, v22, v32
	v_sub_f32_e32 v16, v16, v32
	v_mul_f32_e32 v20, 0x3fb8aa3b, v20
	v_mul_f32_e32 v16, 0x3fb8aa3b, v16
	v_add_f32_e32 v24, v71, v24
	v_exp_f32_e32 v75, v20
	v_sub_f32_e32 v20, v23, v32
	v_exp_f32_e32 v77, v16
	v_sub_f32_e32 v16, v17, v32
	v_add_f32_e32 v24, v72, v24
	v_mul_f32_e32 v20, 0x3fb8aa3b, v20
	v_mul_f32_e32 v16, 0x3fb8aa3b, v16
	v_add_f32_e32 v24, v73, v24
	v_exp_f32_e32 v76, v20
	v_exp_f32_e32 v78, v16
	v_sub_f32_e32 v16, v18, v32
	v_sub_f32_e32 v12, v12, v32
	v_add_f32_e32 v20, v69, v24
	v_mul_f32_e32 v16, 0x3fb8aa3b, v16
	v_mul_f32_e32 v12, 0x3fb8aa3b, v12
	v_add_f32_e32 v20, v74, v20
	v_exp_f32_e32 v79, v16
	v_sub_f32_e32 v16, v19, v32
	v_exp_f32_e32 v89, v12
	v_sub_f32_e32 v12, v13, v32
	v_add_f32_e32 v20, v75, v20
	v_mul_f32_e32 v16, 0x3fb8aa3b, v16
	v_mul_f32_e32 v12, 0x3fb8aa3b, v12
	v_add_f32_e32 v20, v76, v20
	v_exp_f32_e32 v88, v16
	v_exp_f32_e32 v90, v12
	v_sub_f32_e32 v12, v14, v32
	v_sub_f32_e32 v8, v8, v32
	v_add_f32_e32 v16, v77, v20
	v_mul_f32_e32 v12, 0x3fb8aa3b, v12
	v_mul_f32_e32 v8, 0x3fb8aa3b, v8
	v_add_f32_e32 v16, v78, v16
	v_exp_f32_e32 v91, v12
	v_sub_f32_e32 v12, v15, v32
	v_exp_f32_e32 v93, v8
	v_sub_f32_e32 v8, v9, v32
	v_add_f32_e32 v16, v79, v16
	v_mul_f32_e32 v12, 0x3fb8aa3b, v12
	v_mul_f32_e32 v8, 0x3fb8aa3b, v8
	v_add_f32_e32 v16, v88, v16
	v_exp_f32_e32 v92, v12
	v_exp_f32_e32 v100, v8
	v_sub_f32_e32 v8, v10, v32
	v_sub_f32_e32 v4, v4, v32
	v_add_f32_e32 v12, v89, v16
	v_mul_f32_e32 v8, 0x3fb8aa3b, v8
	v_mul_f32_e32 v4, 0x3fb8aa3b, v4
	v_add_f32_e32 v12, v90, v12
	v_exp_f32_e32 v101, v8
	v_sub_f32_e32 v8, v11, v32
	v_exp_f32_e32 v103, v4
	v_sub_f32_e32 v4, v5, v32
	v_add_f32_e32 v12, v91, v12
	v_mul_f32_e32 v8, 0x3fb8aa3b, v8
	v_mul_f32_e32 v4, 0x3fb8aa3b, v4
	v_add_f32_e32 v12, v92, v12
	v_exp_f32_e32 v102, v8
	v_exp_f32_e32 v104, v4
	v_sub_f32_e32 v4, v6, v32
	v_sub_f32_e32 v0, v0, v32
	v_add_f32_e32 v8, v93, v12
	v_mul_f32_e32 v4, 0x3fb8aa3b, v4
	v_mul_f32_e32 v0, 0x3fb8aa3b, v0
	v_add_f32_e32 v8, v100, v8
	v_exp_f32_e32 v105, v4
	v_sub_f32_e32 v4, v7, v32
	v_exp_f32_e32 v107, v0
	v_sub_f32_e32 v0, v1, v32
	v_add_f32_e32 v8, v101, v8
	v_mul_f32_e32 v4, 0x3fb8aa3b, v4
	v_mul_f32_e32 v0, 0x3fb8aa3b, v0
	v_add_f32_e32 v8, v102, v8
	v_exp_f32_e32 v106, v4
	v_exp_f32_e32 v108, v0
	v_sub_f32_e32 v0, v2, v32
	v_add_f32_e32 v4, v103, v8
	v_mul_f32_e32 v0, 0x3fb8aa3b, v0
	v_add_f32_e32 v4, v104, v4
	v_exp_f32_e32 v109, v0
	v_sub_f32_e32 v0, v3, v32
	v_add_f32_e32 v4, v105, v4
	v_mul_f32_e32 v0, 0x3fb8aa3b, v0
	v_add_f32_e32 v4, v106, v4
	v_exp_f32_e32 v32, v0
	v_add_f32_e32 v0, v107, v4
	v_add_f32_e32 v0, v108, v0
	v_add_f32_e32 v0, v109, v0
	v_add_f32_e32 v0, v32, v0
	ds_bpermute_b32 v1, v38, v0
	v_cvt_pk_bf16_f32 v24, v33, v34
	v_cvt_pk_bf16_f32 v25, v35, v48
	v_cvt_pk_bf16_f32 v26, v49, v50
	v_cvt_pk_bf16_f32 v27, v51, v52
	s_waitcnt lgkmcnt(0)
; #define LAS __attribute__((address_space(3)))
; __device__ __forceinline__ unsigned pk2(float lo, float hi) { return pg8::cvt_pk_bf16(lo, hi); }
; __device__ __forceinline__ bf16x8 pack8(const float (&o)[8]) { v4u w; w.x = pk2(o[0], o[1]); w.y = pk2(o[2], o[3]); w.z = pk2(o[4], o[5]); w.w = pk2(o[6], o[7]); return __builtin_bit_cast(bf16x8, w); }
; __device__ __forceinline__ v2u vtr(const LAS bf16* p) { return __builtin_bit_cast(v2u, __builtin_amdgcn_ds_read_tr16_b64_v4i16((LAS v4i16_t*)p)); }
; template <bool SAMPLE>
; __device__ __forceinline__ void mem_unit(const Params& p, int l, LAS unsigned char* lds, int unit, int tid, int wave, int lane) {
;     ...
;         den += __shfl_xor(den, 16); den += __shfl_xor(den, 32);
;         const float rden = 1.f / den;
;         bf16x8 pf[8];
; #pragma unroll
;         for (int cc = 0; cc < 8; ++cc) { float t8[8];
; #pragma unroll
;             for (int e = 0; e < 4; ++e) { t8[e] = S[cc][0][e]; t8[4 + e] = S[cc][1][e]; }
;             pf[cc] = pack8(t8); }
; #pragma unroll
;         for (int dt = 0; dt < 8; ++dt) { f32x4 o = (f32x4){0.f, 0.f, 0.f, 0.f};
; #pragma unroll
;             for (int cc = 0; cc < 8; ++cc) { const LAS bf16* vp = Vt + (32 * cc + 4 * kq + (q16 >> 2)) * MEM_VS + 16 * dt + 4 * (q16 & 3);
;                 const v2u lo = vtr(vp), hi = vtr(vp + 16 * MEM_VS);
;                 v4u av; av.x = lo.x; av.y = lo.y; av.z = hi.x; av.w = hi.y;
;                 o = __builtin_amdgcn_mfma_f32_16x16x32_bf16(__builtin_bit_cast(bf16x8, av), pf[cc], o, 0, 0, 0); }
;             if (st) { v2u w; w.x = pk2(o[0] * rden, o[1] * rden); w.y = pk2(o[2] * rden, o[3] * rden);
;                 *(v2u*)(MO + row * 512 + h * 128 + 16 * dt + 4 * kq) = w; } }
	v_add_f32_e32 v0, v0, v1
	ds_bpermute_b32 v1, v39, v0
	v_cvt_pk_bf16_f32 v20, v53, v54
	v_cvt_pk_bf16_f32 v21, v55, v56
	v_cvt_pk_bf16_f32 v22, v57, v58
	v_cvt_pk_bf16_f32 v23, v59, v60
	s_waitcnt lgkmcnt(0)
	v_add_f32_e32 v39, v0, v1
	v_cvt_pk_bf16_f32 v16, v61, v62
	v_cvt_pk_bf16_f32 v17, v63, v64
	v_cvt_pk_bf16_f32 v18, v65, v66
	v_cvt_pk_bf16_f32 v19, v67, v68
	v_cvt_pk_bf16_f32 v12, v40, v41
	v_cvt_pk_bf16_f32 v13, v42, v43
	v_cvt_pk_bf16_f32 v14, v44, v45
	v_cvt_pk_bf16_f32 v15, v46, v47
	v_cvt_pk_bf16_f32 v8, v28, v29
	v_cvt_pk_bf16_f32 v9, v30, v31
	v_cvt_pk_bf16_f32 v10, v70, v71
	v_cvt_pk_bf16_f32 v11, v72, v73
	v_cvt_pk_bf16_f32 v4, v69, v74
	v_cvt_pk_bf16_f32 v5, v75, v76
	v_cvt_pk_bf16_f32 v6, v77, v78
	v_cvt_pk_bf16_f32 v7, v79, v88
	v_cvt_pk_bf16_f32 v0, v89, v90
	v_cvt_pk_bf16_f32 v1, v91, v92
	v_cvt_pk_bf16_f32 v2, v93, v100
	v_cvt_pk_bf16_f32 v3, v101, v102
	v_cvt_pk_bf16_f32 v28, v103, v104
	v_cvt_pk_bf16_f32 v29, v105, v106
	v_cvt_pk_bf16_f32 v30, v107, v108
	v_cvt_pk_bf16_f32 v31, v109, v32
	v_lshlrev_b32_e32 v52, 2, v37
	v_lshrrev_b32_e32 v32, 2, v36
	v_add_u32_e32 v32, v32, v52
	v_lshlrev_b32_e32 v33, 3, v36
	v_and_b32_e32 v33, 24, v33
	v_mul_lo_u32 v32, v32, s22
	v_add3_u32 v38, s90, v33, v32
	ds_read_b64_tr_b16 v[230:231], v38
	ds_read_b64_tr_b16 v[232:233], v38 offset:4352
	ds_read_b64_tr_b16 v[234:235], v38 offset:8704
	ds_read_b64_tr_b16 v[236:237], v38 offset:13056
	ds_read_b64_tr_b16 v[242:243], v38 offset:17408
	ds_read_b64_tr_b16 v[244:245], v38 offset:21760
	ds_read_b64_tr_b16 v[246:247], v38 offset:26112
	ds_read_b64_tr_b16 v[248:249], v38 offset:30464
	ds_read_b64_tr_b16 v[186:187], v38 offset:34816
	ds_read_b64_tr_b16 v[188:189], v38 offset:39168
	s_nop 3
	s_waitcnt lgkmcnt(8)
	v_mfma_f32_16x16x32_bf16 v[32:35], v[230:233], v[24:27], 0
	s_nop 3
	v_div_scale_f32 v53, s[2:3], v39, v39, 1.0
	s_waitcnt lgkmcnt(6)
	v_mfma_f32_16x16x32_bf16 v[32:35], v[234:237], v[20:23], v[32:35]
	s_nop 1
	v_rcp_f32_e32 v37, v53
	s_add_u32 s2, s70, s0
	s_waitcnt lgkmcnt(4)
	v_mfma_f32_16x16x32_bf16 v[32:35], v[242:245], v[16:19], v[32:35]
	ds_read_b64_tr_b16 v[44:45], v38 offset:43520
	ds_read_b64_tr_b16 v[46:47], v38 offset:47872
	v_cmp_gt_i32_e64 s[0:1], 8, v36
	v_fma_f32 v36, -v53, v37, 1.0
	s_waitcnt lgkmcnt(4)
	v_mfma_f32_16x16x32_bf16 v[32:35], v[246:249], v[12:15], v[32:35]
	ds_read_b64_tr_b16 v[48:49], v38 offset:52224
	ds_read_b64_tr_b16 v[50:51], v38 offset:56576
	v_fmac_f32_e32 v37, v36, v37
	v_div_scale_f32 v36, vcc, 1.0, v39, 1.0
	s_waitcnt lgkmcnt(4)
	v_mfma_f32_16x16x32_bf16 v[32:35], v[186:189], v[8:11], v[32:35]
	ds_read_b64_tr_b16 v[40:41], v38 offset:60928
	ds_read_b64_tr_b16 v[42:43], v38 offset:65280
	v_mul_f32_e32 v54, v36, v37
	v_fma_f32 v55, -v53, v54, v36
	s_waitcnt lgkmcnt(4)
	v_mfma_f32_16x16x32_bf16 v[32:35], v[44:47], v[4:7], v[32:35]
	v_fmac_f32_e32 v54, v55, v37
	v_fma_f32 v36, -v53, v54, v36
	s_addc_u32 s3, s71, 0
	s_waitcnt lgkmcnt(2)
	v_mfma_f32_16x16x32_bf16 v[32:35], v[48:51], v[0:3], v[32:35]
	v_div_fmas_f32 v36, v36, v37, v54
	v_div_fixup_f32 v39, v36, v39, 1.0
	v_lshl_add_u64 v[36:37], s[2:3], 0, v[82:83]
	s_waitcnt lgkmcnt(0)
	v_mfma_f32_16x16x32_bf16 v[32:35], v[40:43], v[28:31], v[32:35]
	v_ashrrev_i32_e32 v53, 31, v52
	v_lshl_add_u64 v[36:37], v[52:53], 1, v[36:37]
	s_and_saveexec_b64 s[2:3], s[0:1]
	s_cbranch_execz .LBB0_2734
	s_nop 3
	v_mul_f32_e32 v32, v32, v39
	v_mul_f32_e32 v33, v33, v39
	v_cvt_pk_bf16_f32 v32, v32, v33
	v_mul_f32_e32 v33, v34, v39
	v_mul_f32_e32 v34, v35, v39
	v_cvt_pk_bf16_f32 v33, v33, v34
	global_store_dwordx2 v[36:37], v[32:33], off

; __device__ __forceinline__ void unpack8(const v4u w, float (&o)[8]) { o[0] = bflo(w.x); o[1] = bfhi(w.x); o[2] = bflo(w.y); o[3] = bfhi(w.y); o[4] = bflo(w.z); o[5] = bfhi(w.z); o[6] = bflo(w.w); o[7] = bfhi(w.w); }
; __device__ __forceinline__ bf16x8 pack8(const float (&o)[8]) { v4u w; w.x = pk2(o[0], o[1]); w.y = pk2(o[2], o[3]); w.z = pk2(o[4], o[5]); w.w = pk2(o[6], o[7]); return __builtin_bit_cast(bf16x8, w); }
; template <bool SAMPLE>
; __device__ __forceinline__ void mem_unit(const Params& p, int l, LAS unsigned char* lds, int unit, int tid, int wave, int lane) {
;     ...
;         int q16 = lane & 15, kq = lane >> 4; asm volatile("" : "+v"(q16), "+v"(kq));
;         size_t row; bool st;
;         if (!SAMPLE) { row = (size_t)b * 8192 + (qt * 4 + qq) * 128 + 16 * wave + q16; st = true; } else { row = (size_t)MP + 8 * b + (q16 & 7); st = q16 < 8; }
;         bf16x8 qf[4];
;         {
;             float qv[4][8]; float ss = 0.f;
; #pragma unroll
;             for (int dc = 0; dc < 4; ++dc) { unpack8(*(const v4u*)(MQ + row * 512 + h * 128 + 32 * dc + 8 * kq), qv[dc]);
; #pragma unroll
;                 for (int e = 0; e < 8; ++e) ss += qv[dc][e] * qv[dc][e]; }
;             ss += __shfl_xor(ss, 16); ss += __shfl_xor(ss, 32);
;             const float rs = rsqrtf(ss * (1.f / 128.f) + EPS) * 0.08838834764831845f;
; #pragma unroll
;             for (int dc = 0; dc < 4; ++dc) { float qg[8]; pg8::ld8f(p.in[I_MQG] + l * 128 + 32 * dc + 8 * kq, qg);
; #pragma unroll
;                 for (int e = 0; e < 8; ++e) qv[dc][e] *= rs * qg[e];
;                 qf[dc] = pack8(qv[dc]); }
.LBB0_2762:
	v_mov_b32_e32 v92, v95
	v_mov_b32_e32 v90, v94
	s_add_u32 s16, s10, s8
	s_addc_u32 s17, s18, s9
	v_ashrrev_i32_e32 v91, 31, v90
	v_lshl_add_u64 v[0:1], s[16:17], 0, v[90:91]
	v_lshlrev_b32_e32 v8, 3, v92
	v_lshlrev_b64 v[88:89], 10, v[0:1]
	v_ashrrev_i32_e32 v9, 31, v8
	v_lshl_add_u64 v[10:11], s[0:1], 0, v[88:89]
	v_lshlrev_b32_e32 v2, 4, v92
	v_mul_lo_u32 v3, v90, s22
	v_lshl_add_u64 v[24:25], v[8:9], 2, s[46:47]
	v_lshl_add_u64 v[20:21], v[8:9], 1, v[10:11]
	v_add3_u32 v91, 0, v2, v3
	global_load_dwordx4 v[0:3], v[24:25], off offset:528
	global_load_dwordx4 v[4:7], v[24:25], off offset:512
	global_load_dwordx4 v[8:11], v[20:21], off
	global_load_dwordx4 v[12:15], v[20:21], off offset:64
	global_load_dwordx4 v[16:19], v[20:21], off offset:128
	s_nop 0
	global_load_dwordx4 v[20:23], v[20:21], off offset:192
	v_lshlrev_b32_e32 v92, 2, v92
	v_ashrrev_i32_e32 v93, 31, v92
	s_add_u32 s8, s8, 0x80
	s_addc_u32 s9, s9, 0
	s_cmpk_lg_i32 s8, 0x200
	s_waitcnt vmcnt(3)
	v_and_b32_e32 v31, 0xffff0000, v8
	v_lshlrev_b32_e32 v30, 16, v8
	v_mul_f32_e32 v50, v31, v31
	v_lshlrev_b32_e32 v32, 16, v9
	v_fmac_f32_e32 v50, v30, v30
	v_and_b32_e32 v33, 0xffff0000, v9
	v_fmac_f32_e32 v50, v32, v32
	v_lshlrev_b32_e32 v34, 16, v10
	v_fmac_f32_e32 v50, v33, v33
	v_and_b32_e32 v35, 0xffff0000, v10
	v_fmac_f32_e32 v50, v34, v34
	v_lshlrev_b32_e32 v36, 16, v11
	v_fmac_f32_e32 v50, v35, v35
	v_and_b32_e32 v37, 0xffff0000, v11
	v_fmac_f32_e32 v50, v36, v36
	s_waitcnt vmcnt(2)
	v_lshlrev_b32_e32 v38, 16, v12
	v_fmac_f32_e32 v50, v37, v37
	v_and_b32_e32 v39, 0xffff0000, v12
	v_fmac_f32_e32 v50, v38, v38
	v_lshlrev_b32_e32 v40, 16, v13
	v_fmac_f32_e32 v50, v39, v39
	v_and_b32_e32 v41, 0xffff0000, v13
	v_fmac_f32_e32 v50, v40, v40
	v_lshlrev_b32_e32 v42, 16, v14
	v_fmac_f32_e32 v50, v41, v41
	v_and_b32_e32 v43, 0xffff0000, v14
	v_fmac_f32_e32 v50, v42, v42
	v_lshlrev_b32_e32 v44, 16, v15
	v_fmac_f32_e32 v50, v43, v43
	v_and_b32_e32 v45, 0xffff0000, v15
	v_fmac_f32_e32 v50, v44, v44
	s_waitcnt vmcnt(1)
	v_lshlrev_b32_e32 v46, 16, v16
	v_fmac_f32_e32 v50, v45, v45
	v_and_b32_e32 v16, 0xffff0000, v16
	v_fmac_f32_e32 v50, v46, v46
	v_lshlrev_b32_e32 v47, 16, v17
	v_fmac_f32_e32 v50, v16, v16
	v_and_b32_e32 v17, 0xffff0000, v17
	v_fmac_f32_e32 v50, v47, v47
	v_lshlrev_b32_e32 v48, 16, v18
	v_fmac_f32_e32 v50, v17, v17
	v_and_b32_e32 v18, 0xffff0000, v18
	v_fmac_f32_e32 v50, v48, v48
	v_lshlrev_b32_e32 v49, 16, v19
	v_fmac_f32_e32 v50, v18, v18
	v_and_b32_e32 v19, 0xffff0000, v19
	s_waitcnt vmcnt(0)
	v_and_b32_e32 v26, 0xffff0000, v20
	v_lshlrev_b32_e32 v27, 16, v20
	v_fmac_f32_e32 v50, v49, v49
	v_pk_mul_f32 v[8:9], v[26:27], v[26:27]
	v_fmac_f32_e32 v50, v19, v19
	v_and_b32_e32 v20, 0xffff0000, v21
	v_lshlrev_b32_e32 v21, 16, v21
	v_add_f32_e32 v9, v9, v50
	v_pk_mul_f32 v[10:11], v[20:21], v[20:21]
	v_add_f32_e32 v8, v8, v9
	v_and_b32_e32 v28, 0xffff0000, v22
	v_lshlrev_b32_e32 v29, 16, v22
	v_add_f32_e32 v8, v11, v8
	v_pk_mul_f32 v[12:13], v[28:29], v[28:29]
	v_add_f32_e32 v8, v10, v8
	v_and_b32_e32 v22, 0xffff0000, v23
	v_lshlrev_b32_e32 v23, 16, v23
	v_add_f32_e32 v8, v13, v8
	v_pk_mul_f32 v[14:15], v[22:23], v[22:23]
	v_add_f32_e32 v8, v12, v8
	v_add_f32_e32 v8, v15, v8
	v_add_f32_e32 v8, v14, v8
	ds_bpermute_b32 v9, v82, v8
	s_waitcnt lgkmcnt(0)
	v_add_f32_e32 v8, v8, v9
	ds_bpermute_b32 v9, v100, v8
	s_waitcnt lgkmcnt(0)
	v_add_f32_e32 v8, v8, v9
	v_fmamk_f32 v8, v8, 0x3c000000, v98
	v_mul_f32_e32 v9, 0x4b800000, v8
	v_cmp_gt_f32_e32 vcc, s23, v8
	s_nop 1
	v_cndmask_b32_e32 v8, v8, v9, vcc
	v_rsq_f32_e32 v8, v8
	s_nop 0
	v_mul_f32_e32 v9, 0x45800000, v8
	v_cndmask_b32_e32 v8, v8, v9, vcc
	v_mul_f32_e32 v50, 0x3db504f3, v8
	v_mul_f32_e32 v4, v4, v50
	v_mul_f32_e32 v5, v5, v50
	v_mul_f32_e32 v6, v6, v50
	v_mul_f32_e32 v7, v7, v50
	v_mul_f32_e32 v0, v0, v50
	v_mul_f32_e32 v1, v1, v50
	v_mul_f32_e32 v2, v2, v50
	v_mul_f32_e32 v3, v3, v50
	v_mul_f32_e32 v4, v4, v30
	v_mul_f32_e32 v5, v5, v31
	v_mul_f32_e32 v6, v6, v32
	v_mul_f32_e32 v7, v7, v33
	v_mul_f32_e32 v0, v0, v34
	v_mul_f32_e32 v1, v1, v35
	v_mul_f32_e32 v2, v2, v36
	v_mul_f32_e32 v3, v3, v37
	v_cvt_pk_bf16_f32 v8, v4, v5
	v_cvt_pk_bf16_f32 v9, v6, v7
	v_cvt_pk_bf16_f32 v10, v0, v1
	v_cvt_pk_bf16_f32 v11, v2, v3
	global_load_dwordx4 v[0:3], v[24:25], off offset:640
	global_load_dwordx4 v[4:7], v[24:25], off offset:656
	s_waitcnt vmcnt(1)
	v_mul_f32_e32 v0, v0, v50
	v_mul_f32_e32 v1, v1, v50
	v_mul_f32_e32 v2, v2, v50
	v_mul_f32_e32 v3, v3, v50
	s_waitcnt vmcnt(0)
	v_mul_f32_e32 v4, v4, v50
	v_mul_f32_e32 v5, v5, v50
	v_mul_f32_e32 v6, v6, v50
	v_mul_f32_e32 v7, v7, v50
	v_mul_f32_e32 v0, v0, v38
	v_mul_f32_e32 v1, v1, v39
	v_mul_f32_e32 v2, v2, v40
	v_mul_f32_e32 v3, v3, v41
	v_mul_f32_e32 v4, v4, v42
	v_mul_f32_e32 v5, v5, v43
	v_mul_f32_e32 v6, v6, v44
	v_mul_f32_e32 v7, v7, v45
	v_cvt_pk_bf16_f32 v12, v0, v1
	v_cvt_pk_bf16_f32 v13, v2, v3
	v_cvt_pk_bf16_f32 v14, v4, v5
	v_cvt_pk_bf16_f32 v15, v6, v7
	global_load_dwordx4 v[0:3], v[24:25], off offset:768
	global_load_dwordx4 v[4:7], v[24:25], off offset:784
	s_waitcnt vmcnt(1)
	v_mul_f32_e32 v0, v0, v50
	v_mul_f32_e32 v1, v1, v50
	v_mul_f32_e32 v2, v2, v50
	v_mul_f32_e32 v3, v3, v50
	s_waitcnt vmcnt(0)
	v_mul_f32_e32 v4, v4, v50
	v_mul_f32_e32 v5, v5, v50
	v_mul_f32_e32 v6, v6, v50
	v_mul_f32_e32 v7, v7, v50
	v_mul_f32_e32 v0, v0, v46
	v_mul_f32_e32 v1, v1, v16
	v_mul_f32_e32 v2, v2, v47
	v_mul_f32_e32 v3, v3, v17
	v_mul_f32_e32 v16, v4, v48
	v_mul_f32_e32 v17, v5, v18
	v_mul_f32_e32 v18, v6, v49
	v_mul_f32_e32 v7, v7, v19
	v_cvt_pk_bf16_f32 v4, v0, v1
	v_cvt_pk_bf16_f32 v5, v2, v3
	v_cvt_pk_bf16_f32 v6, v16, v17
	v_cvt_pk_bf16_f32 v7, v18, v7
	global_load_dwordx4 v[0:3], v[24:25], off offset:896
	global_load_dwordx4 v[16:19], v[24:25], off offset:912
	s_waitcnt vmcnt(1)
; #define LAS __attribute__((address_space(3)))
; template <bool SAMPLE>
; __device__ __forceinline__ void mem_unit(const Params& p, int l, LAS unsigned char* lds, int unit, int tid, int wave, int lane) {
;     ...
;         f32x4 S[8][2]; float mx = -INFINITY;
; #pragma unroll
;         for (int cc = 0; cc < 8; ++cc)
; #pragma unroll
;             for (int tt = 0; tt < 2; ++tt) { const int kb = 32 * cc + 16 * tt; f32x4 a = (f32x4){0.f, 0.f, 0.f, 0.f};
; #pragma unroll
;                 for (int dc = 0; dc < 4; ++dc) { const bf16x8 kf = *(const LAS bf16x8*)(Kl + (kb + q16) * MEM_KS + 32 * dc + 8 * kq);
;                     a = __builtin_amdgcn_mfma_f32_16x16x32_bf16(kf, qf[dc], a, 0, 0, 0); }
; #pragma unroll
;                 for (int e = 0; e < 4; ++e) mx = fmaxf(mx, a[e]);
;                 S[cc][tt] = a; }
	v_mul_f32_e32 v0, v0, v50
	v_mul_f32_e32 v1, v1, v50
	v_mul_f32_e32 v2, v2, v50
	v_mul_f32_e32 v3, v3, v50
	s_waitcnt vmcnt(0)
	v_mul_f32_e32 v16, v16, v50
	v_mul_f32_e32 v17, v17, v50
	v_mul_f32_e32 v18, v18, v50
	v_mul_f32_e32 v19, v19, v50
	v_mul_f32_e32 v0, v0, v27
	v_mul_f32_e32 v1, v1, v26
	v_mul_f32_e32 v2, v2, v21
	v_mul_f32_e32 v3, v3, v20
	v_mul_f32_e32 v16, v16, v29
	v_mul_f32_e32 v17, v17, v28
	v_mul_f32_e32 v18, v18, v23
	v_mul_f32_e32 v19, v19, v22
	v_cvt_pk_bf16_f32 v0, v0, v1
	v_cvt_pk_bf16_f32 v1, v2, v3
	v_cvt_pk_bf16_f32 v2, v16, v17
	v_cvt_pk_bf16_f32 v3, v18, v19
	ds_read_b128 v[186:189], v91
	ds_read_b128 v[190:193], v91 offset:4352
	ds_read_b128 v[194:197], v91 offset:8704
	ds_read_b128 v[198:201], v91 offset:13056
	ds_read_b128 v[202:205], v91 offset:17408
	ds_read_b128 v[206:209], v91 offset:21760
	ds_read_b128 v[210:213], v91 offset:26112
	s_nop 0
	ds_read_b128 v[20:23], v91 offset:64
	s_nop 0
	ds_read_b128 v[28:31], v91 offset:4416
	s_nop 0
	ds_read_b128 v[36:39], v91 offset:8768
	s_nop 0
	ds_read_b128 v[44:47], v91 offset:13120
	s_nop 0
	ds_read_b128 v[52:55], v91 offset:17472
	s_nop 0
	ds_read_b128 v[60:63], v91 offset:21824
	s_nop 0
	ds_read_b128 v[68:71], v91 offset:26176
	ds_read_b128 v[72:75], v91 offset:30464
	ds_read_b128 v[76:79], v91 offset:30528
	ds_read_b128 v[102:105], v91 offset:34816
	ds_read_b128 v[106:109], v91 offset:34880
	ds_read_b128 v[110:113], v91 offset:39168
	ds_read_b128 v[114:117], v91 offset:39232
	ds_read_b128 v[118:121], v91 offset:43520
	ds_read_b128 v[122:125], v91 offset:43584
	ds_read_b128 v[126:129], v91 offset:47872
	ds_read_b128 v[130:133], v91 offset:47936
	ds_read_b128 v[134:137], v91 offset:52224
	ds_read_b128 v[138:141], v91 offset:52288
	ds_read_b128 v[142:145], v91 offset:56576
	ds_read_b128 v[146:149], v91 offset:56640
	ds_read_b128 v[150:153], v91 offset:60928
	ds_read_b128 v[154:157], v91 offset:60992
	ds_read_b128 v[158:161], v91 offset:65280
	ds_read_b128 v[162:165], v91 offset:65344
	s_waitcnt lgkmcnt(14)
	v_mfma_f32_16x16x32_bf16 v[16:19], v[186:189], v[8:11], 0
	v_mfma_f32_16x16x32_bf16 v[24:27], v[190:193], v[8:11], 0
	v_mfma_f32_16x16x32_bf16 v[32:35], v[194:197], v[8:11], 0
	v_mfma_f32_16x16x32_bf16 v[40:43], v[198:201], v[8:11], 0
	v_mfma_f32_16x16x32_bf16 v[48:51], v[202:205], v[8:11], 0
	v_mfma_f32_16x16x32_bf16 v[56:59], v[206:209], v[8:11], 0
	v_mfma_f32_16x16x32_bf16 v[64:67], v[210:213], v[8:11], 0
	v_mfma_f32_16x16x32_bf16 v[72:75], v[72:75], v[8:11], 0
	v_mfma_f32_16x16x32_bf16 v[102:105], v[102:105], v[8:11], 0
	s_waitcnt lgkmcnt(13)
	v_mfma_f32_16x16x32_bf16 v[110:113], v[110:113], v[8:11], 0
	s_waitcnt lgkmcnt(11)
	v_mfma_f32_16x16x32_bf16 v[118:121], v[118:121], v[8:11], 0
	s_waitcnt lgkmcnt(9)
	v_mfma_f32_16x16x32_bf16 v[126:129], v[126:129], v[8:11], 0
	s_waitcnt lgkmcnt(7)
	v_mfma_f32_16x16x32_bf16 v[134:137], v[134:137], v[8:11], 0
	s_waitcnt lgkmcnt(5)
	v_mfma_f32_16x16x32_bf16 v[142:145], v[142:145], v[8:11], 0
	s_waitcnt lgkmcnt(3)
	v_mfma_f32_16x16x32_bf16 v[150:153], v[150:153], v[8:11], 0
	s_waitcnt lgkmcnt(1)
	v_mfma_f32_16x16x32_bf16 v[8:11], v[158:161], v[8:11], 0
	v_mfma_f32_16x16x32_bf16 v[16:19], v[20:23], v[12:15], v[16:19]
	v_mfma_f32_16x16x32_bf16 v[20:23], v[28:31], v[12:15], v[24:27]
	v_mfma_f32_16x16x32_bf16 v[24:27], v[36:39], v[12:15], v[32:35]
	v_mfma_f32_16x16x32_bf16 v[28:31], v[44:47], v[12:15], v[40:43]
	v_mfma_f32_16x16x32_bf16 v[32:35], v[52:55], v[12:15], v[48:51]
	ds_read_b128 v[202:205], v91 offset:128
	ds_read_b128 v[206:209], v91 offset:4480
	ds_read_b128 v[210:213], v91 offset:8832
	v_mfma_f32_16x16x32_bf16 v[36:39], v[60:63], v[12:15], v[56:59]
	v_mfma_f32_16x16x32_bf16 v[40:43], v[68:71], v[12:15], v[64:67]
	v_mfma_f32_16x16x32_bf16 v[44:47], v[76:79], v[12:15], v[72:75]
	v_mfma_f32_16x16x32_bf16 v[48:51], v[106:109], v[12:15], v[102:105]
	v_mfma_f32_16x16x32_bf16 v[52:55], v[114:117], v[12:15], v[110:113]
	v_mfma_f32_16x16x32_bf16 v[56:59], v[122:125], v[12:15], v[118:121]
	v_mfma_f32_16x16x32_bf16 v[60:63], v[130:133], v[12:15], v[126:129]
	ds_read_b128 v[218:221], v91 offset:13184
	ds_read_b128 v[222:225], v91 offset:17536
	ds_read_b128 v[226:229], v91 offset:21888
	ds_read_b128 v[230:233], v91 offset:26240
	ds_read_b128 v[234:237], v91 offset:30592
	ds_read_b128 v[242:245], v91 offset:34944
	ds_read_b128 v[246:249], v91 offset:39296
	v_mfma_f32_16x16x32_bf16 v[64:67], v[138:141], v[12:15], v[134:137]
	v_mfma_f32_16x16x32_bf16 v[68:71], v[146:149], v[12:15], v[142:145]
	v_mfma_f32_16x16x32_bf16 v[102:105], v[154:157], v[12:15], v[150:153]
	s_waitcnt lgkmcnt(10)
	v_mfma_f32_16x16x32_bf16 v[8:11], v[162:165], v[12:15], v[8:11]
	s_nop 0
	ds_read_b128 v[106:109], v91 offset:192
	s_waitcnt lgkmcnt(10)
	v_mfma_f32_16x16x32_bf16 v[12:15], v[202:205], v[4:7], v[16:19]
	s_nop 2
	s_nop 0
	ds_read_b128 v[110:113], v91 offset:4544
	s_waitcnt lgkmcnt(10)
	v_mfma_f32_16x16x32_bf16 v[16:19], v[206:209], v[4:7], v[20:23]
	s_nop 2
	s_nop 0
	ds_read_b128 v[114:117], v91 offset:8896
	s_waitcnt lgkmcnt(10)
	v_mfma_f32_16x16x32_bf16 v[20:23], v[210:213], v[4:7], v[24:27]
	s_nop 2
	s_nop 0
	ds_read_b128 v[118:121], v91 offset:13248
	s_waitcnt lgkmcnt(10)
	ds_read_b128 v[186:189], v91 offset:43648
	ds_read_b128 v[190:193], v91 offset:48000
	ds_read_b128 v[194:197], v91 offset:52352
	ds_read_b128 v[198:201], v91 offset:56704
	ds_read_b128 v[202:205], v91 offset:61056
	ds_read_b128 v[206:209], v91 offset:65408
	v_mfma_f32_16x16x32_bf16 v[24:27], v[218:221], v[4:7], v[28:31]
	s_nop 2
	s_nop 0
	ds_read_b128 v[122:125], v91 offset:17600
	s_waitcnt lgkmcnt(15)
; #define LAS __attribute__((address_space(3)))
; template <bool SAMPLE>
; __device__ __forceinline__ void mem_unit(const Params& p, int l, LAS unsigned char* lds, int unit, int tid, int wave, int lane) {
;     ...
;         f32x4 S[8][2]; float mx = -INFINITY;
; #pragma unroll
;         for (int cc = 0; cc < 8; ++cc)
; #pragma unroll
;             for (int tt = 0; tt < 2; ++tt) { const int kb = 32 * cc + 16 * tt; f32x4 a = (f32x4){0.f, 0.f, 0.f, 0.f};
; #pragma unroll
;                 for (int dc = 0; dc < 4; ++dc) { const bf16x8 kf = *(const LAS bf16x8*)(Kl + (kb + q16) * MEM_KS + 32 * dc + 8 * kq);
;                     a = __builtin_amdgcn_mfma_f32_16x16x32_bf16(kf, qf[dc], a, 0, 0, 0); }
; #pragma unroll
;                 for (int e = 0; e < 4; ++e) mx = fmaxf(mx, a[e]);
;                 S[cc][tt] = a; }
;         mx = fmaxf(mx, __shfl_xor(mx, 16)); mx = fmaxf(mx, __shfl_xor(mx, 32));
	v_mfma_f32_16x16x32_bf16 v[28:31], v[222:225], v[4:7], v[32:35]
	s_nop 2
	s_nop 0
	ds_read_b128 v[126:129], v91 offset:21952
	s_waitcnt lgkmcnt(15)
	v_mfma_f32_16x16x32_bf16 v[32:35], v[226:229], v[4:7], v[36:39]
	s_nop 2
	s_nop 0
	ds_read_b128 v[130:133], v91 offset:26304
	s_waitcnt lgkmcnt(15)
	v_mfma_f32_16x16x32_bf16 v[134:137], v[230:233], v[4:7], v[40:43]
	s_nop 0
	ds_read_b128 v[138:141], v91 offset:30656
	s_waitcnt lgkmcnt(15)
	v_mfma_f32_16x16x32_bf16 v[142:145], v[234:237], v[4:7], v[44:47]
	s_nop 0
	ds_read_b128 v[146:149], v91 offset:35008
	s_waitcnt lgkmcnt(15)
	v_mfma_f32_16x16x32_bf16 v[150:153], v[242:245], v[4:7], v[48:51]
	s_nop 0
	ds_read_b128 v[154:157], v91 offset:39360
	s_waitcnt lgkmcnt(15)
	v_mfma_f32_16x16x32_bf16 v[158:161], v[246:249], v[4:7], v[52:55]
	s_nop 0
	ds_read_b128 v[162:165], v91 offset:43712
	s_waitcnt lgkmcnt(12)
	v_mfma_f32_16x16x32_bf16 v[166:169], v[186:189], v[4:7], v[56:59]
	s_nop 0
	ds_read_b128 v[170:173], v91 offset:48064
	s_waitcnt lgkmcnt(12)
	v_mfma_f32_16x16x32_bf16 v[174:177], v[190:193], v[4:7], v[60:63]
	s_nop 0
	ds_read_b128 v[178:181], v91 offset:52416
	s_waitcnt lgkmcnt(12)
	v_mfma_f32_16x16x32_bf16 v[182:185], v[194:197], v[4:7], v[64:67]
	s_nop 0
	ds_read_b128 v[72:75], v91 offset:56768
	s_waitcnt lgkmcnt(12)
	v_mfma_f32_16x16x32_bf16 v[76:79], v[198:201], v[4:7], v[68:71]
	s_nop 0
	ds_read_b128 v[64:67], v91 offset:61120
	s_waitcnt lgkmcnt(12)
	v_mfma_f32_16x16x32_bf16 v[68:71], v[202:205], v[4:7], v[102:105]
	s_nop 0
	ds_read_b128 v[56:59], v91 offset:65472
	v_lshrrev_b32_e32 v91, 2, v90
	s_waitcnt lgkmcnt(12)
	v_mfma_f32_16x16x32_bf16 v[60:63], v[206:209], v[4:7], v[8:11]
	v_mfma_f32_16x16x32_bf16 v[52:55], v[106:109], v[0:3], v[12:15]
	v_mfma_f32_16x16x32_bf16 v[48:51], v[110:113], v[0:3], v[16:19]
	v_mfma_f32_16x16x32_bf16 v[44:47], v[114:117], v[0:3], v[20:23]
	v_mfma_f32_16x16x32_bf16 v[40:43], v[118:121], v[0:3], v[24:27]
	v_mfma_f32_16x16x32_bf16 v[36:39], v[122:125], v[0:3], v[28:31]
	v_mfma_f32_16x16x32_bf16 v[32:35], v[126:129], v[0:3], v[32:35]
	v_mfma_f32_16x16x32_bf16 v[28:31], v[130:133], v[0:3], v[134:137]
	v_mfma_f32_16x16x32_bf16 v[24:27], v[138:141], v[0:3], v[142:145]
	v_mfma_f32_16x16x32_bf16 v[20:23], v[146:149], v[0:3], v[150:153]
	v_mfma_f32_16x16x32_bf16 v[16:19], v[154:157], v[0:3], v[158:161]
	v_mfma_f32_16x16x32_bf16 v[12:15], v[162:165], v[0:3], v[166:169]
	v_mfma_f32_16x16x32_bf16 v[8:11], v[170:173], v[0:3], v[174:177]
	v_mfma_f32_16x16x32_bf16 v[4:7], v[178:181], v[0:3], v[182:185]
	v_mfma_f32_16x16x32_bf16 v[72:75], v[72:75], v[0:3], v[76:79]
	v_mfma_f32_16x16x32_bf16 v[66:69], v[64:67], v[0:3], v[68:71]
	s_nop 1
	v_lshlrev_b32_e32 v76, 3, v90
	v_add_u32_e32 v77, v91, v92
	v_and_b32_e32 v76, 24, v76
	s_waitcnt lgkmcnt(0)
	v_mfma_f32_16x16x32_bf16 v[0:3], v[56:59], v[0:3], v[60:63]
	v_max3_f32 v56, v52, s24, v53
	v_max3_f32 v56, v56, v54, v55
	v_max3_f32 v56, v56, v48, v49
	v_max3_f32 v56, v56, v50, v51
	v_max3_f32 v56, v56, v44, v45
	v_max3_f32 v56, v56, v46, v47
	v_max3_f32 v56, v56, v40, v41
	v_max3_f32 v56, v56, v42, v43
	v_max3_f32 v56, v56, v36, v37
	v_max3_f32 v56, v56, v38, v39
	v_max3_f32 v56, v56, v32, v33
	v_max3_f32 v56, v56, v34, v35
	v_max3_f32 v56, v56, v28, v29
	v_max3_f32 v56, v56, v30, v31
	v_max3_f32 v56, v56, v24, v25
	v_max3_f32 v56, v56, v26, v27
	v_max3_f32 v56, v56, v20, v21
	v_max3_f32 v56, v56, v22, v23
	v_max3_f32 v56, v56, v16, v17
	v_max3_f32 v56, v56, v18, v19
	v_max3_f32 v56, v56, v12, v13
	v_max3_f32 v56, v56, v14, v15
	v_max3_f32 v56, v56, v8, v9
	v_max3_f32 v56, v56, v10, v11
	v_max3_f32 v56, v56, v4, v5
	v_max3_f32 v56, v56, v6, v7
	v_max3_f32 v56, v56, v72, v73
	v_max3_f32 v56, v56, v74, v75
	v_max3_f32 v56, v56, v66, v67
	v_max3_f32 v56, v56, v68, v69
	v_max3_f32 v56, v56, v0, v1
	v_max3_f32 v56, v56, v2, v3
	ds_bpermute_b32 v57, v82, v56
	v_mul_lo_u32 v64, v77, s22
	v_add3_u32 v64, s90, v76, v64
	ds_read_b64_tr_b16 v[198:199], v64
	ds_read_b64_tr_b16 v[200:201], v64 offset:4352
	ds_read_b64_tr_b16 v[202:203], v64 offset:8704
	ds_read_b64_tr_b16 v[204:205], v64 offset:13056
	ds_read_b64_tr_b16 v[206:207], v64 offset:17408
	ds_read_b64_tr_b16 v[208:209], v64 offset:21760
	ds_read_b64_tr_b16 v[210:211], v64 offset:26112
	ds_read_b64_tr_b16 v[212:213], v64 offset:30464
	ds_read_b64_tr_b16 v[218:219], v64 offset:34816
	ds_read_b64_tr_b16 v[220:221], v64 offset:39168
	ds_read_b64_tr_b16 v[222:223], v64 offset:32
	ds_read_b64_tr_b16 v[224:225], v64 offset:4384
	ds_read_b64_tr_b16 v[226:227], v64 offset:8736
	ds_read_b64_tr_b16 v[228:229], v64 offset:13088
	ds_read_b64_tr_b16 v[230:231], v64 offset:17440
	ds_read_b64_tr_b16 v[232:233], v64 offset:21792
	ds_read_b64_tr_b16 v[234:235], v64 offset:26144
	ds_read_b64_tr_b16 v[236:237], v64 offset:30496
	ds_read_b64_tr_b16 v[242:243], v64 offset:34848
	ds_read_b64_tr_b16 v[244:245], v64 offset:39200
	ds_read_b64_tr_b16 v[246:247], v64 offset:43552
	ds_read_b64_tr_b16 v[248:249], v64 offset:47904
	s_waitcnt lgkmcnt(15)
	v_max_f32_e32 v57, v57, v57
	v_max_f32_e32 v56, v56, v57
	ds_bpermute_b32 v57, v100, v56
	s_waitcnt lgkmcnt(0)
; template <bool SAMPLE>
; __device__ __forceinline__ void mem_unit(const Params& p, int l, LAS unsigned char* lds, int unit, int tid, int wave, int lane) {
;     ...
;         mx = fmaxf(mx, __shfl_xor(mx, 16)); mx = fmaxf(mx, __shfl_xor(mx, 32));
;         float den = 0.f;
; #pragma unroll
;         for (int cc = 0; cc < 8; ++cc)
; #pragma unroll
;             for (int tt = 0; tt < 2; ++tt)
; #pragma unroll
;                 for (int e = 0; e < 4; ++e) { const float pe = __expf(S[cc][tt][e] - mx); S[cc][tt][e] = pe; den += pe; }
;         den += __shfl_xor(den, 16); den += __shfl_xor(den, 32);
;         const float rden = 1.f / den;
	v_max_f32_e32 v57, v57, v57
	v_max_f32_e32 v56, v56, v57
	v_sub_f32_e32 v52, v52, v56
	v_sub_f32_e32 v53, v53, v56
	v_mul_f32_e32 v52, 0x3fb8aa3b, v52
	v_sub_f32_e32 v54, v54, v56
	v_sub_f32_e32 v57, v72, v56
	v_sub_f32_e32 v58, v73, v56
	v_sub_f32_e32 v59, v74, v56
	v_sub_f32_e32 v60, v75, v56
	v_sub_f32_e32 v61, v66, v56
	v_sub_f32_e32 v62, v67, v56
	v_sub_f32_e32 v63, v68, v56
	v_sub_f32_e32 v65, v69, v56
	v_mul_f32_e32 v53, 0x3fb8aa3b, v53
	v_exp_f32_e32 v52, v52
	v_sub_f32_e32 v55, v55, v56
	v_sub_f32_e32 v48, v48, v56
	v_sub_f32_e32 v49, v49, v56
	v_sub_f32_e32 v50, v50, v56
	v_sub_f32_e32 v51, v51, v56
	v_sub_f32_e32 v44, v44, v56
	v_sub_f32_e32 v45, v45, v56
	v_sub_f32_e32 v46, v46, v56
	v_sub_f32_e32 v47, v47, v56
	v_sub_f32_e32 v40, v40, v56
	v_sub_f32_e32 v41, v41, v56
	v_sub_f32_e32 v42, v42, v56
	v_sub_f32_e32 v43, v43, v56
	v_sub_f32_e32 v36, v36, v56
	v_sub_f32_e32 v37, v37, v56
	v_sub_f32_e32 v38, v38, v56
	v_sub_f32_e32 v39, v39, v56
	v_sub_f32_e32 v32, v32, v56
	v_sub_f32_e32 v33, v33, v56
	v_sub_f32_e32 v34, v34, v56
	v_sub_f32_e32 v35, v35, v56
	v_sub_f32_e32 v28, v28, v56
	v_sub_f32_e32 v29, v29, v56
	v_sub_f32_e32 v30, v30, v56
	v_sub_f32_e32 v31, v31, v56
	v_sub_f32_e32 v24, v24, v56
	v_sub_f32_e32 v25, v25, v56
	v_sub_f32_e32 v26, v26, v56
	v_sub_f32_e32 v27, v27, v56
	v_sub_f32_e32 v20, v20, v56
	v_sub_f32_e32 v21, v21, v56
	v_sub_f32_e32 v22, v22, v56
	v_sub_f32_e32 v23, v23, v56
	v_sub_f32_e32 v16, v16, v56
	v_sub_f32_e32 v17, v17, v56
	v_sub_f32_e32 v18, v18, v56
	v_sub_f32_e32 v19, v19, v56
	v_sub_f32_e32 v12, v12, v56
	v_sub_f32_e32 v13, v13, v56
	v_sub_f32_e32 v14, v14, v56
	v_sub_f32_e32 v15, v15, v56
	v_sub_f32_e32 v8, v8, v56
	v_sub_f32_e32 v9, v9, v56
	v_sub_f32_e32 v10, v10, v56
	v_sub_f32_e32 v11, v11, v56
	v_sub_f32_e32 v4, v4, v56
	v_sub_f32_e32 v5, v5, v56
	v_sub_f32_e32 v6, v6, v56
	v_sub_f32_e32 v7, v7, v56
	v_sub_f32_e32 v0, v0, v56
	v_sub_f32_e32 v1, v1, v56
	v_sub_f32_e32 v2, v2, v56
	v_sub_f32_e32 v3, v3, v56
	v_mul_f32_e32 v54, 0x3fb8aa3b, v54
	v_mul_f32_e32 v56, 0x3fb8aa3b, v57
	v_mul_f32_e32 v57, 0x3fb8aa3b, v58
	v_mul_f32_e32 v58, 0x3fb8aa3b, v59
	v_mul_f32_e32 v59, 0x3fb8aa3b, v60
	v_mul_f32_e32 v60, 0x3fb8aa3b, v61
	v_mul_f32_e32 v61, 0x3fb8aa3b, v62
	v_mul_f32_e32 v62, 0x3fb8aa3b, v63
	v_mul_f32_e32 v63, 0x3fb8aa3b, v65
	v_exp_f32_e32 v65, v53
	v_mul_f32_e32 v55, 0x3fb8aa3b, v55
	v_exp_f32_e32 v66, v54
	v_mul_f32_e32 v48, 0x3fb8aa3b, v48
	v_exp_f32_e32 v67, v55
	v_mul_f32_e32 v49, 0x3fb8aa3b, v49
	v_mul_f32_e32 v0, 0x3fb8aa3b, v0
	v_exp_f32_e32 v68, v48
	v_add_f32_e32 v147, 0, v52
	v_mul_f32_e32 v50, 0x3fb8aa3b, v50
	v_exp_f32_e32 v69, v49
	v_exp_f32_e32 v143, v0
	v_cvt_pk_bf16_f32 v0, v52, v65
	v_add_f32_e32 v65, v65, v147
	v_mul_f32_e32 v51, 0x3fb8aa3b, v51
	v_exp_f32_e32 v70, v50
	v_add_f32_e32 v65, v66, v65
	v_mul_f32_e32 v44, 0x3fb8aa3b, v44
	v_exp_f32_e32 v71, v51
	v_add_f32_e32 v65, v67, v65
	v_mul_f32_e32 v45, 0x3fb8aa3b, v45
	v_exp_f32_e32 v72, v44
	v_add_f32_e32 v65, v68, v65
	v_mul_f32_e32 v46, 0x3fb8aa3b, v46
	v_exp_f32_e32 v73, v45
	v_add_f32_e32 v65, v69, v65
	v_mul_f32_e32 v47, 0x3fb8aa3b, v47
	v_exp_f32_e32 v74, v46
	v_add_f32_e32 v65, v70, v65
	v_mul_f32_e32 v40, 0x3fb8aa3b, v40
	v_exp_f32_e32 v75, v47
	v_add_f32_e32 v65, v71, v65
	v_mul_f32_e32 v41, 0x3fb8aa3b, v41
	v_mul_f32_e32 v42, 0x3fb8aa3b, v42
	v_mul_f32_e32 v43, 0x3fb8aa3b, v43
	v_mul_f32_e32 v36, 0x3fb8aa3b, v36
	v_mul_f32_e32 v37, 0x3fb8aa3b, v37
	v_mul_f32_e32 v38, 0x3fb8aa3b, v38
	v_mul_f32_e32 v39, 0x3fb8aa3b, v39
	v_mul_f32_e32 v32, 0x3fb8aa3b, v32
	v_mul_f32_e32 v33, 0x3fb8aa3b, v33
	v_mul_f32_e32 v34, 0x3fb8aa3b, v34
	v_mul_f32_e32 v35, 0x3fb8aa3b, v35
	v_mul_f32_e32 v28, 0x3fb8aa3b, v28
	v_mul_f32_e32 v29, 0x3fb8aa3b, v29
	v_mul_f32_e32 v30, 0x3fb8aa3b, v30
	v_mul_f32_e32 v31, 0x3fb8aa3b, v31
	v_mul_f32_e32 v24, 0x3fb8aa3b, v24
	v_mul_f32_e32 v25, 0x3fb8aa3b, v25
	v_mul_f32_e32 v26, 0x3fb8aa3b, v26
	v_mul_f32_e32 v27, 0x3fb8aa3b, v27
	v_mul_f32_e32 v20, 0x3fb8aa3b, v20
	v_mul_f32_e32 v21, 0x3fb8aa3b, v21
	v_mul_f32_e32 v22, 0x3fb8aa3b, v22
	v_mul_f32_e32 v23, 0x3fb8aa3b, v23
	v_mul_f32_e32 v16, 0x3fb8aa3b, v16
	v_mul_f32_e32 v17, 0x3fb8aa3b, v17
	v_mul_f32_e32 v18, 0x3fb8aa3b, v18
	v_mul_f32_e32 v19, 0x3fb8aa3b, v19
	v_mul_f32_e32 v12, 0x3fb8aa3b, v12
	v_mul_f32_e32 v13, 0x3fb8aa3b, v13
	v_mul_f32_e32 v14, 0x3fb8aa3b, v14
	v_mul_f32_e32 v15, 0x3fb8aa3b, v15
	v_mul_f32_e32 v8, 0x3fb8aa3b, v8
	v_mul_f32_e32 v9, 0x3fb8aa3b, v9
	v_mul_f32_e32 v10, 0x3fb8aa3b, v10
	v_mul_f32_e32 v11, 0x3fb8aa3b, v11
	v_mul_f32_e32 v4, 0x3fb8aa3b, v4
	v_mul_f32_e32 v5, 0x3fb8aa3b, v5
	v_mul_f32_e32 v6, 0x3fb8aa3b, v6
	v_mul_f32_e32 v7, 0x3fb8aa3b, v7
	v_mul_f32_e32 v1, 0x3fb8aa3b, v1
	v_mul_f32_e32 v2, 0x3fb8aa3b, v2
	v_mul_f32_e32 v3, 0x3fb8aa3b, v3
	v_exp_f32_e32 v76, v40
	v_add_f32_e32 v65, v72, v65
	v_exp_f32_e32 v77, v41
	v_exp_f32_e32 v78, v42
	v_exp_f32_e32 v79, v43
	v_exp_f32_e32 v90, v36
	v_exp_f32_e32 v91, v37
	v_exp_f32_e32 v101, v38
	v_exp_f32_e32 v102, v39
	v_exp_f32_e32 v103, v32
	v_exp_f32_e32 v104, v33
	v_exp_f32_e32 v105, v34
	v_exp_f32_e32 v106, v35
	v_exp_f32_e32 v107, v28
	v_exp_f32_e32 v108, v29
	v_exp_f32_e32 v109, v30
	v_exp_f32_e32 v110, v31
	v_exp_f32_e32 v111, v24
	v_exp_f32_e32 v112, v25
	v_exp_f32_e32 v113, v26
	v_exp_f32_e32 v114, v27
	v_exp_f32_e32 v115, v20
	v_exp_f32_e32 v116, v21
	v_exp_f32_e32 v117, v22
	v_exp_f32_e32 v118, v23
	v_exp_f32_e32 v119, v16
	v_exp_f32_e32 v120, v17
	v_exp_f32_e32 v121, v18
	v_exp_f32_e32 v122, v19
	v_exp_f32_e32 v123, v12
	v_exp_f32_e32 v124, v13
	v_exp_f32_e32 v125, v14
	v_exp_f32_e32 v126, v15
	v_exp_f32_e32 v127, v8
	v_exp_f32_e32 v128, v9
	v_exp_f32_e32 v129, v10
; #define LAS __attribute__((address_space(3)))
; __device__ __forceinline__ unsigned pk2(float lo, float hi) { return pg8::cvt_pk_bf16(lo, hi); }
; __device__ __forceinline__ bf16x8 pack8(const float (&o)[8]) { v4u w; w.x = pk2(o[0], o[1]); w.y = pk2(o[2], o[3]); w.z = pk2(o[4], o[5]); w.w = pk2(o[6], o[7]); return __builtin_bit_cast(bf16x8, w); }
; __device__ __forceinline__ v2u vtr(const LAS bf16* p) { return __builtin_bit_cast(v2u, __builtin_amdgcn_ds_read_tr16_b64_v4i16((LAS v4i16_t*)p)); }
; template <bool SAMPLE>
; __device__ __forceinline__ void mem_unit(const Params& p, int l, LAS unsigned char* lds, int unit, int tid, int wave, int lane) {
;     ...
;         den += __shfl_xor(den, 16); den += __shfl_xor(den, 32);
;         const float rden = 1.f / den;
;         bf16x8 pf[8];
; #pragma unroll
;         for (int cc = 0; cc < 8; ++cc) { float t8[8];
; #pragma unroll
;             for (int e = 0; e < 4; ++e) { t8[e] = S[cc][0][e]; t8[4 + e] = S[cc][1][e]; }
;             pf[cc] = pack8(t8); }
; #pragma unroll
;         for (int dt = 0; dt < 8; ++dt) { f32x4 o = (f32x4){0.f, 0.f, 0.f, 0.f};
; #pragma unroll
;             for (int cc = 0; cc < 8; ++cc) { const LAS bf16* vp = Vt + (32 * cc + 4 * kq + (q16 >> 2)) * MEM_VS + 16 * dt + 4 * (q16 & 3);
;                 const v2u lo = vtr(vp), hi = vtr(vp + 16 * MEM_VS);
;                 v4u av; av.x = lo.x; av.y = lo.y; av.z = hi.x; av.w = hi.y;
;                 o = __builtin_amdgcn_mfma_f32_16x16x32_bf16(__builtin_bit_cast(bf16x8, av), pf[cc], o, 0, 0, 0); }
;             if (st) { v2u w; w.x = pk2(o[0] * rden, o[1] * rden); w.y = pk2(o[2] * rden, o[3] * rden);
;                 *(v2u*)(MO + row * 512 + h * 128 + 16 * dt + 4 * kq) = w; } }
	v_exp_f32_e32 v130, v11
	v_exp_f32_e32 v131, v4
	v_exp_f32_e32 v132, v5
	v_exp_f32_e32 v133, v6
	v_exp_f32_e32 v134, v7
	v_exp_f32_e32 v135, v56
	v_exp_f32_e32 v136, v57
	v_exp_f32_e32 v137, v58
	v_exp_f32_e32 v138, v59
	v_exp_f32_e32 v139, v60
	v_exp_f32_e32 v140, v61
	v_exp_f32_e32 v141, v62
	v_exp_f32_e32 v142, v63
	v_exp_f32_e32 v144, v1
	v_exp_f32_e32 v145, v2
	v_exp_f32_e32 v146, v3
	v_cvt_pk_bf16_f32 v1, v66, v67
	v_cvt_pk_bf16_f32 v2, v68, v69
	v_cvt_pk_bf16_f32 v3, v70, v71
	v_cvt_pk_bf16_f32 v4, v72, v73
	v_cvt_pk_bf16_f32 v5, v74, v75
	v_cvt_pk_bf16_f32 v6, v76, v77
	v_cvt_pk_bf16_f32 v7, v78, v79
	v_cvt_pk_bf16_f32 v8, v90, v91
	v_cvt_pk_bf16_f32 v9, v101, v102
	v_cvt_pk_bf16_f32 v10, v103, v104
	v_cvt_pk_bf16_f32 v11, v105, v106
	v_cvt_pk_bf16_f32 v12, v107, v108
	v_cvt_pk_bf16_f32 v13, v109, v110
	v_cvt_pk_bf16_f32 v14, v111, v112
	v_cvt_pk_bf16_f32 v15, v113, v114
	v_cvt_pk_bf16_f32 v16, v115, v116
	v_cvt_pk_bf16_f32 v17, v117, v118
	v_cvt_pk_bf16_f32 v18, v119, v120
	v_cvt_pk_bf16_f32 v19, v121, v122
	v_cvt_pk_bf16_f32 v24, v123, v124
	v_cvt_pk_bf16_f32 v25, v125, v126
	v_cvt_pk_bf16_f32 v26, v127, v128
	v_cvt_pk_bf16_f32 v27, v129, v130
	v_cvt_pk_bf16_f32 v28, v131, v132
	v_cvt_pk_bf16_f32 v29, v133, v134
	v_cvt_pk_bf16_f32 v30, v135, v136
	v_cvt_pk_bf16_f32 v31, v137, v138
	v_cvt_pk_bf16_f32 v20, v139, v140
	v_cvt_pk_bf16_f32 v21, v141, v142
	v_cvt_pk_bf16_f32 v22, v143, v144
	v_cvt_pk_bf16_f32 v23, v145, v146
	s_nop 7
	s_nop 1
	ds_read_b64_tr_b16 v[52:53], v64 offset:43520
	ds_read_b64_tr_b16 v[54:55], v64 offset:47872
	ds_read_b64_tr_b16 v[56:57], v64 offset:52224
	ds_read_b64_tr_b16 v[58:59], v64 offset:56576
	ds_read_b64_tr_b16 v[60:61], v64 offset:60928
	ds_read_b64_tr_b16 v[62:63], v64 offset:65280
	v_add_f32_e32 v65, v73, v65
	s_nop 0
	v_mfma_f32_16x16x32_bf16 v[32:35], v[198:201], v[0:3], 0
	v_add_f32_e32 v65, v74, v65
	v_add_f32_e32 v65, v75, v65
	v_add_f32_e32 v65, v76, v65
	v_add_f32_e32 v65, v77, v65
	s_nop 0
	v_mfma_f32_16x16x32_bf16 v[32:35], v[202:205], v[4:7], v[32:35]
	v_add_f32_e32 v36, v78, v65
	v_add_f32_e32 v36, v79, v36
	v_add_f32_e32 v36, v90, v36
	v_add_f32_e32 v36, v91, v36
	s_nop 0
	v_mfma_f32_16x16x32_bf16 v[32:35], v[206:209], v[8:11], v[32:35]
	v_add_f32_e32 v36, v101, v36
	v_add_f32_e32 v36, v102, v36
	v_add_f32_e32 v36, v103, v36
	v_add_f32_e32 v36, v104, v36
	s_nop 0
	v_mfma_f32_16x16x32_bf16 v[32:35], v[210:213], v[12:15], v[32:35]
	v_add_f32_e32 v36, v105, v36
	v_add_f32_e32 v36, v106, v36
	v_add_f32_e32 v36, v107, v36
	v_add_f32_e32 v36, v108, v36
	s_nop 0
	ds_read_b64_tr_b16 v[186:187], v64 offset:52256
	ds_read_b64_tr_b16 v[188:189], v64 offset:56608
	ds_read_b64_tr_b16 v[190:191], v64 offset:60960
	ds_read_b64_tr_b16 v[192:193], v64 offset:65312
	ds_read_b64_tr_b16 v[194:195], v64 offset:64
	ds_read_b64_tr_b16 v[196:197], v64 offset:4416
	ds_read_b64_tr_b16 v[198:199], v64 offset:8768
	ds_read_b64_tr_b16 v[200:201], v64 offset:13120
	ds_read_b64_tr_b16 v[202:203], v64 offset:17472
	ds_read_b64_tr_b16 v[204:205], v64 offset:21824
	ds_read_b64_tr_b16 v[206:207], v64 offset:26176
	ds_read_b64_tr_b16 v[208:209], v64 offset:30528
	ds_read_b64_tr_b16 v[210:211], v64 offset:34880
	ds_read_b64_tr_b16 v[212:213], v64 offset:39232
	v_mfma_f32_16x16x32_bf16 v[32:35], v[218:221], v[16:19], v[32:35]
	v_add_f32_e32 v36, v109, v36
	v_add_f32_e32 v36, v110, v36
	v_add_f32_e32 v36, v111, v36
	v_add_f32_e32 v36, v112, v36
	s_waitcnt lgkmcnt(15)
	v_mfma_f32_16x16x32_bf16 v[32:35], v[52:55], v[24:27], v[32:35]
	v_add_f32_e32 v36, v113, v36
	v_add_f32_e32 v36, v114, v36
	v_add_f32_e32 v36, v115, v36
	v_add_f32_e32 v36, v116, v36
	s_waitcnt lgkmcnt(15)
	v_mfma_f32_16x16x32_bf16 v[32:35], v[56:59], v[28:31], v[32:35]
	v_add_f32_e32 v36, v117, v36
	v_add_f32_e32 v36, v118, v36
	v_add_f32_e32 v36, v119, v36
	v_add_f32_e32 v40, v120, v36
	s_waitcnt lgkmcnt(14)
	v_mfma_f32_16x16x32_bf16 v[36:39], v[60:63], v[20:23], v[32:35]
	s_nop 2
	v_add_f32_e32 v32, v121, v40
	v_add_f32_e32 v32, v122, v32
	v_add_f32_e32 v32, v123, v32
	v_add_f32_e32 v32, v124, v32
	v_add_f32_e32 v32, v125, v32
	v_add_f32_e32 v32, v126, v32
	v_add_f32_e32 v32, v127, v32
	v_add_f32_e32 v32, v128, v32
	v_add_f32_e32 v32, v129, v32
	v_add_f32_e32 v32, v130, v32
	v_add_f32_e32 v32, v131, v32
	v_add_f32_e32 v32, v132, v32
	v_add_f32_e32 v32, v133, v32
	v_add_f32_e32 v32, v134, v32
	v_add_f32_e32 v32, v135, v32
	v_add_f32_e32 v32, v136, v32
	v_add_f32_e32 v32, v137, v32
	v_add_f32_e32 v32, v138, v32
	v_add_f32_e32 v32, v139, v32
	v_add_f32_e32 v32, v140, v32
	v_add_f32_e32 v32, v141, v32
	v_add_f32_e32 v32, v142, v32
	v_add_f32_e32 v32, v143, v32
	v_add_f32_e32 v32, v144, v32
	v_add_f32_e32 v32, v145, v32
	v_add_f32_e32 v32, v146, v32
	ds_bpermute_b32 v33, v82, v32
	s_waitcnt lgkmcnt(0)
	v_add_f32_e32 v32, v32, v33
	ds_bpermute_b32 v33, v100, v32
	s_waitcnt lgkmcnt(0)
; #define LAS __attribute__((address_space(3)))
; __device__ __forceinline__ unsigned pk2(float lo, float hi) { return pg8::cvt_pk_bf16(lo, hi); }
; __device__ __forceinline__ bf16x8 pack8(const float (&o)[8]) { v4u w; w.x = pk2(o[0], o[1]); w.y = pk2(o[2], o[3]); w.z = pk2(o[4], o[5]); w.w = pk2(o[6], o[7]); return __builtin_bit_cast(bf16x8, w); }
; __device__ __forceinline__ v2u vtr(const LAS bf16* p) { return __builtin_bit_cast(v2u, __builtin_amdgcn_ds_read_tr16_b64_v4i16((LAS v4i16_t*)p)); }
; template <bool SAMPLE>
; __device__ __forceinline__ void mem_unit(const Params& p, int l, LAS unsigned char* lds, int unit, int tid, int wave, int lane) {
;     ...
;         den += __shfl_xor(den, 16); den += __shfl_xor(den, 32);
;         const float rden = 1.f / den;
;         bf16x8 pf[8];
; #pragma unroll
;         for (int cc = 0; cc < 8; ++cc) { float t8[8];
; #pragma unroll
;             for (int e = 0; e < 4; ++e) { t8[e] = S[cc][0][e]; t8[4 + e] = S[cc][1][e]; }
;             pf[cc] = pack8(t8); }
; #pragma unroll
;         for (int dt = 0; dt < 8; ++dt) { f32x4 o = (f32x4){0.f, 0.f, 0.f, 0.f};
; #pragma unroll
;             for (int cc = 0; cc < 8; ++cc) { const LAS bf16* vp = Vt + (32 * cc + 4 * kq + (q16 >> 2)) * MEM_VS + 16 * dt + 4 * (q16 & 3);
;                 const v2u lo = vtr(vp), hi = vtr(vp + 16 * MEM_VS);
;                 v4u av; av.x = lo.x; av.y = lo.y; av.z = hi.x; av.w = hi.y;
;                 o = __builtin_amdgcn_mfma_f32_16x16x32_bf16(__builtin_bit_cast(bf16x8, av), pf[cc], o, 0, 0, 0); }
;             if (st) { v2u w; w.x = pk2(o[0] * rden, o[1] * rden); w.y = pk2(o[2] * rden, o[3] * rden);
;                 *(v2u*)(MO + row * 512 + h * 128 + 16 * dt + 4 * kq) = w; } }
	v_add_f32_e32 v32, v32, v33
	v_div_scale_f32 v33, s[16:17], v32, v32, 1.0
	v_rcp_f32_e32 v35, v33
	v_div_scale_f32 v34, vcc, 1.0, v32, 1.0
	v_fma_f32 v40, -v33, v35, 1.0
	v_fmac_f32_e32 v35, v40, v35
	v_mul_f32_e32 v40, v34, v35
	v_fma_f32 v41, -v33, v40, v34
	v_fmac_f32_e32 v40, v41, v35
	v_fma_f32 v33, -v33, v40, v34
	v_div_fmas_f32 v33, v33, v35, v40
	v_div_fixup_f32 v34, v33, v32, 1.0
	v_mul_f32_e32 v32, v36, v34
	v_mul_f32_e32 v36, v39, v34
	v_mul_f32_e32 v33, v37, v34
	v_mul_f32_e32 v35, v38, v34
	v_cvt_pk_bf16_f32 v52, v32, v33
	v_cvt_pk_bf16_f32 v53, v35, v36
	s_nop 5
	v_mfma_f32_16x16x32_bf16 v[36:39], v[222:225], v[0:3], 0
	s_nop 1
	v_lshl_add_u64 v[32:33], s[2:3], 0, v[88:89]
	v_lshl_add_u64 v[32:33], v[92:93], 1, v[32:33]
	s_nop 0
	v_mfma_f32_16x16x32_bf16 v[36:39], v[226:229], v[4:7], v[36:39]
	s_nop 2
	v_mfma_f32_16x16x32_bf16 v[36:39], v[230:233], v[8:11], v[36:39]
	s_nop 2
	v_mfma_f32_16x16x32_bf16 v[36:39], v[234:237], v[12:15], v[36:39]
	s_nop 2
	v_mfma_f32_16x16x32_bf16 v[36:39], v[242:245], v[16:19], v[36:39]
	s_nop 2
	global_store_dwordx2 v[32:33], v[52:53], off
	s_nop 0
	v_mfma_f32_16x16x32_bf16 v[36:39], v[246:249], v[24:27], v[36:39]
	s_nop 0
	ds_read_b64_tr_b16 v[218:219], v64 offset:43584
	ds_read_b64_tr_b16 v[220:221], v64 offset:47936
	ds_read_b64_tr_b16 v[222:223], v64 offset:52288
	ds_read_b64_tr_b16 v[224:225], v64 offset:56640
	ds_read_b64_tr_b16 v[226:227], v64 offset:60992
	ds_read_b64_tr_b16 v[228:229], v64 offset:65344
	ds_read_b64_tr_b16 v[230:231], v64 offset:96
	ds_read_b64_tr_b16 v[232:233], v64 offset:4448
	ds_read_b64_tr_b16 v[234:235], v64 offset:8800
	ds_read_b64_tr_b16 v[236:237], v64 offset:13152
	ds_read_b64_tr_b16 v[242:243], v64 offset:17504
	ds_read_b64_tr_b16 v[244:245], v64 offset:21856
	ds_read_b64_tr_b16 v[246:247], v64 offset:26208
	ds_read_b64_tr_b16 v[248:249], v64 offset:30560
	v_mfma_f32_16x16x32_bf16 v[36:39], v[186:189], v[28:31], v[36:39]
	s_nop 0
	v_mfma_f32_16x16x32_bf16 v[36:39], v[190:193], v[20:23], v[36:39]
	s_nop 7
	v_mul_f32_e32 v35, v34, v36
	v_mul_f32_e32 v36, v34, v37
	v_mul_f32_e32 v37, v34, v38
	v_mul_f32_e32 v38, v34, v39
	v_cvt_pk_bf16_f32 v52, v35, v36
	v_cvt_pk_bf16_f32 v53, v37, v38
	s_nop 5
	v_mfma_f32_16x16x32_bf16 v[36:39], v[194:197], v[0:3], 0
	s_nop 2
	v_mfma_f32_16x16x32_bf16 v[36:39], v[198:201], v[4:7], v[36:39]
	s_nop 2
	v_mfma_f32_16x16x32_bf16 v[36:39], v[202:205], v[8:11], v[36:39]
	s_nop 2
	v_mfma_f32_16x16x32_bf16 v[36:39], v[206:209], v[12:15], v[36:39]
	s_nop 2
	v_mfma_f32_16x16x32_bf16 v[36:39], v[210:213], v[16:19], v[36:39]
	s_nop 2
	global_store_dwordx2 v[32:33], v[52:53], off offset:32
	s_waitcnt lgkmcnt(12)
	ds_read_b64_tr_b16 v[186:187], v64 offset:34912
	ds_read_b64_tr_b16 v[188:189], v64 offset:39264
	ds_read_b64_tr_b16 v[190:191], v64 offset:43616
	ds_read_b64_tr_b16 v[192:193], v64 offset:47968
	ds_read_b64_tr_b16 v[194:195], v64 offset:52320
	ds_read_b64_tr_b16 v[196:197], v64 offset:56672
	ds_read_b64_tr_b16 v[198:199], v64 offset:61024
	ds_read_b64_tr_b16 v[200:201], v64 offset:65376
	ds_read_b64_tr_b16 v[202:203], v64 offset:128
	ds_read_b64_tr_b16 v[204:205], v64 offset:4480
	ds_read_b64_tr_b16 v[206:207], v64 offset:8832
	ds_read_b64_tr_b16 v[208:209], v64 offset:13184
	ds_read_b64_tr_b16 v[210:211], v64 offset:17536
	ds_read_b64_tr_b16 v[212:213], v64 offset:21888
	v_mfma_f32_16x16x32_bf16 v[36:39], v[218:221], v[24:27], v[36:39]
	s_waitcnt lgkmcnt(15)
	v_mfma_f32_16x16x32_bf16 v[36:39], v[222:225], v[28:31], v[36:39]
	s_waitcnt lgkmcnt(15)
	v_mfma_f32_16x16x32_bf16 v[36:39], v[226:229], v[20:23], v[36:39]
	s_nop 7
	v_mul_f32_e32 v35, v34, v36
	v_mul_f32_e32 v36, v34, v37
	v_mul_f32_e32 v37, v34, v38
	v_mul_f32_e32 v38, v34, v39
	v_cvt_pk_bf16_f32 v52, v35, v36
	v_cvt_pk_bf16_f32 v53, v37, v38
	s_nop 4
	s_waitcnt lgkmcnt(15)
	v_mfma_f32_16x16x32_bf16 v[36:39], v[230:233], v[0:3], 0
	s_nop 1
	s_waitcnt lgkmcnt(15)
	v_mfma_f32_16x16x32_bf16 v[36:39], v[234:237], v[4:7], v[36:39]
	s_nop 1
	s_waitcnt lgkmcnt(15)
	v_mfma_f32_16x16x32_bf16 v[36:39], v[242:245], v[8:11], v[36:39]
	s_nop 1
	s_waitcnt lgkmcnt(14)
	v_mfma_f32_16x16x32_bf16 v[36:39], v[246:249], v[12:15], v[36:39]
	s_nop 1
	s_waitcnt lgkmcnt(12)
	ds_read_b64_tr_b16 v[218:219], v64 offset:26240
	ds_read_b64_tr_b16 v[220:221], v64 offset:30592
	ds_read_b64_tr_b16 v[222:223], v64 offset:34944
	ds_read_b64_tr_b16 v[224:225], v64 offset:39296
	ds_read_b64_tr_b16 v[226:227], v64 offset:43648
	ds_read_b64_tr_b16 v[228:229], v64 offset:48000
	ds_read_b64_tr_b16 v[230:231], v64 offset:52352
	ds_read_b64_tr_b16 v[232:233], v64 offset:56704
	ds_read_b64_tr_b16 v[234:235], v64 offset:61056
	ds_read_b64_tr_b16 v[236:237], v64 offset:65408
	ds_read_b64_tr_b16 v[242:243], v64 offset:160
	ds_read_b64_tr_b16 v[244:245], v64 offset:4512
	ds_read_b64_tr_b16 v[246:247], v64 offset:8864
	ds_read_b64_tr_b16 v[248:249], v64 offset:13216
	v_mfma_f32_16x16x32_bf16 v[36:39], v[186:189], v[16:19], v[36:39]
	s_nop 2
	global_store_dwordx2 v[32:33], v[52:53], off offset:64
	s_waitcnt lgkmcnt(15)
	v_mfma_f32_16x16x32_bf16 v[36:39], v[190:193], v[24:27], v[36:39]
	s_waitcnt lgkmcnt(15)
	v_mfma_f32_16x16x32_bf16 v[36:39], v[194:197], v[28:31], v[36:39]
	s_waitcnt lgkmcnt(15)
	v_mfma_f32_16x16x32_bf16 v[36:39], v[198:201], v[20:23], v[36:39]
	s_nop 7
	v_mul_f32_e32 v35, v34, v36
	v_mul_f32_e32 v36, v34, v37
	v_mul_f32_e32 v37, v34, v38
	v_mul_f32_e32 v38, v34, v39
	v_cvt_pk_bf16_f32 v52, v35, v36
	v_cvt_pk_bf16_f32 v53, v37, v38
	s_nop 4
	s_waitcnt lgkmcnt(15)
	v_mfma_f32_16x16x32_bf16 v[36:39], v[202:205], v[0:3], 0
	s_nop 1
	s_waitcnt lgkmcnt(15)
	v_mfma_f32_16x16x32_bf16 v[36:39], v[206:209], v[4:7], v[36:39]
	s_nop 1
	s_waitcnt lgkmcnt(14)
; #define LAS __attribute__((address_space(3)))
; __device__ __forceinline__ unsigned pk2(float lo, float hi) { return pg8::cvt_pk_bf16(lo, hi); }
; __device__ __forceinline__ v2u vtr(const LAS bf16* p) { return __builtin_bit_cast(v2u, __builtin_amdgcn_ds_read_tr16_b64_v4i16((LAS v4i16_t*)p)); }
; template <bool SAMPLE>
; __device__ __forceinline__ void mem_unit(const Params& p, int l, LAS unsigned char* lds, int unit, int tid, int wave, int lane) {
;     ...
; #pragma unroll
;         for (int dt = 0; dt < 8; ++dt) { f32x4 o = (f32x4){0.f, 0.f, 0.f, 0.f};
; #pragma unroll
;             for (int cc = 0; cc < 8; ++cc) { const LAS bf16* vp = Vt + (32 * cc + 4 * kq + (q16 >> 2)) * MEM_VS + 16 * dt + 4 * (q16 & 3);
;                 const v2u lo = vtr(vp), hi = vtr(vp + 16 * MEM_VS);
;                 v4u av; av.x = lo.x; av.y = lo.y; av.z = hi.x; av.w = hi.y;
;                 o = __builtin_amdgcn_mfma_f32_16x16x32_bf16(__builtin_bit_cast(bf16x8, av), pf[cc], o, 0, 0, 0); }
;             if (st) { v2u w; w.x = pk2(o[0] * rden, o[1] * rden); w.y = pk2(o[2] * rden, o[3] * rden);
;                 *(v2u*)(MO + row * 512 + h * 128 + 16 * dt + 4 * kq) = w; } }
;       }
;     }
;     __syncthreads();
	v_mfma_f32_16x16x32_bf16 v[36:39], v[210:213], v[8:11], v[36:39]
	s_nop 1
	s_waitcnt lgkmcnt(12)
	ds_read_b64_tr_b16 v[186:187], v64 offset:17568
	ds_read_b64_tr_b16 v[188:189], v64 offset:21920
	ds_read_b64_tr_b16 v[190:191], v64 offset:26272
	ds_read_b64_tr_b16 v[192:193], v64 offset:30624
	ds_read_b64_tr_b16 v[194:195], v64 offset:34976
	ds_read_b64_tr_b16 v[196:197], v64 offset:39328
	ds_read_b64_tr_b16 v[198:199], v64 offset:43680
	ds_read_b64_tr_b16 v[200:201], v64 offset:48032
	ds_read_b64_tr_b16 v[202:203], v64 offset:52384
	ds_read_b64_tr_b16 v[204:205], v64 offset:56736
	ds_read_b64_tr_b16 v[206:207], v64 offset:61088
	ds_read_b64_tr_b16 v[208:209], v64 offset:65440
	ds_read_b64_tr_b16 v[210:211], v64 offset:192
	ds_read_b64_tr_b16 v[212:213], v64 offset:4544
	v_mfma_f32_16x16x32_bf16 v[36:39], v[218:221], v[12:15], v[36:39]
	s_nop 1
	s_waitcnt lgkmcnt(15)
	v_mfma_f32_16x16x32_bf16 v[36:39], v[222:225], v[16:19], v[36:39]
	s_nop 2
	global_store_dwordx2 v[32:33], v[52:53], off offset:96
	s_waitcnt lgkmcnt(15)
	v_mfma_f32_16x16x32_bf16 v[36:39], v[226:229], v[24:27], v[36:39]
	s_waitcnt lgkmcnt(15)
	v_mfma_f32_16x16x32_bf16 v[36:39], v[230:233], v[28:31], v[36:39]
	s_waitcnt lgkmcnt(15)
	v_mfma_f32_16x16x32_bf16 v[36:39], v[234:237], v[20:23], v[36:39]
	s_nop 7
	v_mul_f32_e32 v35, v34, v36
	v_mul_f32_e32 v36, v34, v37
	v_mul_f32_e32 v37, v34, v38
	v_mul_f32_e32 v38, v34, v39
	v_cvt_pk_bf16_f32 v52, v35, v36
	v_cvt_pk_bf16_f32 v53, v37, v38
	s_nop 4
	s_waitcnt lgkmcnt(15)
	v_mfma_f32_16x16x32_bf16 v[36:39], v[242:245], v[0:3], 0
	s_nop 1
	s_waitcnt lgkmcnt(14)
	v_mfma_f32_16x16x32_bf16 v[36:39], v[246:249], v[4:7], v[36:39]
	s_nop 1
	s_waitcnt lgkmcnt(12)
	ds_read_b64_tr_b16 v[218:219], v64 offset:8896
	ds_read_b64_tr_b16 v[220:221], v64 offset:13248
	ds_read_b64_tr_b16 v[222:223], v64 offset:17600
	ds_read_b64_tr_b16 v[224:225], v64 offset:21952
	ds_read_b64_tr_b16 v[226:227], v64 offset:26304
	ds_read_b64_tr_b16 v[228:229], v64 offset:30656
	ds_read_b64_tr_b16 v[230:231], v64 offset:35008
	ds_read_b64_tr_b16 v[232:233], v64 offset:39360
	ds_read_b64_tr_b16 v[234:235], v64 offset:43712
	ds_read_b64_tr_b16 v[236:237], v64 offset:48064
	ds_read_b64_tr_b16 v[242:243], v64 offset:61120
	ds_read_b64_tr_b16 v[244:245], v64 offset:65472
	ds_read_b64_tr_b16 v[246:247], v64 offset:224
	ds_read_b64_tr_b16 v[248:249], v64 offset:4576
	v_mfma_f32_16x16x32_bf16 v[36:39], v[186:189], v[8:11], v[36:39]
	s_nop 1
	s_waitcnt lgkmcnt(15)
	v_mfma_f32_16x16x32_bf16 v[36:39], v[190:193], v[12:15], v[36:39]
	s_nop 1
	s_waitcnt lgkmcnt(15)
	v_mfma_f32_16x16x32_bf16 v[36:39], v[194:197], v[16:19], v[36:39]
	s_nop 2
	global_store_dwordx2 v[32:33], v[52:53], off offset:128
	s_waitcnt lgkmcnt(15)
	v_mfma_f32_16x16x32_bf16 v[36:39], v[198:201], v[24:27], v[36:39]
	s_waitcnt lgkmcnt(15)
	v_mfma_f32_16x16x32_bf16 v[36:39], v[202:205], v[28:31], v[36:39]
	s_waitcnt lgkmcnt(15)
	v_mfma_f32_16x16x32_bf16 v[36:39], v[206:209], v[20:23], v[36:39]
	s_nop 7
	v_mul_f32_e32 v35, v34, v36
	v_mul_f32_e32 v36, v34, v37
	v_mul_f32_e32 v37, v34, v38
	v_mul_f32_e32 v38, v34, v39
	v_cvt_pk_bf16_f32 v52, v35, v36
	v_cvt_pk_bf16_f32 v53, v37, v38
	s_nop 4
	s_waitcnt lgkmcnt(14)
	v_mfma_f32_16x16x32_bf16 v[36:39], v[210:213], v[0:3], 0
	s_nop 1
	s_waitcnt lgkmcnt(12)
	ds_read_b64_tr_b16 v[186:187], v64 offset:35040
	ds_read_b64_tr_b16 v[188:189], v64 offset:39392
	v_mfma_f32_16x16x32_bf16 v[36:39], v[218:221], v[4:7], v[36:39]
	s_nop 1
	s_waitcnt lgkmcnt(12)
	v_mfma_f32_16x16x32_bf16 v[36:39], v[222:225], v[8:11], v[36:39]
	s_nop 1
	s_waitcnt lgkmcnt(10)
	v_mfma_f32_16x16x32_bf16 v[36:39], v[226:229], v[12:15], v[36:39]
	s_nop 0
	ds_read_b64_tr_b16 v[48:49], v64 offset:52416
	s_waitcnt lgkmcnt(9)
	v_mfma_f32_16x16x32_bf16 v[36:39], v[230:233], v[16:19], v[36:39]
	ds_read_b64_tr_b16 v[50:51], v64 offset:56768
	s_nop 1
	global_store_dwordx2 v[32:33], v[52:53], off offset:160
	s_waitcnt lgkmcnt(8)
	v_mfma_f32_16x16x32_bf16 v[36:39], v[234:237], v[24:27], v[36:39]
	s_waitcnt lgkmcnt(0)
	v_mfma_f32_16x16x32_bf16 v[36:39], v[48:51], v[28:31], v[36:39]
	s_nop 0
	v_mfma_f32_16x16x32_bf16 v[36:39], v[242:245], v[20:23], v[36:39]
	s_nop 7
	v_mul_f32_e32 v35, v34, v36
	v_mul_f32_e32 v36, v34, v37
	v_mul_f32_e32 v37, v34, v38
	v_mul_f32_e32 v38, v34, v39
	v_cvt_pk_bf16_f32 v48, v35, v36
	v_cvt_pk_bf16_f32 v49, v37, v38
	s_nop 1
	ds_read_b64_tr_b16 v[40:41], v64 offset:8928
	ds_read_b64_tr_b16 v[42:43], v64 offset:13280
	ds_read_b64_tr_b16 v[44:45], v64 offset:17632
	s_nop 0
	v_mfma_f32_16x16x32_bf16 v[0:3], v[246:249], v[0:3], 0
	ds_read_b64_tr_b16 v[46:47], v64 offset:21984
	ds_read_b64_tr_b16 v[36:37], v64 offset:26336
	s_waitcnt lgkmcnt(3)
	v_mfma_f32_16x16x32_bf16 v[0:3], v[40:43], v[4:7], v[0:3]
	ds_read_b64_tr_b16 v[38:39], v64 offset:30688
	s_nop 0
	s_waitcnt lgkmcnt(2)
	v_mfma_f32_16x16x32_bf16 v[0:3], v[44:47], v[8:11], v[0:3]
	s_nop 0
	ds_read_b64_tr_b16 v[8:9], v64 offset:43744
	s_waitcnt lgkmcnt(1)
	v_mfma_f32_16x16x32_bf16 v[0:3], v[36:39], v[12:15], v[0:3]
	ds_read_b64_tr_b16 v[10:11], v64 offset:48096
	ds_read_b64_tr_b16 v[12:13], v64 offset:52448
	s_nop 0
	v_mfma_f32_16x16x32_bf16 v[0:3], v[186:189], v[16:19], v[0:3]
	ds_read_b64_tr_b16 v[14:15], v64 offset:56800
	ds_read_b64_tr_b16 v[4:5], v64 offset:61152
	ds_read_b64_tr_b16 v[6:7], v64 offset:65504
	global_store_dwordx2 v[32:33], v[48:49], off offset:192
	s_waitcnt lgkmcnt(4)
	v_mfma_f32_16x16x32_bf16 v[0:3], v[8:11], v[24:27], v[0:3]
	s_waitcnt lgkmcnt(2)
	v_mfma_f32_16x16x32_bf16 v[0:3], v[12:15], v[28:31], v[0:3]
	s_waitcnt lgkmcnt(0)
	v_mfma_f32_16x16x32_bf16 v[0:3], v[4:7], v[20:23], v[0:3]
	s_nop 7
	v_mul_f32_e32 v0, v34, v0
	v_mul_f32_e32 v1, v34, v1
	v_mul_f32_e32 v2, v34, v2
	v_mul_f32_e32 v3, v34, v3
	v_cvt_pk_bf16_f32 v0, v0, v1
	v_cvt_pk_bf16_f32 v1, v2, v3
	global_store_dwordx2 v[32:33], v[0:1], off offset:224
	s_cbranch_scc1 .LBB0_2762
	s_barrier
	s_branch .LBB0_2727
